# Hyena FFT: LDS read batches (twiddles, pair-32 operands, filter spectrum, short-conv taps) software-pipelined one batch ahead
# baseline (speedup 1.0000x reference)
; #define LAS __attribute__((address_space(3)))
; #define WG_SYNC() do { asm volatile("s_waitcnt lgkmcnt(0)" ::: "memory"); __builtin_amdgcn_s_barrier(); asm volatile("" ::: "memory"); } while (0)
; __device__ __forceinline__ void hy_stage(LAS float* plane, const bf16_t* PHY, int cg, int jc, int tid) {
;     asm volatile("" : "+v"(tid));
;     const u32x4* src = (const u32x4*)(PHY + (size_t)cg * MT * 4);
; #pragma unroll
;     for (int k = 0; k < 8; ++k) { const int i = tid + 512 * k; const u32x4 v = src[i];
;         const unsigned w0 = (jc & 2) ? v.y : v.x, w1 = (jc & 2) ? v.w : v.z;
;         f32x2 o; o.x = (jc & 1) ? bf_hi(w0) : bf_lo(w0); o.y = (jc & 1) ? bf_hi(w1) : bf_lo(w1);
;         *(LAS f32x2*)(plane + 2 * i) = o; }
; __device__ __forceinline__ void hyena_fft(LAS unsigned char* lds, int layer, int G, const int wave_s) {
;     ...
;         for (int c = c_lo; c < c_hi; ++c) { const int unit = c >> 2, jc = c & 3;
;             WG_SYNC();
;             { f32x2 x[16]; const unsigned* tf = TF + (size_t)c * SEQ; const unsigned* tb = TB + (size_t)c * SEQ;
; #pragma unroll
;               for (int r = 0; r < 8; ++r) { const unsigned w = tf[n2 + 512 * r]; x[r] = (f32x2){bf_lo(w), bf_hi(w)}; }
; #pragma unroll
;               for (int r = 8; r < 16; ++r) { const int l = FN - 512 * r - n2; const unsigned w = l < SEQ ? tb[l] : 0u; x[r] = (f32x2){bf_lo(w), bf_hi(w)}; }
;               __builtin_amdgcn_sched_barrier(0); fft_fwd1<false>(x, Fb, n2, w1p); __builtin_amdgcn_sched_barrier(0); }
;             hy_stage(pl0, PHY, 2 * (HY / 4) + unit, jc, tid); __builtin_amdgcn_sched_barrier(0); hy_stage(pl1, PHY, unit, jc, tid); __builtin_amdgcn_sched_barrier(0);
.Lhfft_loop:
	s_lshr_b32 s43, s80, 2
	s_mul_i32 s73, s43, 0x11000
	s_and_b32 s43, s80, 2
	s_lshl_b32 s43, s43, 1
	s_add_u32 s73, s73, s43
	s_and_b32 s43, s80, 1
	s_mov_b32 s15, 0x1000c0c
	s_cmp_eq_u32 s43, 0
	s_cselect_b32 s15, s15, 0x3020c0c
	s_lshl_b32 s43, s80, 14
	s_add_u32 s46, s36, s43
	s_addc_u32 s47, s37, 0
	s_add_u32 s50, s46, 0x4000000
	s_addc_u32 s51, s47, 0
	s_waitcnt lgkmcnt(0)
	s_barrier
	s_add_u32 s60, s46, 0
	s_addc_u32 s61, s47, 0
	global_load_dword v176, v212, s[60:61]
	global_load_dword v178, v212, s[60:61] offset:2048
	s_add_u32 s60, s46, 0x1000
	s_addc_u32 s61, s47, 0
	global_load_dword v180, v212, s[60:61]
	global_load_dword v182, v212, s[60:61] offset:2048
	s_add_u32 s60, s46, 0x2000
	s_addc_u32 s61, s47, 0
	global_load_dword v184, v212, s[60:61]
	global_load_dword v186, v212, s[60:61] offset:2048
	s_add_u32 s60, s46, 0x3000
	s_addc_u32 s61, s47, 0
	global_load_dword v188, v212, s[60:61]
	global_load_dword v166, v212, s[60:61] offset:2048
	s_add_u32 s62, s50, 0x3000
	s_addc_u32 s63, s51, 0
	global_load_dword v177, v214, s[62:63] offset:2048
	global_load_dword v179, v214, s[62:63]
	s_add_u32 s62, s50, 0x2000
	s_addc_u32 s63, s51, 0
	global_load_dword v181, v214, s[62:63] offset:2048
	global_load_dword v183, v214, s[62:63]
	s_add_u32 s62, s50, 0x1000
	s_addc_u32 s63, s51, 0
	global_load_dword v185, v214, s[62:63] offset:2048
	global_load_dword v187, v214, s[62:63]
	s_add_u32 s62, s50, 0
	s_addc_u32 s63, s51, 0
	global_load_dword v189, v214, s[62:63] offset:2048
	global_load_dword v167, v214, s[62:63]
	s_add_u32 s56, s38, s73
	s_addc_u32 s57, s39, 0
	s_add_u32 s56, s56, 0x2200000
	s_addc_u32 s57, s57, 0
	global_load_dwordx3 v[58:60], v216, s[56:57]
	global_load_dwordx3 v[62:64], v218, s[56:57]
	global_load_dwordx3 v[66:68], v220, s[56:57]
	global_load_dwordx3 v[70:72], v222, s[56:57]
	global_load_dwordx3 v[74:76], v240, s[56:57]
	global_load_dwordx3 v[78:80], v242, s[56:57]
	global_load_dwordx3 v[82:84], v244, s[56:57]
	global_load_dwordx3 v[86:88], v61, s[56:57]
	s_waitcnt vmcnt(23)
	v_and_b32_e32 v101, 0xffff0000, v176
	v_lshlrev_b32_e32 v100, 16, v176
	s_waitcnt vmcnt(22)
	v_and_b32_e32 v103, 0xffff0000, v178
	v_lshlrev_b32_e32 v102, 16, v178
	s_waitcnt vmcnt(21)
	v_and_b32_e32 v105, 0xffff0000, v180
	v_lshlrev_b32_e32 v104, 16, v180
	s_waitcnt vmcnt(20)
	v_and_b32_e32 v107, 0xffff0000, v182
	v_lshlrev_b32_e32 v106, 16, v182
	s_waitcnt vmcnt(19)
	v_and_b32_e32 v109, 0xffff0000, v184
	v_lshlrev_b32_e32 v108, 16, v184
	s_waitcnt vmcnt(18)
	v_and_b32_e32 v111, 0xffff0000, v186
	v_lshlrev_b32_e32 v110, 16, v186
	s_waitcnt vmcnt(17)
	v_and_b32_e32 v113, 0xffff0000, v188
	v_lshlrev_b32_e32 v112, 16, v188
	s_waitcnt vmcnt(16)
	v_and_b32_e32 v115, 0xffff0000, v166
	v_lshlrev_b32_e32 v114, 16, v166
	s_waitcnt vmcnt(15)
	v_cndmask_b32_e64 v177, v177, 0, s[10:11]
	v_and_b32_e32 v117, 0xffff0000, v177
	v_lshlrev_b32_e32 v116, 16, v177
	s_waitcnt vmcnt(14)
	v_and_b32_e32 v119, 0xffff0000, v179
	v_lshlrev_b32_e32 v118, 16, v179
	s_waitcnt vmcnt(13)
	v_and_b32_e32 v121, 0xffff0000, v181
	v_lshlrev_b32_e32 v120, 16, v181
	s_waitcnt vmcnt(12)
	v_and_b32_e32 v123, 0xffff0000, v183
	v_lshlrev_b32_e32 v122, 16, v183
	s_waitcnt vmcnt(11)
	v_and_b32_e32 v125, 0xffff0000, v185
	v_lshlrev_b32_e32 v124, 16, v185
	s_waitcnt vmcnt(10)
	v_and_b32_e32 v127, 0xffff0000, v187
	v_lshlrev_b32_e32 v126, 16, v187
	s_waitcnt vmcnt(9)
	v_and_b32_e32 v129, 0xffff0000, v189
	v_lshlrev_b32_e32 v128, 16, v189
	s_waitcnt vmcnt(8)
	v_and_b32_e32 v131, 0xffff0000, v167
	v_lshlrev_b32_e32 v130, 16, v167
	v_pk_add_f32 v[168:169], v[100:101], v[116:117]
	v_pk_add_f32 v[174:175], v[100:101], v[116:117] neg_lo:[0,1] neg_hi:[0,1]
	v_pk_add_f32 v[176:177], v[108:109], v[124:125]
	v_pk_add_f32 v[178:179], v[108:109], v[124:125] neg_lo:[0,1] neg_hi:[0,1]
	v_pk_add_f32 v[100:101], v[168:169], v[176:177]
	v_pk_add_f32 v[116:117], v[168:169], v[176:177] neg_lo:[0,1] neg_hi:[0,1]
	v_pk_add_f32 v[108:109], v[174:175], v[178:179] op_sel:[0,1] op_sel_hi:[1,0] neg_hi:[0,1]
	v_pk_add_f32 v[124:125], v[174:175], v[178:179] op_sel:[0,1] op_sel_hi:[1,0] neg_lo:[0,1]
	v_pk_add_f32 v[180:181], v[102:103], v[118:119]
	v_pk_add_f32 v[182:183], v[102:103], v[118:119] neg_lo:[0,1] neg_hi:[0,1]
	v_pk_add_f32 v[184:185], v[110:111], v[126:127]
	v_pk_add_f32 v[186:187], v[110:111], v[126:127] neg_lo:[0,1] neg_hi:[0,1]
	v_pk_add_f32 v[102:103], v[180:181], v[184:185]
	v_pk_add_f32 v[118:119], v[180:181], v[184:185] neg_lo:[0,1] neg_hi:[0,1]
	v_pk_add_f32 v[110:111], v[182:183], v[186:187] op_sel:[0,1] op_sel_hi:[1,0] neg_hi:[0,1]
	v_pk_add_f32 v[126:127], v[182:183], v[186:187] op_sel:[0,1] op_sel_hi:[1,0] neg_lo:[0,1]
	v_pk_add_f32 v[188:189], v[104:105], v[120:121]
	v_pk_add_f32 v[166:167], v[104:105], v[120:121] neg_lo:[0,1] neg_hi:[0,1]
	v_pk_add_f32 v[168:169], v[112:113], v[128:129]
	v_pk_add_f32 v[174:175], v[112:113], v[128:129] neg_lo:[0,1] neg_hi:[0,1]
	v_pk_add_f32 v[104:105], v[188:189], v[168:169]
	v_pk_add_f32 v[120:121], v[188:189], v[168:169] neg_lo:[0,1] neg_hi:[0,1]
	v_pk_add_f32 v[112:113], v[166:167], v[174:175] op_sel:[0,1] op_sel_hi:[1,0] neg_hi:[0,1]
	v_pk_add_f32 v[128:129], v[166:167], v[174:175] op_sel:[0,1] op_sel_hi:[1,0] neg_lo:[0,1]
	v_pk_add_f32 v[176:177], v[106:107], v[122:123]
	v_pk_add_f32 v[178:179], v[106:107], v[122:123] neg_lo:[0,1] neg_hi:[0,1]
	v_pk_add_f32 v[180:181], v[114:115], v[130:131]
	v_pk_add_f32 v[182:183], v[114:115], v[130:131] neg_lo:[0,1] neg_hi:[0,1]
	v_pk_add_f32 v[106:107], v[176:177], v[180:181]
	v_pk_add_f32 v[122:123], v[176:177], v[180:181] neg_lo:[0,1] neg_hi:[0,1]
	v_pk_add_f32 v[114:115], v[178:179], v[182:183] op_sel:[0,1] op_sel_hi:[1,0] neg_hi:[0,1]
; #define LAS __attribute__((address_space(3)))
; __device__ __forceinline__ f32x2 cmul(f32x2 a, f32x2 b) { return (f32x2){a.x * b.x - a.y * b.y, a.x * b.y + a.y * b.x}; }
; template <bool INV> __device__ __forceinline__ f32x2 cmul_tw(f32x2 a, f32x2 w) { return INV ? cmulc(a, w) : cmul(a, w); }
; template <bool INV> __device__ __forceinline__ void dft16(f32x2 (&x)[16]) {
;     constexpr float C1 = 0.92387953251128674f, S1 = 0.38268343236508977f, C2 = 0.70710678118654752f;
; #pragma unroll
;     for (int b = 0; b < 4; ++b) dft4<INV>(x[b], x[4 + b], x[8 + b], x[12 + b]);
;     const f32x2 w1 = {C1, -S1}, w2 = {C2, -C2}, w3 = {S1, -C1}, w4 = {0.f, -1.f}, w6 = {-C2, -C2}, w9 = {-C1, S1};
;     x[4 * 1 + 1] = cmul_tw<INV>(x[5], w1); x[4 * 1 + 2] = cmul_tw<INV>(x[6], w2); x[4 * 1 + 3] = cmul_tw<INV>(x[7], w3);
;     x[4 * 2 + 1] = cmul_tw<INV>(x[9], w2); x[4 * 2 + 2] = cmul_tw<INV>(x[10], w4); x[4 * 2 + 3] = cmul_tw<INV>(x[11], w6);
;     x[4 * 3 + 1] = cmul_tw<INV>(x[13], w3); x[4 * 3 + 2] = cmul_tw<INV>(x[14], w6); x[4 * 3 + 3] = cmul_tw<INV>(x[15], w9);
; #pragma unroll
;     for (int c = 0; c < 4; ++c) dft4<INV>(x[4 * c], x[4 * c + 1], x[4 * c + 2], x[4 * c + 3]);
;     f32x2 y[16];
; #pragma unroll
;     for (int k = 0; k < 16; ++k) y[k] = x[4 * (k & 3) + (k >> 2)];
; #pragma unroll
;     for (int k = 0; k < 16; ++k) x[k] = y[k];
; }
; template <bool LO> __device__ __forceinline__ void fft_fwd1(f32x2 (&x)[16], LAS f32x2* B, int n2, const f32x2 (&w)[16]) {
;     asm volatile("" : "+v"(n2));
;     if (LO) dft16_fwd_lo(x); else dft16<false>(x);
;     B[fpad(n2)] = x[0];
; #pragma unroll
;     for (int k = 1; k < 16; ++k) B[fpad(512 * k + n2)] = cmul(x[k], w[k]);
; }
	v_pk_add_f32 v[130:131], v[178:179], v[182:183] op_sel:[0,1] op_sel_hi:[1,0] neg_lo:[0,1]
	v_pk_mul_f32 v[184:185], v[110:111], s[68:69] op_sel:[1,1] op_sel_hi:[0,1]
	v_pk_fma_f32 v[110:111], v[110:111], s[68:69], v[184:185] op_sel_hi:[1,0,1] neg_lo:[0,0,1]
	v_pk_mul_f32 v[186:187], v[112:113], s[84:85] op_sel:[1,1] op_sel_hi:[0,1]
	v_pk_fma_f32 v[112:113], v[112:113], s[84:85], v[186:187] op_sel_hi:[1,0,1] neg_lo:[0,0,1]
	v_pk_mul_f32 v[188:189], v[114:115], s[88:89] op_sel:[1,1] op_sel_hi:[0,1]
	v_pk_fma_f32 v[114:115], v[114:115], s[88:89], v[188:189] op_sel_hi:[1,0,1] neg_lo:[0,0,1]
	v_pk_mul_f32 v[166:167], v[118:119], s[84:85] op_sel:[1,1] op_sel_hi:[0,1]
	v_pk_fma_f32 v[118:119], v[118:119], s[84:85], v[166:167] op_sel_hi:[1,0,1] neg_lo:[0,0,1]
	v_pk_mul_f32 v[168:169], v[122:123], s[90:91] op_sel:[1,1] op_sel_hi:[0,1]
	v_pk_fma_f32 v[122:123], v[122:123], s[90:91], v[168:169] op_sel_hi:[1,0,1] neg_lo:[0,0,1]
	v_pk_mul_f32 v[174:175], v[126:127], s[88:89] op_sel:[1,1] op_sel_hi:[0,1]
	v_pk_fma_f32 v[126:127], v[126:127], s[88:89], v[174:175] op_sel_hi:[1,0,1] neg_lo:[0,0,1]
	v_pk_mul_f32 v[176:177], v[128:129], s[90:91] op_sel:[1,1] op_sel_hi:[0,1]
	v_pk_fma_f32 v[128:129], v[128:129], s[90:91], v[176:177] op_sel_hi:[1,0,1] neg_lo:[0,0,1]
	v_pk_mul_f32 v[178:179], v[130:131], s[98:99] op_sel:[1,1] op_sel_hi:[0,1]
	v_pk_fma_f32 v[130:131], v[130:131], s[98:99], v[178:179] op_sel_hi:[1,0,1] neg_lo:[0,0,1]
	v_pk_add_f32 v[180:181], v[100:101], v[104:105]
	v_pk_add_f32 v[182:183], v[100:101], v[104:105] neg_lo:[0,1] neg_hi:[0,1]
	v_pk_add_f32 v[184:185], v[102:103], v[106:107]
	v_pk_add_f32 v[186:187], v[102:103], v[106:107] neg_lo:[0,1] neg_hi:[0,1]
	v_pk_add_f32 v[100:101], v[180:181], v[184:185]
	v_pk_add_f32 v[104:105], v[180:181], v[184:185] neg_lo:[0,1] neg_hi:[0,1]
	v_pk_add_f32 v[102:103], v[182:183], v[186:187] op_sel:[0,1] op_sel_hi:[1,0] neg_hi:[0,1]
	v_pk_add_f32 v[106:107], v[182:183], v[186:187] op_sel:[0,1] op_sel_hi:[1,0] neg_lo:[0,1]
	v_pk_add_f32 v[188:189], v[108:109], v[112:113]
	v_pk_add_f32 v[166:167], v[108:109], v[112:113] neg_lo:[0,1] neg_hi:[0,1]
	v_pk_add_f32 v[168:169], v[110:111], v[114:115]
	v_pk_add_f32 v[174:175], v[110:111], v[114:115] neg_lo:[0,1] neg_hi:[0,1]
	v_pk_add_f32 v[108:109], v[188:189], v[168:169]
	v_pk_add_f32 v[112:113], v[188:189], v[168:169] neg_lo:[0,1] neg_hi:[0,1]
	v_pk_add_f32 v[110:111], v[166:167], v[174:175] op_sel:[0,1] op_sel_hi:[1,0] neg_hi:[0,1]
	v_pk_add_f32 v[114:115], v[166:167], v[174:175] op_sel:[0,1] op_sel_hi:[1,0] neg_lo:[0,1]
	v_pk_add_f32 v[176:177], v[116:117], v[120:121] op_sel:[0,1] op_sel_hi:[1,0] neg_hi:[0,1]
	v_pk_add_f32 v[178:179], v[116:117], v[120:121] op_sel:[0,1] op_sel_hi:[1,0] neg_lo:[0,1]
	v_pk_add_f32 v[180:181], v[118:119], v[122:123]
	v_pk_add_f32 v[182:183], v[118:119], v[122:123] neg_lo:[0,1] neg_hi:[0,1]
	v_pk_add_f32 v[116:117], v[176:177], v[180:181]
	v_pk_add_f32 v[120:121], v[176:177], v[180:181] neg_lo:[0,1] neg_hi:[0,1]
	v_pk_add_f32 v[118:119], v[178:179], v[182:183] op_sel:[0,1] op_sel_hi:[1,0] neg_hi:[0,1]
	v_pk_add_f32 v[122:123], v[178:179], v[182:183] op_sel:[0,1] op_sel_hi:[1,0] neg_lo:[0,1]
	v_pk_add_f32 v[184:185], v[124:125], v[128:129]
	v_pk_add_f32 v[186:187], v[124:125], v[128:129] neg_lo:[0,1] neg_hi:[0,1]
	v_pk_add_f32 v[188:189], v[126:127], v[130:131]
	v_pk_add_f32 v[166:167], v[126:127], v[130:131] neg_lo:[0,1] neg_hi:[0,1]
	v_pk_add_f32 v[124:125], v[184:185], v[188:189]
	v_pk_add_f32 v[128:129], v[184:185], v[188:189] neg_lo:[0,1] neg_hi:[0,1]
	v_pk_add_f32 v[126:127], v[186:187], v[166:167] op_sel:[0,1] op_sel_hi:[1,0] neg_hi:[0,1]
	v_pk_add_f32 v[130:131], v[186:187], v[166:167] op_sel:[0,1] op_sel_hi:[1,0] neg_lo:[0,1]
	v_add_u32_e32 v65, 0x10800, v3
	ds_write_b64 v65, v[100:101]
	v_pk_mul_f32 v[174:175], v[108:109], v[6:7] op_sel:[1,1] op_sel_hi:[0,1]
	v_pk_fma_f32 v[168:169], v[108:109], v[6:7], v[174:175] op_sel_hi:[1,0,1] neg_lo:[0,0,1]
	ds_write_b64 v65, v[168:169] offset:4224
	v_pk_mul_f32 v[178:179], v[116:117], v[8:9] op_sel:[1,1] op_sel_hi:[0,1]
	v_pk_fma_f32 v[176:177], v[116:117], v[8:9], v[178:179] op_sel_hi:[1,0,1] neg_lo:[0,0,1]
	ds_write_b64 v65, v[176:177] offset:8448
	v_pk_mul_f32 v[182:183], v[124:125], v[10:11] op_sel:[1,1] op_sel_hi:[0,1]
	v_pk_fma_f32 v[180:181], v[124:125], v[10:11], v[182:183] op_sel_hi:[1,0,1] neg_lo:[0,0,1]
	ds_write_b64 v65, v[180:181] offset:12672
	v_pk_mul_f32 v[186:187], v[102:103], v[12:13] op_sel:[1,1] op_sel_hi:[0,1]
	v_pk_fma_f32 v[184:185], v[102:103], v[12:13], v[186:187] op_sel_hi:[1,0,1] neg_lo:[0,0,1]
	ds_write_b64 v65, v[184:185] offset:16896
	v_pk_mul_f32 v[166:167], v[110:111], v[14:15] op_sel:[1,1] op_sel_hi:[0,1]
	v_pk_fma_f32 v[188:189], v[110:111], v[14:15], v[166:167] op_sel_hi:[1,0,1] neg_lo:[0,0,1]
	ds_write_b64 v65, v[188:189] offset:21120
	v_pk_mul_f32 v[168:169], v[118:119], v[16:17] op_sel:[1,1] op_sel_hi:[0,1]
	v_pk_fma_f32 v[174:175], v[118:119], v[16:17], v[168:169] op_sel_hi:[1,0,1] neg_lo:[0,0,1]
	ds_write_b64 v65, v[174:175] offset:25344
	v_pk_mul_f32 v[176:177], v[126:127], v[18:19] op_sel:[1,1] op_sel_hi:[0,1]
	v_pk_fma_f32 v[178:179], v[126:127], v[18:19], v[176:177] op_sel_hi:[1,0,1] neg_lo:[0,0,1]
	ds_write_b64 v65, v[178:179] offset:29568
	v_pk_mul_f32 v[180:181], v[104:105], v[20:21] op_sel:[1,1] op_sel_hi:[0,1]
	v_pk_fma_f32 v[182:183], v[104:105], v[20:21], v[180:181] op_sel_hi:[1,0,1] neg_lo:[0,0,1]
	ds_write_b64 v65, v[182:183] offset:33792
	v_pk_mul_f32 v[184:185], v[112:113], v[22:23] op_sel:[1,1] op_sel_hi:[0,1]
	v_pk_fma_f32 v[186:187], v[112:113], v[22:23], v[184:185] op_sel_hi:[1,0,1] neg_lo:[0,0,1]
	ds_write_b64 v65, v[186:187] offset:38016
	v_pk_mul_f32 v[188:189], v[120:121], v[24:25] op_sel:[1,1] op_sel_hi:[0,1]
	v_pk_fma_f32 v[166:167], v[120:121], v[24:25], v[188:189] op_sel_hi:[1,0,1] neg_lo:[0,0,1]
	ds_write_b64 v65, v[166:167] offset:42240
	v_pk_mul_f32 v[174:175], v[128:129], v[26:27] op_sel:[1,1] op_sel_hi:[0,1]
	v_pk_fma_f32 v[168:169], v[128:129], v[26:27], v[174:175] op_sel_hi:[1,0,1] neg_lo:[0,0,1]
	ds_write_b64 v65, v[168:169] offset:46464
	v_pk_mul_f32 v[178:179], v[106:107], v[28:29] op_sel:[1,1] op_sel_hi:[0,1]
	v_pk_fma_f32 v[176:177], v[106:107], v[28:29], v[178:179] op_sel_hi:[1,0,1] neg_lo:[0,0,1]
	ds_write_b64 v65, v[176:177] offset:50688
	v_pk_mul_f32 v[182:183], v[114:115], v[30:31] op_sel:[1,1] op_sel_hi:[0,1]
	v_pk_fma_f32 v[180:181], v[114:115], v[30:31], v[182:183] op_sel_hi:[1,0,1] neg_lo:[0,0,1]
	ds_write_b64 v65, v[180:181] offset:54912
	v_pk_mul_f32 v[186:187], v[122:123], v[32:33] op_sel:[1,1] op_sel_hi:[0,1]
	v_pk_fma_f32 v[184:185], v[122:123], v[32:33], v[186:187] op_sel_hi:[1,0,1] neg_lo:[0,0,1]
	ds_write_b64 v65, v[184:185] offset:59136
	v_pk_mul_f32 v[166:167], v[130:131], v[34:35] op_sel:[1,1] op_sel_hi:[0,1]
	v_pk_fma_f32 v[188:189], v[130:131], v[34:35], v[166:167] op_sel_hi:[1,0,1] neg_lo:[0,0,1]
	ds_write_b64 v65, v[188:189] offset:63360
	s_waitcnt vmcnt(7)
; #define LAS __attribute__((address_space(3)))
; #define WG_SYNC() do { asm volatile("s_waitcnt lgkmcnt(0)" ::: "memory"); __builtin_amdgcn_s_barrier(); asm volatile("" ::: "memory"); } while (0)
; __device__ __forceinline__ void hy_stage(LAS float* plane, const bf16_t* PHY, int cg, int jc, int tid) {
;     asm volatile("" : "+v"(tid));
;     const u32x4* src = (const u32x4*)(PHY + (size_t)cg * MT * 4);
; #pragma unroll
;     for (int k = 0; k < 8; ++k) { const int i = tid + 512 * k; const u32x4 v = src[i];
;         const unsigned w0 = (jc & 2) ? v.y : v.x, w1 = (jc & 2) ? v.w : v.z;
;         f32x2 o; o.x = (jc & 1) ? bf_hi(w0) : bf_lo(w0); o.y = (jc & 1) ? bf_hi(w1) : bf_lo(w1);
;         *(LAS f32x2*)(plane + 2 * i) = o; }
; }
; __device__ __forceinline__ void hy_sconv(const LAS float* plane, float w0, float w1, float w2, float cb, int n2, float (&u)[8][2]) {
;     asm volatile("" : "+v"(n2));
; #pragma unroll
;     for (int r = 0; r < 8; ++r)
; #pragma unroll
;         for (int b = 0; b < 2; ++b) { const int t = n2 + 512 * r, row = b * SEQ + t;
;             float a = cb + w1 * plane[row];
;             if (t > 0) a += w0 * plane[row - 1];
;             if (t < SEQ - 1) a += w2 * plane[row + 1];
;             u[r][b] = a; }
; }
; __device__ __forceinline__ void hyena_fft(LAS unsigned char* lds, int layer, int G, const int wave_s) {
;     ...
;             hy_stage(pl0, PHY, 2 * (HY / 4) + unit, jc, tid); __builtin_amdgcn_sched_barrier(0); hy_stage(pl1, PHY, unit, jc, tid); __builtin_amdgcn_sched_barrier(0);
;             WG_SYNC();
;             float uz[8][2], ux[8][2];
;             hy_sconv(pl0, cw[2 * HY + c], cw[3 * HY + 2 * HY + c], cw[6 * HY + 2 * HY + c], cb[2 * HY + c], n2, uz);
;             __builtin_amdgcn_sched_barrier(0); hy_sconv(pl1, cw[c], cw[3 * HY + c], cw[6 * HY + c], cb[c], n2, ux); __builtin_amdgcn_sched_barrier(0);
	v_perm_b32 v174, 0, v58, s15
	v_perm_b32 v175, 0, v60, s15
	ds_write_b64 v206, v[174:175]
	s_waitcnt vmcnt(6)
	v_perm_b32 v168, 0, v62, s15
	v_perm_b32 v169, 0, v64, s15
	ds_write_b64 v206, v[168:169] offset:4096
	s_waitcnt vmcnt(5)
	v_perm_b32 v178, 0, v66, s15
	v_perm_b32 v179, 0, v68, s15
	ds_write_b64 v206, v[178:179] offset:8192
	s_waitcnt vmcnt(4)
	v_perm_b32 v176, 0, v70, s15
	v_perm_b32 v177, 0, v72, s15
	ds_write_b64 v206, v[176:177] offset:12288
	s_waitcnt vmcnt(3)
	v_perm_b32 v182, 0, v74, s15
	v_perm_b32 v183, 0, v76, s15
	ds_write_b64 v206, v[182:183] offset:16384
	s_waitcnt vmcnt(2)
	v_perm_b32 v180, 0, v78, s15
	v_perm_b32 v181, 0, v80, s15
	ds_write_b64 v206, v[180:181] offset:20480
	s_waitcnt vmcnt(1)
	v_perm_b32 v186, 0, v82, s15
	v_perm_b32 v187, 0, v84, s15
	ds_write_b64 v206, v[186:187] offset:24576
	s_waitcnt vmcnt(0)
	v_perm_b32 v184, 0, v86, s15
	v_perm_b32 v185, 0, v88, s15
	ds_write_b64 v206, v[184:185] offset:28672
	s_add_u32 s56, s38, s73
	s_addc_u32 s57, s39, 0
	global_load_dwordx3 v[58:60], v216, s[56:57]
	global_load_dwordx3 v[62:64], v218, s[56:57]
	global_load_dwordx3 v[66:68], v220, s[56:57]
	global_load_dwordx3 v[70:72], v222, s[56:57]
	global_load_dwordx3 v[74:76], v240, s[56:57]
	global_load_dwordx3 v[78:80], v242, s[56:57]
	global_load_dwordx3 v[82:84], v244, s[56:57]
	global_load_dwordx3 v[86:88], v61, s[56:57]
	s_load_dwordx2 s[60:61], s[94:95], 0x48
	s_load_dwordx2 s[62:63], s[94:95], 0x50
	s_load_dwordx2 s[50:51], s[94:95], 0x88
	s_lshl_b32 s43, s80, 2
	s_mul_i32 s53, s76, 0x9000
	s_add_u32 s53, s53, s43
	s_mul_i32 s55, s76, 0x3000
	s_add_u32 s55, s55, s43
	s_waitcnt lgkmcnt(0)
	s_add_u32 s60, s60, s53
	s_addc_u32 s61, s61, 0
	s_add_u32 s62, s62, s55
	s_addc_u32 s63, s63, 0
	s_mul_i32 s53, s76, 0x2000
	s_add_u32 s53, s53, s43
	s_add_u32 s50, s50, s53
	s_addc_u32 s51, s51, 0
	s_load_dword s17, s[60:61], 0x2000
	s_load_dword s23, s[60:61], 0x5000
	s_load_dword s25, s[60:61], 0x8000
	s_load_dword s26, s[62:63], 0x2000
	s_waitcnt lgkmcnt(0)
	s_barrier
	v_mov_b32_e32 v166, s17
	v_mov_b32_e32 v167, s23
	v_mov_b32_e32 v188, s25
	v_mov_b32_e32 v189, s26
	ds_read_b32 v174, v208
	ds_read_b32 v168, v210
	ds_read_b32 v178, v208 offset:4
	ds_read_b32 v175, v208 offset:16384
	ds_read_b32 v169, v210 offset:16384
	ds_read_b32 v179, v208 offset:16388
	ds_read_b32 v176, v208 offset:2048
	ds_read_b32 v182, v208 offset:2044
	ds_read_b32 v180, v208 offset:2052
	ds_read_b32 v177, v208 offset:18432
	ds_read_b32 v183, v208 offset:18428
	ds_read_b32 v181, v208 offset:18436
	s_waitcnt lgkmcnt(10)
	v_cndmask_b32_e64 v168, v168, 0, s[10:11]
	s_waitcnt lgkmcnt(7)
	v_cndmask_b32_e64 v169, v169, 0, s[10:11]
	v_pk_fma_f32 v[132:133], v[166:167], v[174:175], v[188:189] op_sel:[1,0,1]
	v_pk_fma_f32 v[132:133], v[166:167], v[168:169], v[132:133] op_sel_hi:[0,1,1]
	s_waitcnt lgkmcnt(6)
	v_pk_fma_f32 v[132:133], v[188:189], v[178:179], v[132:133] op_sel_hi:[0,1,1]
	ds_read_b32 v186, v208 offset:4096
	ds_read_b32 v184, v208 offset:4092
	ds_read_b32 v174, v208 offset:4100
	ds_read_b32 v187, v208 offset:20480
	ds_read_b32 v185, v208 offset:20476
	ds_read_b32 v175, v208 offset:20484
	s_waitcnt lgkmcnt(8)
	v_pk_fma_f32 v[134:135], v[166:167], v[176:177], v[188:189] op_sel:[1,0,1]
	s_waitcnt lgkmcnt(7)
	v_pk_fma_f32 v[134:135], v[166:167], v[182:183], v[134:135] op_sel_hi:[0,1,1]
	s_waitcnt lgkmcnt(6)
	v_pk_fma_f32 v[134:135], v[188:189], v[180:181], v[134:135] op_sel_hi:[0,1,1]
	ds_read_b32 v168, v208 offset:6144
	ds_read_b32 v178, v208 offset:6140
	ds_read_b32 v176, v208 offset:6148
	ds_read_b32 v169, v208 offset:22528
	ds_read_b32 v179, v208 offset:22524
	ds_read_b32 v177, v208 offset:22532
	s_waitcnt lgkmcnt(8)
	v_pk_fma_f32 v[136:137], v[166:167], v[186:187], v[188:189] op_sel:[1,0,1]
	s_waitcnt lgkmcnt(7)
	v_pk_fma_f32 v[136:137], v[166:167], v[184:185], v[136:137] op_sel_hi:[0,1,1]
	s_waitcnt lgkmcnt(6)
	v_pk_fma_f32 v[136:137], v[188:189], v[174:175], v[136:137] op_sel_hi:[0,1,1]
	ds_read_b32 v182, v208 offset:8192
	ds_read_b32 v180, v208 offset:8188
	ds_read_b32 v186, v208 offset:8196
	ds_read_b32 v183, v208 offset:24576
	ds_read_b32 v181, v208 offset:24572
	ds_read_b32 v187, v208 offset:24580
	s_waitcnt lgkmcnt(8)
	v_pk_fma_f32 v[138:139], v[166:167], v[168:169], v[188:189] op_sel:[1,0,1]
	s_waitcnt lgkmcnt(7)
	v_pk_fma_f32 v[138:139], v[166:167], v[178:179], v[138:139] op_sel_hi:[0,1,1]
	s_waitcnt lgkmcnt(6)
	v_pk_fma_f32 v[138:139], v[188:189], v[176:177], v[138:139] op_sel_hi:[0,1,1]
	ds_read_b32 v184, v208 offset:10240
	ds_read_b32 v174, v208 offset:10236
	ds_read_b32 v168, v208 offset:10244
	ds_read_b32 v185, v208 offset:26624
	ds_read_b32 v175, v208 offset:26620
	ds_read_b32 v169, v208 offset:26628
	s_waitcnt lgkmcnt(8)
	v_pk_fma_f32 v[140:141], v[166:167], v[182:183], v[188:189] op_sel:[1,0,1]
	s_waitcnt lgkmcnt(7)
	v_pk_fma_f32 v[140:141], v[166:167], v[180:181], v[140:141] op_sel_hi:[0,1,1]
	s_waitcnt lgkmcnt(6)
	v_pk_fma_f32 v[140:141], v[188:189], v[186:187], v[140:141] op_sel_hi:[0,1,1]
	ds_read_b32 v178, v208 offset:12288
	ds_read_b32 v176, v208 offset:12284
	ds_read_b32 v182, v208 offset:12292
	ds_read_b32 v179, v208 offset:28672
	ds_read_b32 v177, v208 offset:28668
	ds_read_b32 v183, v208 offset:28676
	s_waitcnt lgkmcnt(8)
	v_pk_fma_f32 v[142:143], v[166:167], v[184:185], v[188:189] op_sel:[1,0,1]
	s_waitcnt lgkmcnt(7)
	v_pk_fma_f32 v[142:143], v[166:167], v[174:175], v[142:143] op_sel_hi:[0,1,1]
	s_waitcnt lgkmcnt(6)
	v_pk_fma_f32 v[142:143], v[188:189], v[168:169], v[142:143] op_sel_hi:[0,1,1]
	ds_read_b32 v180, v208 offset:14336
	ds_read_b32 v186, v208 offset:14332
	ds_read_b32 v184, v208 offset:14340
	ds_read_b32 v181, v208 offset:30720
	ds_read_b32 v187, v208 offset:30716
	ds_read_b32 v185, v208 offset:30724
	s_waitcnt lgkmcnt(8)
; #define LAS __attribute__((address_space(3)))
; __device__ __forceinline__ void fft_fwd2(LAS f32x2* B, const LAS f32x2* TW2, int tid) {
;     asm volatile("" : "+v"(tid));
;     const int b = tid >> 5, n2 = tid & 31, base = 512 * b + n2; f32x2 x[16];
; #pragma unroll
;     for (int r = 0; r < 16; ++r) x[r] = B[fpad(base + 32 * r)];
;     dft16<false>(x);
; __device__ __forceinline__ void hy_sconv(const LAS float* plane, float w0, float w1, float w2, float cb, int n2, float (&u)[8][2]) {
;     asm volatile("" : "+v"(n2));
; #pragma unroll
;     for (int r = 0; r < 8; ++r)
; #pragma unroll
;         for (int b = 0; b < 2; ++b) { const int t = n2 + 512 * r, row = b * SEQ + t;
;             float a = cb + w1 * plane[row];
;             if (t > 0) a += w0 * plane[row - 1];
;             if (t < SEQ - 1) a += w2 * plane[row + 1];
;             u[r][b] = a; }
; }
	v_pk_fma_f32 v[144:145], v[166:167], v[178:179], v[188:189] op_sel:[1,0,1]
	s_waitcnt lgkmcnt(7)
	v_pk_fma_f32 v[144:145], v[166:167], v[176:177], v[144:145] op_sel_hi:[0,1,1]
	s_waitcnt lgkmcnt(6)
	v_pk_fma_f32 v[144:145], v[188:189], v[182:183], v[144:145] op_sel_hi:[0,1,1]
	s_waitcnt lgkmcnt(3)
	v_cndmask_b32_e64 v184, v184, 0, s[28:29]
	s_waitcnt lgkmcnt(0)
	v_cndmask_b32_e64 v185, v185, 0, s[28:29]
	v_pk_fma_f32 v[146:147], v[166:167], v[180:181], v[188:189] op_sel:[1,0,1]
	v_pk_fma_f32 v[146:147], v[166:167], v[186:187], v[146:147] op_sel_hi:[0,1,1]
	v_pk_fma_f32 v[146:147], v[188:189], v[184:185], v[146:147] op_sel_hi:[0,1,1]
	s_load_dword s17, s[60:61], 0x0
	s_load_dword s23, s[60:61], 0x3000
	s_load_dword s25, s[60:61], 0x6000
	s_load_dword s26, s[62:63], 0x0
	s_waitcnt vmcnt(7)
	v_perm_b32 v174, 0, v58, s15
	v_perm_b32 v175, 0, v60, s15
	ds_write_b64 v206, v[174:175] offset:32768
	s_waitcnt vmcnt(6)
	v_perm_b32 v168, 0, v62, s15
	v_perm_b32 v169, 0, v64, s15
	ds_write_b64 v206, v[168:169] offset:36864
	s_waitcnt vmcnt(5)
	v_perm_b32 v178, 0, v66, s15
	v_perm_b32 v179, 0, v68, s15
	ds_write_b64 v206, v[178:179] offset:40960
	s_waitcnt vmcnt(4)
	v_perm_b32 v176, 0, v70, s15
	v_perm_b32 v177, 0, v72, s15
	ds_write_b64 v206, v[176:177] offset:45056
	s_waitcnt vmcnt(3)
	v_perm_b32 v182, 0, v74, s15
	v_perm_b32 v183, 0, v76, s15
	ds_write_b64 v206, v[182:183] offset:49152
	s_waitcnt vmcnt(2)
	v_perm_b32 v180, 0, v78, s15
	v_perm_b32 v181, 0, v80, s15
	ds_write_b64 v206, v[180:181] offset:53248
	s_waitcnt vmcnt(1)
	v_perm_b32 v186, 0, v82, s15
	v_perm_b32 v187, 0, v84, s15
	ds_write_b64 v206, v[186:187] offset:57344
	s_waitcnt vmcnt(0)
	v_perm_b32 v184, 0, v86, s15
	v_perm_b32 v185, 0, v88, s15
	ds_write_b64 v206, v[184:185] offset:61440
	s_add_u32 s56, s38, s73
	s_addc_u32 s57, s39, 0
	s_add_u32 s56, s56, 0x1100000
	s_addc_u32 s57, s57, 0
	global_load_dwordx3 v[58:60], v216, s[56:57]
	global_load_dwordx3 v[62:64], v218, s[56:57]
	global_load_dwordx3 v[66:68], v220, s[56:57]
	global_load_dwordx3 v[70:72], v222, s[56:57]
	global_load_dwordx3 v[74:76], v240, s[56:57]
	global_load_dwordx3 v[78:80], v242, s[56:57]
	global_load_dwordx3 v[82:84], v244, s[56:57]
	global_load_dwordx3 v[86:88], v61, s[56:57]
	v_add_u32_e32 v65, 0x10800, v5
	ds_read_b64 v[100:101], v65
	ds_read_b64 v[102:103], v65 offset:1056
	ds_read_b64 v[104:105], v65 offset:2112
	ds_read_b64 v[106:107], v65 offset:3168
	ds_read_b64 v[108:109], v65 offset:264
	ds_read_b64 v[110:111], v65 offset:1320
	ds_read_b64 v[112:113], v65 offset:2376
	ds_read_b64 v[114:115], v65 offset:3432
	ds_read_b64 v[116:117], v65 offset:528
	ds_read_b64 v[118:119], v65 offset:1584
	ds_read_b64 v[120:121], v65 offset:2640
	ds_read_b64 v[122:123], v65 offset:3696
	s_waitcnt lgkmcnt(8)
	ds_read_b64 v[124:125], v65 offset:792
	ds_read_b64 v[126:127], v65 offset:1848
	ds_read_b64 v[128:129], v65 offset:2904
	ds_read_b64 v[130:131], v65 offset:3960
	ds_read_b64 v[166:167], v56 offset:256
	ds_read_b64 v[188:189], v56 offset:512
	ds_read_b64 v[174:175], v56 offset:768
	ds_read_b64 v[168:169], v56 offset:1024
	v_pk_add_f32 v[178:179], v[100:101], v[104:105]
	v_pk_add_f32 v[176:177], v[100:101], v[104:105] neg_lo:[0,1] neg_hi:[0,1]
	v_pk_add_f32 v[182:183], v[102:103], v[106:107]
	v_pk_add_f32 v[180:181], v[102:103], v[106:107] neg_lo:[0,1] neg_hi:[0,1]
	v_pk_add_f32 v[100:101], v[178:179], v[182:183]
	v_pk_add_f32 v[104:105], v[178:179], v[182:183] neg_lo:[0,1] neg_hi:[0,1]
	v_pk_add_f32 v[102:103], v[176:177], v[180:181] op_sel:[0,1] op_sel_hi:[1,0] neg_hi:[0,1]
	v_pk_add_f32 v[106:107], v[176:177], v[180:181] op_sel:[0,1] op_sel_hi:[1,0] neg_lo:[0,1]
	s_waitcnt lgkmcnt(13)
	v_pk_add_f32 v[186:187], v[108:109], v[112:113]
	v_pk_add_f32 v[184:185], v[108:109], v[112:113] neg_lo:[0,1] neg_hi:[0,1]
	s_waitcnt lgkmcnt(12)
	v_pk_add_f32 v[178:179], v[110:111], v[114:115]
	v_pk_add_f32 v[176:177], v[110:111], v[114:115] neg_lo:[0,1] neg_hi:[0,1]
	v_pk_add_f32 v[108:109], v[186:187], v[178:179]
	v_pk_add_f32 v[112:113], v[186:187], v[178:179] neg_lo:[0,1] neg_hi:[0,1]
	v_pk_add_f32 v[110:111], v[184:185], v[176:177] op_sel:[0,1] op_sel_hi:[1,0] neg_hi:[0,1]
	v_pk_add_f32 v[114:115], v[184:185], v[176:177] op_sel:[0,1] op_sel_hi:[1,0] neg_lo:[0,1]
	s_waitcnt lgkmcnt(9)
	v_pk_add_f32 v[182:183], v[116:117], v[120:121]
	v_pk_add_f32 v[180:181], v[116:117], v[120:121] neg_lo:[0,1] neg_hi:[0,1]
	s_waitcnt lgkmcnt(8)
	v_pk_add_f32 v[186:187], v[118:119], v[122:123]
	v_pk_add_f32 v[184:185], v[118:119], v[122:123] neg_lo:[0,1] neg_hi:[0,1]
	v_pk_add_f32 v[116:117], v[182:183], v[186:187]
	v_pk_add_f32 v[120:121], v[182:183], v[186:187] neg_lo:[0,1] neg_hi:[0,1]
	v_pk_add_f32 v[118:119], v[180:181], v[184:185] op_sel:[0,1] op_sel_hi:[1,0] neg_hi:[0,1]
	v_pk_add_f32 v[122:123], v[180:181], v[184:185] op_sel:[0,1] op_sel_hi:[1,0] neg_lo:[0,1]
	s_waitcnt lgkmcnt(5)
	v_pk_add_f32 v[178:179], v[124:125], v[128:129]
	v_pk_add_f32 v[176:177], v[124:125], v[128:129] neg_lo:[0,1] neg_hi:[0,1]
	s_waitcnt lgkmcnt(4)
; #define LAS __attribute__((address_space(3)))
; __device__ __forceinline__ f32x2 cmul(f32x2 a, f32x2 b) { return (f32x2){a.x * b.x - a.y * b.y, a.x * b.y + a.y * b.x}; }
; template <bool INV> __device__ __forceinline__ f32x2 cmul_tw(f32x2 a, f32x2 w) { return INV ? cmulc(a, w) : cmul(a, w); }
; template <bool INV> __device__ __forceinline__ void dft16(f32x2 (&x)[16]) {
;     constexpr float C1 = 0.92387953251128674f, S1 = 0.38268343236508977f, C2 = 0.70710678118654752f;
; #pragma unroll
;     for (int b = 0; b < 4; ++b) dft4<INV>(x[b], x[4 + b], x[8 + b], x[12 + b]);
;     const f32x2 w1 = {C1, -S1}, w2 = {C2, -C2}, w3 = {S1, -C1}, w4 = {0.f, -1.f}, w6 = {-C2, -C2}, w9 = {-C1, S1};
;     x[4 * 1 + 1] = cmul_tw<INV>(x[5], w1); x[4 * 1 + 2] = cmul_tw<INV>(x[6], w2); x[4 * 1 + 3] = cmul_tw<INV>(x[7], w3);
;     x[4 * 2 + 1] = cmul_tw<INV>(x[9], w2); x[4 * 2 + 2] = cmul_tw<INV>(x[10], w4); x[4 * 2 + 3] = cmul_tw<INV>(x[11], w6);
;     x[4 * 3 + 1] = cmul_tw<INV>(x[13], w3); x[4 * 3 + 2] = cmul_tw<INV>(x[14], w6); x[4 * 3 + 3] = cmul_tw<INV>(x[15], w9);
; #pragma unroll
;     for (int c = 0; c < 4; ++c) dft4<INV>(x[4 * c], x[4 * c + 1], x[4 * c + 2], x[4 * c + 3]);
;     f32x2 y[16];
; #pragma unroll
;     for (int k = 0; k < 16; ++k) y[k] = x[4 * (k & 3) + (k >> 2)];
; #pragma unroll
;     for (int k = 0; k < 16; ++k) x[k] = y[k];
; }
; __device__ __forceinline__ void fft_fwd2(LAS f32x2* B, const LAS f32x2* TW2, int tid) {
;     asm volatile("" : "+v"(tid));
;     const int b = tid >> 5, n2 = tid & 31, base = 512 * b + n2; f32x2 x[16];
; #pragma unroll
;     for (int r = 0; r < 16; ++r) x[r] = B[fpad(base + 32 * r)];
;     dft16<false>(x);
;     B[fpad(base)] = x[0];
; #pragma unroll
;     for (int k = 1; k < 16; ++k) B[fpad(base + 32 * k)] = cmul(x[k], TW2[k * 32 + n2]);
; }
	v_pk_add_f32 v[182:183], v[126:127], v[130:131]
	v_pk_add_f32 v[180:181], v[126:127], v[130:131] neg_lo:[0,1] neg_hi:[0,1]
	v_pk_add_f32 v[124:125], v[178:179], v[182:183]
	v_pk_add_f32 v[128:129], v[178:179], v[182:183] neg_lo:[0,1] neg_hi:[0,1]
	v_pk_add_f32 v[126:127], v[176:177], v[180:181] op_sel:[0,1] op_sel_hi:[1,0] neg_hi:[0,1]
	v_pk_add_f32 v[130:131], v[176:177], v[180:181] op_sel:[0,1] op_sel_hi:[1,0] neg_lo:[0,1]
	v_pk_mul_f32 v[186:187], v[110:111], s[68:69] op_sel:[1,1] op_sel_hi:[0,1]
	v_pk_fma_f32 v[110:111], v[110:111], s[68:69], v[186:187] op_sel_hi:[1,0,1] neg_lo:[0,0,1]
	v_pk_mul_f32 v[184:185], v[118:119], s[84:85] op_sel:[1,1] op_sel_hi:[0,1]
	v_pk_fma_f32 v[118:119], v[118:119], s[84:85], v[184:185] op_sel_hi:[1,0,1] neg_lo:[0,0,1]
	v_pk_mul_f32 v[178:179], v[126:127], s[88:89] op_sel:[1,1] op_sel_hi:[0,1]
	v_pk_fma_f32 v[126:127], v[126:127], s[88:89], v[178:179] op_sel_hi:[1,0,1] neg_lo:[0,0,1]
	v_pk_mul_f32 v[176:177], v[112:113], s[84:85] op_sel:[1,1] op_sel_hi:[0,1]
	v_pk_fma_f32 v[112:113], v[112:113], s[84:85], v[176:177] op_sel_hi:[1,0,1] neg_lo:[0,0,1]
	v_pk_mul_f32 v[182:183], v[128:129], s[90:91] op_sel:[1,1] op_sel_hi:[0,1]
	v_pk_fma_f32 v[128:129], v[128:129], s[90:91], v[182:183] op_sel_hi:[1,0,1] neg_lo:[0,0,1]
	v_pk_mul_f32 v[180:181], v[114:115], s[88:89] op_sel:[1,1] op_sel_hi:[0,1]
	v_pk_fma_f32 v[114:115], v[114:115], s[88:89], v[180:181] op_sel_hi:[1,0,1] neg_lo:[0,0,1]
	v_pk_mul_f32 v[186:187], v[122:123], s[90:91] op_sel:[1,1] op_sel_hi:[0,1]
	v_pk_fma_f32 v[122:123], v[122:123], s[90:91], v[186:187] op_sel_hi:[1,0,1] neg_lo:[0,0,1]
	v_pk_mul_f32 v[184:185], v[130:131], s[98:99] op_sel:[1,1] op_sel_hi:[0,1]
	v_pk_fma_f32 v[130:131], v[130:131], s[98:99], v[184:185] op_sel_hi:[1,0,1] neg_lo:[0,0,1]
	v_pk_add_f32 v[178:179], v[100:101], v[116:117]
	v_pk_add_f32 v[176:177], v[100:101], v[116:117] neg_lo:[0,1] neg_hi:[0,1]
	v_pk_add_f32 v[182:183], v[108:109], v[124:125]
	v_pk_add_f32 v[180:181], v[108:109], v[124:125] neg_lo:[0,1] neg_hi:[0,1]
	v_pk_add_f32 v[100:101], v[178:179], v[182:183]
	v_pk_add_f32 v[116:117], v[178:179], v[182:183] neg_lo:[0,1] neg_hi:[0,1]
	v_pk_add_f32 v[108:109], v[176:177], v[180:181] op_sel:[0,1] op_sel_hi:[1,0] neg_hi:[0,1]
	v_pk_add_f32 v[124:125], v[176:177], v[180:181] op_sel:[0,1] op_sel_hi:[1,0] neg_lo:[0,1]
	v_pk_add_f32 v[186:187], v[102:103], v[118:119]
	v_pk_add_f32 v[184:185], v[102:103], v[118:119] neg_lo:[0,1] neg_hi:[0,1]
	v_pk_add_f32 v[178:179], v[110:111], v[126:127]
	v_pk_add_f32 v[176:177], v[110:111], v[126:127] neg_lo:[0,1] neg_hi:[0,1]
	v_pk_add_f32 v[102:103], v[186:187], v[178:179]
	v_pk_add_f32 v[118:119], v[186:187], v[178:179] neg_lo:[0,1] neg_hi:[0,1]
	v_pk_add_f32 v[110:111], v[184:185], v[176:177] op_sel:[0,1] op_sel_hi:[1,0] neg_hi:[0,1]
	v_pk_add_f32 v[126:127], v[184:185], v[176:177] op_sel:[0,1] op_sel_hi:[1,0] neg_lo:[0,1]
	v_pk_add_f32 v[182:183], v[104:105], v[120:121] op_sel:[0,1] op_sel_hi:[1,0] neg_hi:[0,1]
	v_pk_add_f32 v[180:181], v[104:105], v[120:121] op_sel:[0,1] op_sel_hi:[1,0] neg_lo:[0,1]
	v_pk_add_f32 v[186:187], v[112:113], v[128:129]
	v_pk_add_f32 v[184:185], v[112:113], v[128:129] neg_lo:[0,1] neg_hi:[0,1]
	v_pk_add_f32 v[104:105], v[182:183], v[186:187]
	v_pk_add_f32 v[120:121], v[182:183], v[186:187] neg_lo:[0,1] neg_hi:[0,1]
	v_pk_add_f32 v[112:113], v[180:181], v[184:185] op_sel:[0,1] op_sel_hi:[1,0] neg_hi:[0,1]
	v_pk_add_f32 v[128:129], v[180:181], v[184:185] op_sel:[0,1] op_sel_hi:[1,0] neg_lo:[0,1]
	v_pk_add_f32 v[178:179], v[106:107], v[122:123]
	v_pk_add_f32 v[176:177], v[106:107], v[122:123] neg_lo:[0,1] neg_hi:[0,1]
	v_pk_add_f32 v[182:183], v[114:115], v[130:131]
	v_pk_add_f32 v[180:181], v[114:115], v[130:131] neg_lo:[0,1] neg_hi:[0,1]
	v_pk_add_f32 v[106:107], v[178:179], v[182:183]
	v_pk_add_f32 v[122:123], v[178:179], v[182:183] neg_lo:[0,1] neg_hi:[0,1]
	v_pk_add_f32 v[114:115], v[176:177], v[180:181] op_sel:[0,1] op_sel_hi:[1,0] neg_hi:[0,1]
	v_pk_add_f32 v[130:131], v[176:177], v[180:181] op_sel:[0,1] op_sel_hi:[1,0] neg_lo:[0,1]
	ds_write_b64 v65, v[100:101]
	ds_read_b64 v[186:187], v56 offset:1280
	ds_read_b64 v[184:185], v56 offset:1536
	ds_read_b64 v[178:179], v56 offset:1792
	ds_read_b64 v[176:177], v56 offset:2048
	s_waitcnt lgkmcnt(8)
	v_pk_mul_f32 v[182:183], v[102:103], v[166:167] op_sel:[1,1] op_sel_hi:[0,1]
	v_pk_fma_f32 v[102:103], v[102:103], v[166:167], v[182:183] op_sel_hi:[1,0,1] neg_lo:[0,0,1]
	ds_write_b64 v65, v[102:103] offset:264
	s_waitcnt lgkmcnt(8)
	v_pk_mul_f32 v[180:181], v[104:105], v[188:189] op_sel:[1,1] op_sel_hi:[0,1]
	v_pk_fma_f32 v[104:105], v[104:105], v[188:189], v[180:181] op_sel_hi:[1,0,1] neg_lo:[0,0,1]
	ds_write_b64 v65, v[104:105] offset:528
	s_waitcnt lgkmcnt(8)
	v_pk_mul_f32 v[182:183], v[106:107], v[174:175] op_sel:[1,1] op_sel_hi:[0,1]
	v_pk_fma_f32 v[106:107], v[106:107], v[174:175], v[182:183] op_sel_hi:[1,0,1] neg_lo:[0,0,1]
	ds_write_b64 v65, v[106:107] offset:792
	s_waitcnt lgkmcnt(8)
	v_pk_mul_f32 v[180:181], v[108:109], v[168:169] op_sel:[1,1] op_sel_hi:[0,1]
	v_pk_fma_f32 v[108:109], v[108:109], v[168:169], v[180:181] op_sel_hi:[1,0,1] neg_lo:[0,0,1]
	ds_write_b64 v65, v[108:109] offset:1056
	ds_read_b64 v[182:183], v56 offset:2304
	ds_read_b64 v[180:181], v56 offset:2560
	ds_read_b64 v[166:167], v56 offset:2816
	ds_read_b64 v[188:189], v56 offset:3072
	s_waitcnt lgkmcnt(11)
	v_pk_mul_f32 v[174:175], v[110:111], v[186:187] op_sel:[1,1] op_sel_hi:[0,1]
	v_pk_fma_f32 v[110:111], v[110:111], v[186:187], v[174:175] op_sel_hi:[1,0,1] neg_lo:[0,0,1]
	ds_write_b64 v65, v[110:111] offset:1320
	s_waitcnt lgkmcnt(11)
; #define LAS __attribute__((address_space(3)))
; __device__ __forceinline__ f32x2 cmul(f32x2 a, f32x2 b) { return (f32x2){a.x * b.x - a.y * b.y, a.x * b.y + a.y * b.x}; }
; __device__ __forceinline__ void fft_fwd2(LAS f32x2* B, const LAS f32x2* TW2, int tid) {
;     ...
;     dft16<false>(x);
;     B[fpad(base)] = x[0];
; #pragma unroll
;     for (int k = 1; k < 16; ++k) B[fpad(base + 32 * k)] = cmul(x[k], TW2[k * 32 + n2]);
; }
; __device__ __forceinline__ void hy_sconv(const LAS float* plane, float w0, float w1, float w2, float cb, int n2, float (&u)[8][2]) {
;     asm volatile("" : "+v"(n2));
; #pragma unroll
;     for (int r = 0; r < 8; ++r)
; #pragma unroll
;         for (int b = 0; b < 2; ++b) { const int t = n2 + 512 * r, row = b * SEQ + t;
;             float a = cb + w1 * plane[row];
;             if (t > 0) a += w0 * plane[row - 1];
;             if (t < SEQ - 1) a += w2 * plane[row + 1];
;             u[r][b] = a; }
; }
	v_pk_mul_f32 v[168:169], v[112:113], v[184:185] op_sel:[1,1] op_sel_hi:[0,1]
	v_pk_fma_f32 v[112:113], v[112:113], v[184:185], v[168:169] op_sel_hi:[1,0,1] neg_lo:[0,0,1]
	ds_write_b64 v65, v[112:113] offset:1584
	s_waitcnt lgkmcnt(11)
	v_pk_mul_f32 v[174:175], v[114:115], v[178:179] op_sel:[1,1] op_sel_hi:[0,1]
	v_pk_fma_f32 v[114:115], v[114:115], v[178:179], v[174:175] op_sel_hi:[1,0,1] neg_lo:[0,0,1]
	ds_write_b64 v65, v[114:115] offset:1848
	s_waitcnt lgkmcnt(11)
	v_pk_mul_f32 v[168:169], v[116:117], v[176:177] op_sel:[1,1] op_sel_hi:[0,1]
	v_pk_fma_f32 v[116:117], v[116:117], v[176:177], v[168:169] op_sel_hi:[1,0,1] neg_lo:[0,0,1]
	ds_write_b64 v65, v[116:117] offset:2112
	ds_read_b64 v[174:175], v56 offset:3328
	ds_read_b64 v[168:169], v56 offset:3584
	ds_read_b64 v[186:187], v56 offset:3840
	s_waitcnt lgkmcnt(10)
	v_pk_mul_f32 v[184:185], v[118:119], v[182:183] op_sel:[1,1] op_sel_hi:[0,1]
	v_pk_fma_f32 v[118:119], v[118:119], v[182:183], v[184:185] op_sel_hi:[1,0,1] neg_lo:[0,0,1]
	ds_write_b64 v65, v[118:119] offset:2376
	s_waitcnt lgkmcnt(10)
	v_pk_mul_f32 v[178:179], v[120:121], v[180:181] op_sel:[1,1] op_sel_hi:[0,1]
	v_pk_fma_f32 v[120:121], v[120:121], v[180:181], v[178:179] op_sel_hi:[1,0,1] neg_lo:[0,0,1]
	ds_write_b64 v65, v[120:121] offset:2640
	s_waitcnt lgkmcnt(10)
	v_pk_mul_f32 v[176:177], v[122:123], v[166:167] op_sel:[1,1] op_sel_hi:[0,1]
	v_pk_fma_f32 v[122:123], v[122:123], v[166:167], v[176:177] op_sel_hi:[1,0,1] neg_lo:[0,0,1]
	ds_write_b64 v65, v[122:123] offset:2904
	s_waitcnt lgkmcnt(10)
	v_pk_mul_f32 v[184:185], v[124:125], v[188:189] op_sel:[1,1] op_sel_hi:[0,1]
	v_pk_fma_f32 v[124:125], v[124:125], v[188:189], v[184:185] op_sel_hi:[1,0,1] neg_lo:[0,0,1]
	ds_write_b64 v65, v[124:125] offset:3168
	s_waitcnt lgkmcnt(6)
	v_pk_mul_f32 v[178:179], v[126:127], v[174:175] op_sel:[1,1] op_sel_hi:[0,1]
	v_pk_fma_f32 v[126:127], v[126:127], v[174:175], v[178:179] op_sel_hi:[1,0,1] neg_lo:[0,0,1]
	ds_write_b64 v65, v[126:127] offset:3432
	s_waitcnt lgkmcnt(6)
	v_pk_mul_f32 v[176:177], v[128:129], v[168:169] op_sel:[1,1] op_sel_hi:[0,1]
	v_pk_fma_f32 v[128:129], v[128:129], v[168:169], v[176:177] op_sel_hi:[1,0,1] neg_lo:[0,0,1]
	ds_write_b64 v65, v[128:129] offset:3696
	s_waitcnt lgkmcnt(6)
	v_pk_mul_f32 v[184:185], v[130:131], v[186:187] op_sel:[1,1] op_sel_hi:[0,1]
	v_pk_fma_f32 v[130:131], v[130:131], v[186:187], v[184:185] op_sel_hi:[1,0,1] neg_lo:[0,0,1]
	ds_write_b64 v65, v[130:131] offset:3960
	s_waitcnt lgkmcnt(0)
	s_barrier
	v_mov_b32_e32 v182, s17
	v_mov_b32_e32 v183, s23
	v_mov_b32_e32 v180, s25
	v_mov_b32_e32 v181, s26
	ds_read_b32 v166, v208 offset:32768
	ds_read_b32 v188, v210 offset:32768
	ds_read_b32 v178, v208 offset:32772
	ds_read_b32 v167, v208 offset:49152
	ds_read_b32 v189, v210 offset:49152
	ds_read_b32 v179, v208 offset:49156
	ds_read_b32 v176, v208 offset:34816
	ds_read_b32 v184, v208 offset:34812
	ds_read_b32 v174, v208 offset:34820
	ds_read_b32 v177, v208 offset:51200
	ds_read_b32 v185, v208 offset:51196
	ds_read_b32 v175, v208 offset:51204
	s_waitcnt lgkmcnt(10)
	v_cndmask_b32_e64 v188, v188, 0, s[10:11]
	s_waitcnt lgkmcnt(7)
	v_cndmask_b32_e64 v189, v189, 0, s[10:11]
	v_pk_fma_f32 v[148:149], v[182:183], v[166:167], v[180:181] op_sel:[1,0,1]
	v_pk_fma_f32 v[148:149], v[182:183], v[188:189], v[148:149] op_sel_hi:[0,1,1]
	s_waitcnt lgkmcnt(6)
	v_pk_fma_f32 v[148:149], v[180:181], v[178:179], v[148:149] op_sel_hi:[0,1,1]
	ds_read_b32 v168, v208 offset:36864
	ds_read_b32 v186, v208 offset:36860
	ds_read_b32 v166, v208 offset:36868
	ds_read_b32 v169, v208 offset:53248
	ds_read_b32 v187, v208 offset:53244
	ds_read_b32 v167, v208 offset:53252
	s_waitcnt lgkmcnt(8)
	v_pk_fma_f32 v[150:151], v[182:183], v[176:177], v[180:181] op_sel:[1,0,1]
	s_waitcnt lgkmcnt(7)
	v_pk_fma_f32 v[150:151], v[182:183], v[184:185], v[150:151] op_sel_hi:[0,1,1]
	s_waitcnt lgkmcnt(6)
	v_pk_fma_f32 v[150:151], v[180:181], v[174:175], v[150:151] op_sel_hi:[0,1,1]
	ds_read_b32 v188, v208 offset:38912
	ds_read_b32 v178, v208 offset:38908
	ds_read_b32 v176, v208 offset:38916
	ds_read_b32 v189, v208 offset:55296
	ds_read_b32 v179, v208 offset:55292
	ds_read_b32 v177, v208 offset:55300
	s_waitcnt lgkmcnt(8)
	v_pk_fma_f32 v[152:153], v[182:183], v[168:169], v[180:181] op_sel:[1,0,1]
	s_waitcnt lgkmcnt(7)
	v_pk_fma_f32 v[152:153], v[182:183], v[186:187], v[152:153] op_sel_hi:[0,1,1]
	s_waitcnt lgkmcnt(6)
	v_pk_fma_f32 v[152:153], v[180:181], v[166:167], v[152:153] op_sel_hi:[0,1,1]
	ds_read_b32 v184, v208 offset:40960
	ds_read_b32 v174, v208 offset:40956
	ds_read_b32 v168, v208 offset:40964
	ds_read_b32 v185, v208 offset:57344
	ds_read_b32 v175, v208 offset:57340
	ds_read_b32 v169, v208 offset:57348
	s_waitcnt lgkmcnt(8)
	v_pk_fma_f32 v[154:155], v[182:183], v[188:189], v[180:181] op_sel:[1,0,1]
	s_waitcnt lgkmcnt(7)
	v_pk_fma_f32 v[154:155], v[182:183], v[178:179], v[154:155] op_sel_hi:[0,1,1]
	s_waitcnt lgkmcnt(6)
	v_pk_fma_f32 v[154:155], v[180:181], v[176:177], v[154:155] op_sel_hi:[0,1,1]
	ds_read_b32 v186, v208 offset:43008
	ds_read_b32 v166, v208 offset:43004
	ds_read_b32 v188, v208 offset:43012
	ds_read_b32 v187, v208 offset:59392
	ds_read_b32 v167, v208 offset:59388
	ds_read_b32 v189, v208 offset:59396
	s_waitcnt lgkmcnt(8)
	v_pk_fma_f32 v[158:159], v[182:183], v[184:185], v[180:181] op_sel:[1,0,1]
	s_waitcnt lgkmcnt(7)
	v_pk_fma_f32 v[158:159], v[182:183], v[174:175], v[158:159] op_sel_hi:[0,1,1]
	s_waitcnt lgkmcnt(6)
	v_pk_fma_f32 v[158:159], v[180:181], v[168:169], v[158:159] op_sel_hi:[0,1,1]
	ds_read_b32 v178, v208 offset:45056
	ds_read_b32 v176, v208 offset:45052
	ds_read_b32 v184, v208 offset:45060
	ds_read_b32 v179, v208 offset:61440
	ds_read_b32 v177, v208 offset:61436
	ds_read_b32 v185, v208 offset:61444
	s_waitcnt lgkmcnt(8)
; #define LAS __attribute__((address_space(3)))
; __device__ __forceinline__ f32x2 cmul(f32x2 a, f32x2 b) { return (f32x2){a.x * b.x - a.y * b.y, a.x * b.y + a.y * b.x}; }
; template <int MODE> __device__ __forceinline__ void fft_pair32(LAS f32x2* B, const LAS f32x2* F, int wave, int lane) {
;     asm volatile("" : "+v"(lane));
;     constexpr float CS[16] = {1.f, 0.98078528040323043f, 0.92387953251128674f, 0.83146961230254524f, 0.70710678118654752f, 0.55557023301960218f, 0.38268343236508977f, 0.19509032201612825f,
;                               0.f, -0.19509032201612825f, -0.38268343236508977f, -0.55557023301960218f, -0.70710678118654752f, -0.83146961230254524f, -0.92387953251128674f, -0.98078528040323043f};
;     constexpr float SN[16] = {0.f, 0.19509032201612825f, 0.38268343236508977f, 0.55557023301960218f, 0.70710678118654752f, 0.83146961230254524f, 0.92387953251128674f, 0.98078528040323043f,
;                               1.f, 0.98078528040323043f, 0.92387953251128674f, 0.83146961230254524f, 0.70710678118654752f, 0.55557023301960218f, 0.38268343236508977f, 0.19509032201612825f};
;     const int hi = lane >> 5, blk = 32 * wave + (lane & 31); const float sg = hi ? -1.f : 1.f;
;     LAS f32x2* p = B + 33 * blk; f32x2 v[16];
; #pragma unroll
;     for (int j = 0; j < 16; ++j) { const f32x2 d = p[j] + p[j + 16] * sg;
;         const f32x2 w = {hi ? CS[j] : 1.f, hi ? -SN[j] : 0.f}; v[j] = j == 0 ? d : cmul(d, w); }
;     dft16<false>(v);
; __device__ __forceinline__ void hy_sconv(const LAS float* plane, float w0, float w1, float w2, float cb, int n2, float (&u)[8][2]) {
;     asm volatile("" : "+v"(n2));
; #pragma unroll
;     for (int r = 0; r < 8; ++r)
; #pragma unroll
;         for (int b = 0; b < 2; ++b) { const int t = n2 + 512 * r, row = b * SEQ + t;
;             float a = cb + w1 * plane[row];
;             if (t > 0) a += w0 * plane[row - 1];
;             if (t < SEQ - 1) a += w2 * plane[row + 1];
;             u[r][b] = a; }
; }
	v_pk_fma_f32 v[160:161], v[182:183], v[186:187], v[180:181] op_sel:[1,0,1]
	s_waitcnt lgkmcnt(7)
	v_pk_fma_f32 v[160:161], v[182:183], v[166:167], v[160:161] op_sel_hi:[0,1,1]
	s_waitcnt lgkmcnt(6)
	v_pk_fma_f32 v[160:161], v[180:181], v[188:189], v[160:161] op_sel_hi:[0,1,1]
	ds_read_b32 v174, v208 offset:47104
	ds_read_b32 v168, v208 offset:47100
	ds_read_b32 v186, v208 offset:47108
	ds_read_b32 v175, v208 offset:63488
	ds_read_b32 v169, v208 offset:63484
	ds_read_b32 v187, v208 offset:63492
	s_waitcnt lgkmcnt(8)
	v_pk_fma_f32 v[162:163], v[182:183], v[178:179], v[180:181] op_sel:[1,0,1]
	s_waitcnt lgkmcnt(7)
	v_pk_fma_f32 v[162:163], v[182:183], v[176:177], v[162:163] op_sel_hi:[0,1,1]
	s_waitcnt lgkmcnt(6)
	v_pk_fma_f32 v[162:163], v[180:181], v[184:185], v[162:163] op_sel_hi:[0,1,1]
	s_waitcnt lgkmcnt(3)
	v_cndmask_b32_e64 v186, v186, 0, s[28:29]
	s_waitcnt lgkmcnt(0)
	v_cndmask_b32_e64 v187, v187, 0, s[28:29]
	v_pk_fma_f32 v[164:165], v[182:183], v[174:175], v[180:181] op_sel:[1,0,1]
	v_pk_fma_f32 v[164:165], v[182:183], v[168:169], v[164:165] op_sel_hi:[0,1,1]
	v_pk_fma_f32 v[164:165], v[180:181], v[186:187], v[164:165] op_sel_hi:[0,1,1]
	s_load_dword s17, s[60:61], 0x1000
	s_load_dword s23, s[60:61], 0x4000
	s_load_dword s25, s[60:61], 0x7000
	s_load_dword s26, s[62:63], 0x1000
	v_add_u32_e32 v65, 0x10800, v156
	v_add_u32_e32 v69, 0x10800, v196
	ds_read_b64 v[100:101], v65
	ds_read_b64 v[166:167], v65 offset:128
	ds_read_b64 v[102:103], v65 offset:8
	ds_read_b64 v[188:189], v65 offset:136
	ds_read_b64 v[104:105], v65 offset:16
	ds_read_b64 v[178:179], v65 offset:144
	ds_read_b64 v[106:107], v65 offset:24
	ds_read_b64 v[176:177], v65 offset:152
	ds_read_b64 v[108:109], v65 offset:32
	ds_read_b64 v[184:185], v65 offset:160
	ds_read_b64 v[110:111], v65 offset:40
	ds_read_b64 v[174:175], v65 offset:168
	ds_read_b64 v[112:113], v65 offset:48
	ds_read_b64 v[168:169], v65 offset:176
	ds_read_b64 v[114:115], v65 offset:56
	ds_read_b64 v[186:187], v65 offset:184
	s_waitcnt lgkmcnt(0)
	v_pk_fma_f32 v[100:101], v[166:167], v[190:191], v[100:101] op_sel_hi:[1,0,1]
	v_pk_fma_f32 v[102:103], v[188:189], v[190:191], v[102:103] op_sel_hi:[1,0,1]
	v_pk_mul_f32 v[182:183], v[102:103], v[36:37] op_sel:[1,1] op_sel_hi:[0,1]
	v_pk_fma_f32 v[102:103], v[102:103], v[36:37], v[182:183] op_sel_hi:[1,0,1] neg_lo:[0,0,1]
	v_pk_fma_f32 v[104:105], v[178:179], v[190:191], v[104:105] op_sel_hi:[1,0,1]
	v_pk_mul_f32 v[180:181], v[104:105], v[38:39] op_sel:[1,1] op_sel_hi:[0,1]
	v_pk_fma_f32 v[104:105], v[104:105], v[38:39], v[180:181] op_sel_hi:[1,0,1] neg_lo:[0,0,1]
	v_pk_fma_f32 v[106:107], v[176:177], v[190:191], v[106:107] op_sel_hi:[1,0,1]
	v_pk_mul_f32 v[182:183], v[106:107], v[40:41] op_sel:[1,1] op_sel_hi:[0,1]
	v_pk_fma_f32 v[106:107], v[106:107], v[40:41], v[182:183] op_sel_hi:[1,0,1] neg_lo:[0,0,1]
	ds_read_b64 v[116:117], v65 offset:64
	ds_read_b64 v[180:181], v65 offset:192
	ds_read_b64 v[118:119], v65 offset:72
	ds_read_b64 v[182:183], v65 offset:200
	ds_read_b64 v[120:121], v65 offset:80
	ds_read_b64 v[166:167], v65 offset:208
	ds_read_b64 v[122:123], v65 offset:88
	ds_read_b64 v[188:189], v65 offset:216
	v_pk_fma_f32 v[108:109], v[184:185], v[190:191], v[108:109] op_sel_hi:[1,0,1]
	v_pk_mul_f32 v[178:179], v[108:109], v[42:43] op_sel:[1,1] op_sel_hi:[0,1]
	v_pk_fma_f32 v[108:109], v[108:109], v[42:43], v[178:179] op_sel_hi:[1,0,1] neg_lo:[0,0,1]
	v_pk_fma_f32 v[110:111], v[174:175], v[190:191], v[110:111] op_sel_hi:[1,0,1]
	v_pk_mul_f32 v[176:177], v[110:111], v[44:45] op_sel:[1,1] op_sel_hi:[0,1]
	v_pk_fma_f32 v[110:111], v[110:111], v[44:45], v[176:177] op_sel_hi:[1,0,1] neg_lo:[0,0,1]
	v_pk_fma_f32 v[112:113], v[168:169], v[190:191], v[112:113] op_sel_hi:[1,0,1]
	v_pk_mul_f32 v[178:179], v[112:113], v[46:47] op_sel:[1,1] op_sel_hi:[0,1]
	v_pk_fma_f32 v[112:113], v[112:113], v[46:47], v[178:179] op_sel_hi:[1,0,1] neg_lo:[0,0,1]
	v_pk_fma_f32 v[114:115], v[186:187], v[190:191], v[114:115] op_sel_hi:[1,0,1]
	v_pk_mul_f32 v[176:177], v[114:115], v[48:49] op_sel:[1,1] op_sel_hi:[0,1]
	v_pk_fma_f32 v[114:115], v[114:115], v[48:49], v[176:177] op_sel_hi:[1,0,1] neg_lo:[0,0,1]
	ds_read_b64 v[124:125], v65 offset:96
	ds_read_b64 v[178:179], v65 offset:224
	ds_read_b64 v[126:127], v65 offset:104
	ds_read_b64 v[176:177], v65 offset:232
	ds_read_b64 v[128:129], v65 offset:112
	ds_read_b64 v[184:185], v65 offset:240
	ds_read_b64 v[130:131], v65 offset:120
	ds_read_b64 v[174:175], v65 offset:248
	s_waitcnt lgkmcnt(14)
	v_pk_fma_f32 v[116:117], v[180:181], v[190:191], v[116:117] op_sel_hi:[1,0,1]
	v_pk_mul_f32 v[168:169], v[116:117], v[50:51] op_sel:[1,1] op_sel_hi:[0,1]
	v_pk_fma_f32 v[116:117], v[116:117], v[50:51], v[168:169] op_sel_hi:[1,0,1] neg_lo:[0,0,1]
	s_waitcnt lgkmcnt(12)
	v_pk_fma_f32 v[118:119], v[182:183], v[190:191], v[118:119] op_sel_hi:[1,0,1]
	v_pk_mul_f32 v[186:187], v[118:119], v[52:53] op_sel:[1,1] op_sel_hi:[0,1]
	v_pk_fma_f32 v[118:119], v[118:119], v[52:53], v[186:187] op_sel_hi:[1,0,1] neg_lo:[0,0,1]
	s_waitcnt lgkmcnt(10)
	v_pk_fma_f32 v[120:121], v[166:167], v[190:191], v[120:121] op_sel_hi:[1,0,1]
	v_pk_mul_f32 v[168:169], v[120:121], v[54:55] op_sel:[1,1] op_sel_hi:[0,1]
	v_pk_fma_f32 v[120:121], v[120:121], v[54:55], v[168:169] op_sel_hi:[1,0,1] neg_lo:[0,0,1]
	s_waitcnt lgkmcnt(8)
	v_pk_fma_f32 v[122:123], v[188:189], v[190:191], v[122:123] op_sel_hi:[1,0,1]
	v_pk_mul_f32 v[186:187], v[122:123], v[90:91] op_sel:[1,1] op_sel_hi:[0,1]
	v_pk_fma_f32 v[122:123], v[122:123], v[90:91], v[186:187] op_sel_hi:[1,0,1] neg_lo:[0,0,1]
	s_waitcnt lgkmcnt(6)
; template <bool INV> __device__ __forceinline__ f32x2 cmul_tw(f32x2 a, f32x2 w) { return INV ? cmulc(a, w) : cmul(a, w); }
; template <bool INV> __device__ __forceinline__ void dft16(f32x2 (&x)[16]) {
;     constexpr float C1 = 0.92387953251128674f, S1 = 0.38268343236508977f, C2 = 0.70710678118654752f;
; #pragma unroll
;     for (int b = 0; b < 4; ++b) dft4<INV>(x[b], x[4 + b], x[8 + b], x[12 + b]);
;     const f32x2 w1 = {C1, -S1}, w2 = {C2, -C2}, w3 = {S1, -C1}, w4 = {0.f, -1.f}, w6 = {-C2, -C2}, w9 = {-C1, S1};
;     x[4 * 1 + 1] = cmul_tw<INV>(x[5], w1); x[4 * 1 + 2] = cmul_tw<INV>(x[6], w2); x[4 * 1 + 3] = cmul_tw<INV>(x[7], w3);
;     x[4 * 2 + 1] = cmul_tw<INV>(x[9], w2); x[4 * 2 + 2] = cmul_tw<INV>(x[10], w4); x[4 * 2 + 3] = cmul_tw<INV>(x[11], w6);
;     x[4 * 3 + 1] = cmul_tw<INV>(x[13], w3); x[4 * 3 + 2] = cmul_tw<INV>(x[14], w6); x[4 * 3 + 3] = cmul_tw<INV>(x[15], w9);
; #pragma unroll
;     for (int c = 0; c < 4; ++c) dft4<INV>(x[4 * c], x[4 * c + 1], x[4 * c + 2], x[4 * c + 3]);
;     f32x2 y[16];
; #pragma unroll
;     for (int k = 0; k < 16; ++k) y[k] = x[4 * (k & 3) + (k >> 2)];
; #pragma unroll
;     for (int k = 0; k < 16; ++k) x[k] = y[k];
; }
; template <int MODE> __device__ __forceinline__ void fft_pair32(LAS f32x2* B, const LAS f32x2* F, int wave, int lane) {
;     ...
;     if (MODE == 2) {
; #pragma unroll
;         for (int k = 0; k < 16; ++k) p[2 * k + hi] = v[k];
;         return; }
	v_pk_fma_f32 v[124:125], v[178:179], v[190:191], v[124:125] op_sel_hi:[1,0,1]
	v_pk_mul_f32 v[168:169], v[124:125], v[92:93] op_sel:[1,1] op_sel_hi:[0,1]
	v_pk_fma_f32 v[124:125], v[124:125], v[92:93], v[168:169] op_sel_hi:[1,0,1] neg_lo:[0,0,1]
	s_waitcnt lgkmcnt(4)
	v_pk_fma_f32 v[126:127], v[176:177], v[190:191], v[126:127] op_sel_hi:[1,0,1]
	v_pk_mul_f32 v[186:187], v[126:127], v[94:95] op_sel:[1,1] op_sel_hi:[0,1]
	v_pk_fma_f32 v[126:127], v[126:127], v[94:95], v[186:187] op_sel_hi:[1,0,1] neg_lo:[0,0,1]
	s_waitcnt lgkmcnt(2)
	v_pk_fma_f32 v[128:129], v[184:185], v[190:191], v[128:129] op_sel_hi:[1,0,1]
	v_pk_mul_f32 v[180:181], v[128:129], v[96:97] op_sel:[1,1] op_sel_hi:[0,1]
	v_pk_fma_f32 v[128:129], v[128:129], v[96:97], v[180:181] op_sel_hi:[1,0,1] neg_lo:[0,0,1]
	s_waitcnt lgkmcnt(0)
	v_pk_fma_f32 v[130:131], v[174:175], v[190:191], v[130:131] op_sel_hi:[1,0,1]
	v_pk_mul_f32 v[182:183], v[130:131], v[98:99] op_sel:[1,1] op_sel_hi:[0,1]
	v_pk_fma_f32 v[130:131], v[130:131], v[98:99], v[182:183] op_sel_hi:[1,0,1] neg_lo:[0,0,1]
	v_pk_add_f32 v[166:167], v[100:101], v[116:117]
	v_pk_add_f32 v[188:189], v[100:101], v[116:117] neg_lo:[0,1] neg_hi:[0,1]
	v_pk_add_f32 v[168:169], v[108:109], v[124:125]
	v_pk_add_f32 v[186:187], v[108:109], v[124:125] neg_lo:[0,1] neg_hi:[0,1]
	v_pk_add_f32 v[100:101], v[166:167], v[168:169]
	v_pk_add_f32 v[116:117], v[166:167], v[168:169] neg_lo:[0,1] neg_hi:[0,1]
	v_pk_add_f32 v[108:109], v[188:189], v[186:187] op_sel:[0,1] op_sel_hi:[1,0] neg_hi:[0,1]
	v_pk_add_f32 v[124:125], v[188:189], v[186:187] op_sel:[0,1] op_sel_hi:[1,0] neg_lo:[0,1]
	v_pk_add_f32 v[180:181], v[102:103], v[118:119]
	v_pk_add_f32 v[182:183], v[102:103], v[118:119] neg_lo:[0,1] neg_hi:[0,1]
	v_pk_add_f32 v[178:179], v[110:111], v[126:127]
	v_pk_add_f32 v[176:177], v[110:111], v[126:127] neg_lo:[0,1] neg_hi:[0,1]
	v_pk_add_f32 v[102:103], v[180:181], v[178:179]
	v_pk_add_f32 v[118:119], v[180:181], v[178:179] neg_lo:[0,1] neg_hi:[0,1]
	v_pk_add_f32 v[110:111], v[182:183], v[176:177] op_sel:[0,1] op_sel_hi:[1,0] neg_hi:[0,1]
	v_pk_add_f32 v[126:127], v[182:183], v[176:177] op_sel:[0,1] op_sel_hi:[1,0] neg_lo:[0,1]
	v_pk_add_f32 v[184:185], v[104:105], v[120:121]
	v_pk_add_f32 v[174:175], v[104:105], v[120:121] neg_lo:[0,1] neg_hi:[0,1]
	v_pk_add_f32 v[166:167], v[112:113], v[128:129]
	v_pk_add_f32 v[188:189], v[112:113], v[128:129] neg_lo:[0,1] neg_hi:[0,1]
	v_pk_add_f32 v[104:105], v[184:185], v[166:167]
	v_pk_add_f32 v[120:121], v[184:185], v[166:167] neg_lo:[0,1] neg_hi:[0,1]
	v_pk_add_f32 v[112:113], v[174:175], v[188:189] op_sel:[0,1] op_sel_hi:[1,0] neg_hi:[0,1]
	v_pk_add_f32 v[128:129], v[174:175], v[188:189] op_sel:[0,1] op_sel_hi:[1,0] neg_lo:[0,1]
	v_pk_add_f32 v[168:169], v[106:107], v[122:123]
	v_pk_add_f32 v[186:187], v[106:107], v[122:123] neg_lo:[0,1] neg_hi:[0,1]
	v_pk_add_f32 v[180:181], v[114:115], v[130:131]
	v_pk_add_f32 v[182:183], v[114:115], v[130:131] neg_lo:[0,1] neg_hi:[0,1]
	v_pk_add_f32 v[106:107], v[168:169], v[180:181]
	v_pk_add_f32 v[122:123], v[168:169], v[180:181] neg_lo:[0,1] neg_hi:[0,1]
	v_pk_add_f32 v[114:115], v[186:187], v[182:183] op_sel:[0,1] op_sel_hi:[1,0] neg_hi:[0,1]
	v_pk_add_f32 v[130:131], v[186:187], v[182:183] op_sel:[0,1] op_sel_hi:[1,0] neg_lo:[0,1]
	v_pk_mul_f32 v[178:179], v[110:111], s[68:69] op_sel:[1,1] op_sel_hi:[0,1]
	v_pk_fma_f32 v[110:111], v[110:111], s[68:69], v[178:179] op_sel_hi:[1,0,1] neg_lo:[0,0,1]
	v_pk_mul_f32 v[176:177], v[112:113], s[84:85] op_sel:[1,1] op_sel_hi:[0,1]
	v_pk_fma_f32 v[112:113], v[112:113], s[84:85], v[176:177] op_sel_hi:[1,0,1] neg_lo:[0,0,1]
	v_pk_mul_f32 v[184:185], v[114:115], s[88:89] op_sel:[1,1] op_sel_hi:[0,1]
	v_pk_fma_f32 v[114:115], v[114:115], s[88:89], v[184:185] op_sel_hi:[1,0,1] neg_lo:[0,0,1]
	v_pk_mul_f32 v[174:175], v[118:119], s[84:85] op_sel:[1,1] op_sel_hi:[0,1]
	v_pk_fma_f32 v[118:119], v[118:119], s[84:85], v[174:175] op_sel_hi:[1,0,1] neg_lo:[0,0,1]
	v_pk_mul_f32 v[166:167], v[122:123], s[90:91] op_sel:[1,1] op_sel_hi:[0,1]
	v_pk_fma_f32 v[122:123], v[122:123], s[90:91], v[166:167] op_sel_hi:[1,0,1] neg_lo:[0,0,1]
	v_pk_mul_f32 v[188:189], v[126:127], s[88:89] op_sel:[1,1] op_sel_hi:[0,1]
	v_pk_fma_f32 v[126:127], v[126:127], s[88:89], v[188:189] op_sel_hi:[1,0,1] neg_lo:[0,0,1]
	v_pk_mul_f32 v[168:169], v[128:129], s[90:91] op_sel:[1,1] op_sel_hi:[0,1]
	v_pk_fma_f32 v[128:129], v[128:129], s[90:91], v[168:169] op_sel_hi:[1,0,1] neg_lo:[0,0,1]
	v_pk_mul_f32 v[186:187], v[130:131], s[98:99] op_sel:[1,1] op_sel_hi:[0,1]
	v_pk_fma_f32 v[130:131], v[130:131], s[98:99], v[186:187] op_sel_hi:[1,0,1] neg_lo:[0,0,1]
	v_pk_add_f32 v[180:181], v[100:101], v[104:105]
	v_pk_add_f32 v[182:183], v[100:101], v[104:105] neg_lo:[0,1] neg_hi:[0,1]
	v_pk_add_f32 v[178:179], v[102:103], v[106:107]
	v_pk_add_f32 v[176:177], v[102:103], v[106:107] neg_lo:[0,1] neg_hi:[0,1]
	v_pk_add_f32 v[100:101], v[180:181], v[178:179]
	v_pk_add_f32 v[104:105], v[180:181], v[178:179] neg_lo:[0,1] neg_hi:[0,1]
	v_pk_add_f32 v[102:103], v[182:183], v[176:177] op_sel:[0,1] op_sel_hi:[1,0] neg_hi:[0,1]
	v_pk_add_f32 v[106:107], v[182:183], v[176:177] op_sel:[0,1] op_sel_hi:[1,0] neg_lo:[0,1]
	v_pk_add_f32 v[184:185], v[108:109], v[112:113]
	v_pk_add_f32 v[174:175], v[108:109], v[112:113] neg_lo:[0,1] neg_hi:[0,1]
	v_pk_add_f32 v[166:167], v[110:111], v[114:115]
	v_pk_add_f32 v[188:189], v[110:111], v[114:115] neg_lo:[0,1] neg_hi:[0,1]
	v_pk_add_f32 v[108:109], v[184:185], v[166:167]
	v_pk_add_f32 v[112:113], v[184:185], v[166:167] neg_lo:[0,1] neg_hi:[0,1]
	v_pk_add_f32 v[110:111], v[174:175], v[188:189] op_sel:[0,1] op_sel_hi:[1,0] neg_hi:[0,1]
; #define LAS __attribute__((address_space(3)))
; __device__ __forceinline__ f32x2 cmul(f32x2 a, f32x2 b) { return (f32x2){a.x * b.x - a.y * b.y, a.x * b.y + a.y * b.x}; }
; __device__ __forceinline__ void dft16_fwd_lo(f32x2 (&x)[16]) {
;     constexpr float C1 = 0.92387953251128674f, S1 = 0.38268343236508977f, C2 = 0.70710678118654752f;
; #pragma unroll
;     for (int b = 0; b < 4; ++b) { const f32x2 x0 = x[b], x1 = x[4 + b]; const f32x2 j1 = {x1.y, -x1.x};
;         x[b] = x0 + x1; x[4 + b] = x0 + j1; x[8 + b] = x0 - x1; x[12 + b] = x0 - j1; }
;     const f32x2 w1 = {C1, -S1}, w2 = {C2, -C2}, w3 = {S1, -C1}, w4 = {0.f, -1.f}, w6 = {-C2, -C2}, w9 = {-C1, S1};
;     x[5] = cmul(x[5], w1); x[6] = cmul(x[6], w2); x[7] = cmul(x[7], w3);
;     x[9] = cmul(x[9], w2); x[10] = cmul(x[10], w4); x[11] = cmul(x[11], w6);
;     x[13] = cmul(x[13], w3); x[14] = cmul(x[14], w6); x[15] = cmul(x[15], w9);
; #pragma unroll
;     for (int c = 0; c < 4; ++c) dft4<false>(x[4 * c], x[4 * c + 1], x[4 * c + 2], x[4 * c + 3]);
;     f32x2 y[16];
; #pragma unroll
;     for (int k = 0; k < 16; ++k) y[k] = x[4 * (k & 3) + (k >> 2)];
; #pragma unroll
;     for (int k = 0; k < 16; ++k) x[k] = y[k];
; }
; template <bool LO> __device__ __forceinline__ void fft_fwd1(f32x2 (&x)[16], LAS f32x2* B, int n2, const f32x2 (&w)[16]) {
;     asm volatile("" : "+v"(n2));
;     if (LO) dft16_fwd_lo(x); else dft16<false>(x);
;     B[fpad(n2)] = x[0];
; #pragma unroll
;     for (int k = 1; k < 16; ++k) B[fpad(512 * k + n2)] = cmul(x[k], w[k]);
; }
	v_pk_add_f32 v[114:115], v[174:175], v[188:189] op_sel:[0,1] op_sel_hi:[1,0] neg_lo:[0,1]
	v_pk_add_f32 v[168:169], v[116:117], v[120:121] op_sel:[0,1] op_sel_hi:[1,0] neg_hi:[0,1]
	v_pk_add_f32 v[186:187], v[116:117], v[120:121] op_sel:[0,1] op_sel_hi:[1,0] neg_lo:[0,1]
	v_pk_add_f32 v[180:181], v[118:119], v[122:123]
	v_pk_add_f32 v[182:183], v[118:119], v[122:123] neg_lo:[0,1] neg_hi:[0,1]
	v_pk_add_f32 v[116:117], v[168:169], v[180:181]
	v_pk_add_f32 v[120:121], v[168:169], v[180:181] neg_lo:[0,1] neg_hi:[0,1]
	v_pk_add_f32 v[118:119], v[186:187], v[182:183] op_sel:[0,1] op_sel_hi:[1,0] neg_hi:[0,1]
	v_pk_add_f32 v[122:123], v[186:187], v[182:183] op_sel:[0,1] op_sel_hi:[1,0] neg_lo:[0,1]
	v_pk_add_f32 v[178:179], v[124:125], v[128:129]
	v_pk_add_f32 v[176:177], v[124:125], v[128:129] neg_lo:[0,1] neg_hi:[0,1]
	v_pk_add_f32 v[184:185], v[126:127], v[130:131]
	v_pk_add_f32 v[174:175], v[126:127], v[130:131] neg_lo:[0,1] neg_hi:[0,1]
	v_pk_add_f32 v[124:125], v[178:179], v[184:185]
	v_pk_add_f32 v[128:129], v[178:179], v[184:185] neg_lo:[0,1] neg_hi:[0,1]
	v_pk_add_f32 v[126:127], v[176:177], v[174:175] op_sel:[0,1] op_sel_hi:[1,0] neg_hi:[0,1]
	v_pk_add_f32 v[130:131], v[176:177], v[174:175] op_sel:[0,1] op_sel_hi:[1,0] neg_lo:[0,1]
	v_pk_mul_f32 v[100:101], v[100:101], v[192:193] op_sel_hi:[1,0]
	ds_write_b64 v69, v[100:101]
	v_pk_mul_f32 v[108:109], v[108:109], v[192:193] op_sel_hi:[1,0]
	ds_write_b64 v69, v[108:109] offset:16
	v_pk_mul_f32 v[116:117], v[116:117], v[192:193] op_sel_hi:[1,0]
	ds_write_b64 v69, v[116:117] offset:32
	v_pk_mul_f32 v[124:125], v[124:125], v[192:193] op_sel_hi:[1,0]
	ds_write_b64 v69, v[124:125] offset:48
	v_pk_mul_f32 v[102:103], v[102:103], v[192:193] op_sel_hi:[1,0]
	ds_write_b64 v69, v[102:103] offset:64
	v_pk_mul_f32 v[110:111], v[110:111], v[192:193] op_sel_hi:[1,0]
	ds_write_b64 v69, v[110:111] offset:80
	v_pk_mul_f32 v[118:119], v[118:119], v[192:193] op_sel_hi:[1,0]
	ds_write_b64 v69, v[118:119] offset:96
	v_pk_mul_f32 v[126:127], v[126:127], v[192:193] op_sel_hi:[1,0]
	ds_write_b64 v69, v[126:127] offset:112
	v_pk_mul_f32 v[104:105], v[104:105], v[192:193] op_sel_hi:[1,0]
	ds_write_b64 v69, v[104:105] offset:128
	v_pk_mul_f32 v[112:113], v[112:113], v[192:193] op_sel_hi:[1,0]
	ds_write_b64 v69, v[112:113] offset:144
	v_pk_mul_f32 v[120:121], v[120:121], v[192:193] op_sel_hi:[1,0]
	ds_write_b64 v69, v[120:121] offset:160
	v_pk_mul_f32 v[128:129], v[128:129], v[192:193] op_sel_hi:[1,0]
	ds_write_b64 v69, v[128:129] offset:176
	v_pk_mul_f32 v[106:107], v[106:107], v[192:193] op_sel_hi:[1,0]
	ds_write_b64 v69, v[106:107] offset:192
	v_pk_mul_f32 v[114:115], v[114:115], v[192:193] op_sel_hi:[1,0]
	ds_write_b64 v69, v[114:115] offset:208
	v_pk_mul_f32 v[122:123], v[122:123], v[192:193] op_sel_hi:[1,0]
	ds_write_b64 v69, v[122:123] offset:224
	v_pk_mul_f32 v[130:131], v[130:131], v[192:193] op_sel_hi:[1,0]
	ds_write_b64 v69, v[130:131] offset:240
	s_waitcnt lgkmcnt(0)
	s_barrier
	v_pk_add_f32 v[104:105], v[132:133], v[140:141] neg_lo:[0,1] neg_hi:[0,1]
	v_pk_add_f32 v[106:107], v[132:133], v[140:141] op_sel:[0,1] op_sel_hi:[1,0] neg_lo:[0,1]
	v_pk_add_f32 v[166:167], v[132:133], v[140:141] op_sel:[0,1] op_sel_hi:[1,0] neg_hi:[0,1]
	v_pk_add_f32 v[100:101], v[132:133], v[140:141]
	v_pk_add_f32 v[112:113], v[134:135], v[142:143] neg_lo:[0,1] neg_hi:[0,1]
	v_pk_add_f32 v[114:115], v[134:135], v[142:143] op_sel:[0,1] op_sel_hi:[1,0] neg_lo:[0,1]
	v_pk_add_f32 v[188:189], v[134:135], v[142:143] op_sel:[0,1] op_sel_hi:[1,0] neg_hi:[0,1]
	v_pk_add_f32 v[108:109], v[134:135], v[142:143]
	v_pk_add_f32 v[120:121], v[136:137], v[144:145] neg_lo:[0,1] neg_hi:[0,1]
	v_pk_add_f32 v[122:123], v[136:137], v[144:145] op_sel:[0,1] op_sel_hi:[1,0] neg_lo:[0,1]
	v_pk_add_f32 v[168:169], v[136:137], v[144:145] op_sel:[0,1] op_sel_hi:[1,0] neg_hi:[0,1]
	v_pk_add_f32 v[116:117], v[136:137], v[144:145]
	v_pk_add_f32 v[128:129], v[138:139], v[146:147] neg_lo:[0,1] neg_hi:[0,1]
	v_pk_add_f32 v[130:131], v[138:139], v[146:147] op_sel:[0,1] op_sel_hi:[1,0] neg_lo:[0,1]
	v_pk_add_f32 v[186:187], v[138:139], v[146:147] op_sel:[0,1] op_sel_hi:[1,0] neg_hi:[0,1]
	v_pk_add_f32 v[124:125], v[138:139], v[146:147]
	v_pk_mul_f32 v[180:181], v[188:189], s[68:69] op_sel:[1,1] op_sel_hi:[0,1]
	v_pk_fma_f32 v[188:189], v[188:189], s[68:69], v[180:181] op_sel_hi:[1,0,1] neg_lo:[0,0,1]
	v_pk_mul_f32 v[182:183], v[168:169], s[84:85] op_sel:[1,1] op_sel_hi:[0,1]
	v_pk_fma_f32 v[168:169], v[168:169], s[84:85], v[182:183] op_sel_hi:[1,0,1] neg_lo:[0,0,1]
	v_pk_mul_f32 v[178:179], v[186:187], s[88:89] op_sel:[1,1] op_sel_hi:[0,1]
	v_pk_fma_f32 v[186:187], v[186:187], s[88:89], v[178:179] op_sel_hi:[1,0,1] neg_lo:[0,0,1]
	v_pk_mul_f32 v[176:177], v[112:113], s[84:85] op_sel:[1,1] op_sel_hi:[0,1]
	v_pk_fma_f32 v[112:113], v[112:113], s[84:85], v[176:177] op_sel_hi:[1,0,1] neg_lo:[0,0,1]
	v_pk_mul_f32 v[184:185], v[128:129], s[90:91] op_sel:[1,1] op_sel_hi:[0,1]
	v_pk_fma_f32 v[128:129], v[128:129], s[90:91], v[184:185] op_sel_hi:[1,0,1] neg_lo:[0,0,1]
	v_pk_mul_f32 v[174:175], v[114:115], s[88:89] op_sel:[1,1] op_sel_hi:[0,1]
	v_pk_fma_f32 v[114:115], v[114:115], s[88:89], v[174:175] op_sel_hi:[1,0,1] neg_lo:[0,0,1]
	v_pk_mul_f32 v[102:103], v[122:123], s[90:91] op_sel:[1,1] op_sel_hi:[0,1]
	v_pk_fma_f32 v[122:123], v[122:123], s[90:91], v[102:103] op_sel_hi:[1,0,1] neg_lo:[0,0,1]
	v_pk_mul_f32 v[110:111], v[130:131], s[98:99] op_sel:[1,1] op_sel_hi:[0,1]
	v_pk_fma_f32 v[130:131], v[130:131], s[98:99], v[110:111] op_sel_hi:[1,0,1] neg_lo:[0,0,1]
	v_pk_add_f32 v[118:119], v[100:101], v[116:117]
	v_pk_add_f32 v[126:127], v[100:101], v[116:117] neg_lo:[0,1] neg_hi:[0,1]
; #define LAS __attribute__((address_space(3)))
; __device__ __forceinline__ f32x2 cmul(f32x2 a, f32x2 b) { return (f32x2){a.x * b.x - a.y * b.y, a.x * b.y + a.y * b.x}; }
; __device__ __forceinline__ void dft16_fwd_lo(f32x2 (&x)[16]) {
;     constexpr float C1 = 0.92387953251128674f, S1 = 0.38268343236508977f, C2 = 0.70710678118654752f;
; #pragma unroll
;     for (int b = 0; b < 4; ++b) { const f32x2 x0 = x[b], x1 = x[4 + b]; const f32x2 j1 = {x1.y, -x1.x};
;         x[b] = x0 + x1; x[4 + b] = x0 + j1; x[8 + b] = x0 - x1; x[12 + b] = x0 - j1; }
;     const f32x2 w1 = {C1, -S1}, w2 = {C2, -C2}, w3 = {S1, -C1}, w4 = {0.f, -1.f}, w6 = {-C2, -C2}, w9 = {-C1, S1};
;     x[5] = cmul(x[5], w1); x[6] = cmul(x[6], w2); x[7] = cmul(x[7], w3);
;     x[9] = cmul(x[9], w2); x[10] = cmul(x[10], w4); x[11] = cmul(x[11], w6);
;     x[13] = cmul(x[13], w3); x[14] = cmul(x[14], w6); x[15] = cmul(x[15], w9);
; #pragma unroll
;     for (int c = 0; c < 4; ++c) dft4<false>(x[4 * c], x[4 * c + 1], x[4 * c + 2], x[4 * c + 3]);
;     f32x2 y[16];
; #pragma unroll
;     for (int k = 0; k < 16; ++k) y[k] = x[4 * (k & 3) + (k >> 2)];
; #pragma unroll
;     for (int k = 0; k < 16; ++k) x[k] = y[k];
; }
; template <bool LO> __device__ __forceinline__ void fft_fwd1(f32x2 (&x)[16], LAS f32x2* B, int n2, const f32x2 (&w)[16]) {
;     asm volatile("" : "+v"(n2));
;     if (LO) dft16_fwd_lo(x); else dft16<false>(x);
;     B[fpad(n2)] = x[0];
; #pragma unroll
;     for (int k = 1; k < 16; ++k) B[fpad(512 * k + n2)] = cmul(x[k], w[k]);
; }
	v_pk_add_f32 v[180:181], v[108:109], v[124:125]
	v_pk_add_f32 v[182:183], v[108:109], v[124:125] neg_lo:[0,1] neg_hi:[0,1]
	v_pk_add_f32 v[100:101], v[118:119], v[180:181]
	v_pk_add_f32 v[116:117], v[118:119], v[180:181] neg_lo:[0,1] neg_hi:[0,1]
	v_pk_add_f32 v[108:109], v[126:127], v[182:183] op_sel:[0,1] op_sel_hi:[1,0] neg_hi:[0,1]
	v_pk_add_f32 v[124:125], v[126:127], v[182:183] op_sel:[0,1] op_sel_hi:[1,0] neg_lo:[0,1]
	v_pk_add_f32 v[178:179], v[166:167], v[168:169]
	v_pk_add_f32 v[176:177], v[166:167], v[168:169] neg_lo:[0,1] neg_hi:[0,1]
	v_pk_add_f32 v[184:185], v[188:189], v[186:187]
	v_pk_add_f32 v[174:175], v[188:189], v[186:187] neg_lo:[0,1] neg_hi:[0,1]
	v_pk_add_f32 v[166:167], v[178:179], v[184:185]
	v_pk_add_f32 v[168:169], v[178:179], v[184:185] neg_lo:[0,1] neg_hi:[0,1]
	v_pk_add_f32 v[188:189], v[176:177], v[174:175] op_sel:[0,1] op_sel_hi:[1,0] neg_hi:[0,1]
	v_pk_add_f32 v[186:187], v[176:177], v[174:175] op_sel:[0,1] op_sel_hi:[1,0] neg_lo:[0,1]
	v_pk_add_f32 v[102:103], v[104:105], v[120:121] op_sel:[0,1] op_sel_hi:[1,0] neg_hi:[0,1]
	v_pk_add_f32 v[110:111], v[104:105], v[120:121] op_sel:[0,1] op_sel_hi:[1,0] neg_lo:[0,1]
	v_pk_add_f32 v[118:119], v[112:113], v[128:129]
	v_pk_add_f32 v[126:127], v[112:113], v[128:129] neg_lo:[0,1] neg_hi:[0,1]
	v_pk_add_f32 v[104:105], v[102:103], v[118:119]
	v_pk_add_f32 v[120:121], v[102:103], v[118:119] neg_lo:[0,1] neg_hi:[0,1]
	v_pk_add_f32 v[112:113], v[110:111], v[126:127] op_sel:[0,1] op_sel_hi:[1,0] neg_hi:[0,1]
	v_pk_add_f32 v[128:129], v[110:111], v[126:127] op_sel:[0,1] op_sel_hi:[1,0] neg_lo:[0,1]
	v_pk_add_f32 v[180:181], v[106:107], v[122:123]
	v_pk_add_f32 v[182:183], v[106:107], v[122:123] neg_lo:[0,1] neg_hi:[0,1]
	v_pk_add_f32 v[178:179], v[114:115], v[130:131]
	v_pk_add_f32 v[176:177], v[114:115], v[130:131] neg_lo:[0,1] neg_hi:[0,1]
	v_pk_add_f32 v[106:107], v[180:181], v[178:179]
	v_pk_add_f32 v[122:123], v[180:181], v[178:179] neg_lo:[0,1] neg_hi:[0,1]
	v_pk_add_f32 v[114:115], v[182:183], v[176:177] op_sel:[0,1] op_sel_hi:[1,0] neg_hi:[0,1]
	v_pk_add_f32 v[130:131], v[182:183], v[176:177] op_sel:[0,1] op_sel_hi:[1,0] neg_lo:[0,1]
	ds_write_b64 v3, v[100:101]
	v_pk_mul_f32 v[174:175], v[166:167], v[6:7] op_sel:[1,1] op_sel_hi:[0,1]
	v_pk_fma_f32 v[184:185], v[166:167], v[6:7], v[174:175] op_sel_hi:[1,0,1] neg_lo:[0,0,1]
	ds_write_b64 v3, v[184:185] offset:4224
	v_pk_mul_f32 v[110:111], v[104:105], v[8:9] op_sel:[1,1] op_sel_hi:[0,1]
	v_pk_fma_f32 v[102:103], v[104:105], v[8:9], v[110:111] op_sel_hi:[1,0,1] neg_lo:[0,0,1]
	ds_write_b64 v3, v[102:103] offset:8448
	v_pk_mul_f32 v[126:127], v[106:107], v[10:11] op_sel:[1,1] op_sel_hi:[0,1]
	v_pk_fma_f32 v[118:119], v[106:107], v[10:11], v[126:127] op_sel_hi:[1,0,1] neg_lo:[0,0,1]
	ds_write_b64 v3, v[118:119] offset:12672
	v_pk_mul_f32 v[182:183], v[108:109], v[12:13] op_sel:[1,1] op_sel_hi:[0,1]
	v_pk_fma_f32 v[180:181], v[108:109], v[12:13], v[182:183] op_sel_hi:[1,0,1] neg_lo:[0,0,1]
	ds_write_b64 v3, v[180:181] offset:16896
	v_pk_mul_f32 v[176:177], v[188:189], v[14:15] op_sel:[1,1] op_sel_hi:[0,1]
	v_pk_fma_f32 v[178:179], v[188:189], v[14:15], v[176:177] op_sel_hi:[1,0,1] neg_lo:[0,0,1]
	ds_write_b64 v3, v[178:179] offset:21120
	v_pk_mul_f32 v[184:185], v[112:113], v[16:17] op_sel:[1,1] op_sel_hi:[0,1]
	v_pk_fma_f32 v[174:175], v[112:113], v[16:17], v[184:185] op_sel_hi:[1,0,1] neg_lo:[0,0,1]
	ds_write_b64 v3, v[174:175] offset:25344
	v_pk_mul_f32 v[102:103], v[114:115], v[18:19] op_sel:[1,1] op_sel_hi:[0,1]
	v_pk_fma_f32 v[110:111], v[114:115], v[18:19], v[102:103] op_sel_hi:[1,0,1] neg_lo:[0,0,1]
	ds_write_b64 v3, v[110:111] offset:29568
	v_pk_mul_f32 v[118:119], v[116:117], v[20:21] op_sel:[1,1] op_sel_hi:[0,1]
	v_pk_fma_f32 v[126:127], v[116:117], v[20:21], v[118:119] op_sel_hi:[1,0,1] neg_lo:[0,0,1]
	ds_write_b64 v3, v[126:127] offset:33792
	v_pk_mul_f32 v[180:181], v[168:169], v[22:23] op_sel:[1,1] op_sel_hi:[0,1]
	v_pk_fma_f32 v[182:183], v[168:169], v[22:23], v[180:181] op_sel_hi:[1,0,1] neg_lo:[0,0,1]
	ds_write_b64 v3, v[182:183] offset:38016
	v_pk_mul_f32 v[178:179], v[120:121], v[24:25] op_sel:[1,1] op_sel_hi:[0,1]
	v_pk_fma_f32 v[176:177], v[120:121], v[24:25], v[178:179] op_sel_hi:[1,0,1] neg_lo:[0,0,1]
	ds_write_b64 v3, v[176:177] offset:42240
	v_pk_mul_f32 v[174:175], v[122:123], v[26:27] op_sel:[1,1] op_sel_hi:[0,1]
	v_pk_fma_f32 v[184:185], v[122:123], v[26:27], v[174:175] op_sel_hi:[1,0,1] neg_lo:[0,0,1]
	ds_write_b64 v3, v[184:185] offset:46464
	v_pk_mul_f32 v[110:111], v[124:125], v[28:29] op_sel:[1,1] op_sel_hi:[0,1]
	v_pk_fma_f32 v[102:103], v[124:125], v[28:29], v[110:111] op_sel_hi:[1,0,1] neg_lo:[0,0,1]
	ds_write_b64 v3, v[102:103] offset:50688
	v_pk_mul_f32 v[126:127], v[186:187], v[30:31] op_sel:[1,1] op_sel_hi:[0,1]
	v_pk_fma_f32 v[118:119], v[186:187], v[30:31], v[126:127] op_sel_hi:[1,0,1] neg_lo:[0,0,1]
	ds_write_b64 v3, v[118:119] offset:54912
	v_pk_mul_f32 v[182:183], v[128:129], v[32:33] op_sel:[1,1] op_sel_hi:[0,1]
	v_pk_fma_f32 v[180:181], v[128:129], v[32:33], v[182:183] op_sel_hi:[1,0,1] neg_lo:[0,0,1]
	ds_write_b64 v3, v[180:181] offset:59136
	v_pk_mul_f32 v[176:177], v[130:131], v[34:35] op_sel:[1,1] op_sel_hi:[0,1]
	v_pk_fma_f32 v[178:179], v[130:131], v[34:35], v[176:177] op_sel_hi:[1,0,1] neg_lo:[0,0,1]
	ds_write_b64 v3, v[178:179] offset:63360
	s_waitcnt lgkmcnt(0)
	s_barrier
; #define LAS __attribute__((address_space(3)))
; __device__ __forceinline__ f32x2 cmul(f32x2 a, f32x2 b) { return (f32x2){a.x * b.x - a.y * b.y, a.x * b.y + a.y * b.x}; }
; template <bool INV> __device__ __forceinline__ f32x2 cmul_tw(f32x2 a, f32x2 w) { return INV ? cmulc(a, w) : cmul(a, w); }
; template <bool INV> __device__ __forceinline__ void dft16(f32x2 (&x)[16]) {
;     constexpr float C1 = 0.92387953251128674f, S1 = 0.38268343236508977f, C2 = 0.70710678118654752f;
; #pragma unroll
;     for (int b = 0; b < 4; ++b) dft4<INV>(x[b], x[4 + b], x[8 + b], x[12 + b]);
;     const f32x2 w1 = {C1, -S1}, w2 = {C2, -C2}, w3 = {S1, -C1}, w4 = {0.f, -1.f}, w6 = {-C2, -C2}, w9 = {-C1, S1};
;     x[4 * 1 + 1] = cmul_tw<INV>(x[5], w1); x[4 * 1 + 2] = cmul_tw<INV>(x[6], w2); x[4 * 1 + 3] = cmul_tw<INV>(x[7], w3);
;     x[4 * 2 + 1] = cmul_tw<INV>(x[9], w2); x[4 * 2 + 2] = cmul_tw<INV>(x[10], w4); x[4 * 2 + 3] = cmul_tw<INV>(x[11], w6);
;     x[4 * 3 + 1] = cmul_tw<INV>(x[13], w3); x[4 * 3 + 2] = cmul_tw<INV>(x[14], w6); x[4 * 3 + 3] = cmul_tw<INV>(x[15], w9);
; #pragma unroll
;     for (int c = 0; c < 4; ++c) dft4<INV>(x[4 * c], x[4 * c + 1], x[4 * c + 2], x[4 * c + 3]);
;     f32x2 y[16];
; #pragma unroll
;     for (int k = 0; k < 16; ++k) y[k] = x[4 * (k & 3) + (k >> 2)];
; #pragma unroll
;     for (int k = 0; k < 16; ++k) x[k] = y[k];
; }
; __device__ __forceinline__ void fft_fwd2(LAS f32x2* B, const LAS f32x2* TW2, int tid) {
;     asm volatile("" : "+v"(tid));
;     const int b = tid >> 5, n2 = tid & 31, base = 512 * b + n2; f32x2 x[16];
; #pragma unroll
;     for (int r = 0; r < 16; ++r) x[r] = B[fpad(base + 32 * r)];
;     dft16<false>(x);
;     B[fpad(base)] = x[0];
; #pragma unroll
;     for (int k = 1; k < 16; ++k) B[fpad(base + 32 * k)] = cmul(x[k], TW2[k * 32 + n2]);
; }
	ds_read_b64 v[100:101], v5
	ds_read_b64 v[108:109], v5 offset:1056
	ds_read_b64 v[116:117], v5 offset:2112
	ds_read_b64 v[124:125], v5 offset:3168
	ds_read_b64 v[166:167], v5 offset:264
	ds_read_b64 v[188:189], v5 offset:1320
	ds_read_b64 v[168:169], v5 offset:2376
	ds_read_b64 v[186:187], v5 offset:3432
	ds_read_b64 v[104:105], v5 offset:528
	ds_read_b64 v[112:113], v5 offset:1584
	ds_read_b64 v[120:121], v5 offset:2640
	ds_read_b64 v[128:129], v5 offset:3696
	s_waitcnt lgkmcnt(8)
	ds_read_b64 v[106:107], v5 offset:792
	ds_read_b64 v[114:115], v5 offset:1848
	ds_read_b64 v[122:123], v5 offset:2904
	ds_read_b64 v[130:131], v5 offset:3960
	ds_read_b64 v[174:175], v56 offset:256
	ds_read_b64 v[184:185], v56 offset:512
	ds_read_b64 v[110:111], v56 offset:768
	ds_read_b64 v[102:103], v56 offset:1024
	v_pk_add_f32 v[126:127], v[100:101], v[116:117]
	v_pk_add_f32 v[118:119], v[100:101], v[116:117] neg_lo:[0,1] neg_hi:[0,1]
	v_pk_add_f32 v[182:183], v[108:109], v[124:125]
	v_pk_add_f32 v[180:181], v[108:109], v[124:125] neg_lo:[0,1] neg_hi:[0,1]
	v_pk_add_f32 v[100:101], v[126:127], v[182:183]
	v_pk_add_f32 v[116:117], v[126:127], v[182:183] neg_lo:[0,1] neg_hi:[0,1]
	v_pk_add_f32 v[108:109], v[118:119], v[180:181] op_sel:[0,1] op_sel_hi:[1,0] neg_hi:[0,1]
	v_pk_add_f32 v[124:125], v[118:119], v[180:181] op_sel:[0,1] op_sel_hi:[1,0] neg_lo:[0,1]
	s_waitcnt lgkmcnt(13)
	v_pk_add_f32 v[176:177], v[166:167], v[168:169]
	v_pk_add_f32 v[178:179], v[166:167], v[168:169] neg_lo:[0,1] neg_hi:[0,1]
	s_waitcnt lgkmcnt(12)
	v_pk_add_f32 v[126:127], v[188:189], v[186:187]
	v_pk_add_f32 v[118:119], v[188:189], v[186:187] neg_lo:[0,1] neg_hi:[0,1]
	v_pk_add_f32 v[166:167], v[176:177], v[126:127]
	v_pk_add_f32 v[168:169], v[176:177], v[126:127] neg_lo:[0,1] neg_hi:[0,1]
	v_pk_add_f32 v[188:189], v[178:179], v[118:119] op_sel:[0,1] op_sel_hi:[1,0] neg_hi:[0,1]
	v_pk_add_f32 v[186:187], v[178:179], v[118:119] op_sel:[0,1] op_sel_hi:[1,0] neg_lo:[0,1]
	s_waitcnt lgkmcnt(9)
	v_pk_add_f32 v[182:183], v[104:105], v[120:121]
	v_pk_add_f32 v[180:181], v[104:105], v[120:121] neg_lo:[0,1] neg_hi:[0,1]
	s_waitcnt lgkmcnt(8)
	v_pk_add_f32 v[176:177], v[112:113], v[128:129]
	v_pk_add_f32 v[178:179], v[112:113], v[128:129] neg_lo:[0,1] neg_hi:[0,1]
	v_pk_add_f32 v[104:105], v[182:183], v[176:177]
	v_pk_add_f32 v[120:121], v[182:183], v[176:177] neg_lo:[0,1] neg_hi:[0,1]
	v_pk_add_f32 v[112:113], v[180:181], v[178:179] op_sel:[0,1] op_sel_hi:[1,0] neg_hi:[0,1]
	v_pk_add_f32 v[128:129], v[180:181], v[178:179] op_sel:[0,1] op_sel_hi:[1,0] neg_lo:[0,1]
	s_waitcnt lgkmcnt(5)
	v_pk_add_f32 v[126:127], v[106:107], v[122:123]
	v_pk_add_f32 v[118:119], v[106:107], v[122:123] neg_lo:[0,1] neg_hi:[0,1]
	s_waitcnt lgkmcnt(4)
	v_pk_add_f32 v[182:183], v[114:115], v[130:131]
	v_pk_add_f32 v[180:181], v[114:115], v[130:131] neg_lo:[0,1] neg_hi:[0,1]
	v_pk_add_f32 v[106:107], v[126:127], v[182:183]
	v_pk_add_f32 v[122:123], v[126:127], v[182:183] neg_lo:[0,1] neg_hi:[0,1]
	v_pk_add_f32 v[114:115], v[118:119], v[180:181] op_sel:[0,1] op_sel_hi:[1,0] neg_hi:[0,1]
	v_pk_add_f32 v[130:131], v[118:119], v[180:181] op_sel:[0,1] op_sel_hi:[1,0] neg_lo:[0,1]
	v_pk_mul_f32 v[176:177], v[188:189], s[68:69] op_sel:[1,1] op_sel_hi:[0,1]
	v_pk_fma_f32 v[188:189], v[188:189], s[68:69], v[176:177] op_sel_hi:[1,0,1] neg_lo:[0,0,1]
	v_pk_mul_f32 v[178:179], v[112:113], s[84:85] op_sel:[1,1] op_sel_hi:[0,1]
	v_pk_fma_f32 v[112:113], v[112:113], s[84:85], v[178:179] op_sel_hi:[1,0,1] neg_lo:[0,0,1]
	v_pk_mul_f32 v[126:127], v[114:115], s[88:89] op_sel:[1,1] op_sel_hi:[0,1]
	v_pk_fma_f32 v[114:115], v[114:115], s[88:89], v[126:127] op_sel_hi:[1,0,1] neg_lo:[0,0,1]
	v_pk_mul_f32 v[118:119], v[168:169], s[84:85] op_sel:[1,1] op_sel_hi:[0,1]
	v_pk_fma_f32 v[168:169], v[168:169], s[84:85], v[118:119] op_sel_hi:[1,0,1] neg_lo:[0,0,1]
	v_pk_mul_f32 v[182:183], v[122:123], s[90:91] op_sel:[1,1] op_sel_hi:[0,1]
	v_pk_fma_f32 v[122:123], v[122:123], s[90:91], v[182:183] op_sel_hi:[1,0,1] neg_lo:[0,0,1]
	v_pk_mul_f32 v[180:181], v[186:187], s[88:89] op_sel:[1,1] op_sel_hi:[0,1]
	v_pk_fma_f32 v[186:187], v[186:187], s[88:89], v[180:181] op_sel_hi:[1,0,1] neg_lo:[0,0,1]
	v_pk_mul_f32 v[176:177], v[128:129], s[90:91] op_sel:[1,1] op_sel_hi:[0,1]
	v_pk_fma_f32 v[128:129], v[128:129], s[90:91], v[176:177] op_sel_hi:[1,0,1] neg_lo:[0,0,1]
	v_pk_mul_f32 v[178:179], v[130:131], s[98:99] op_sel:[1,1] op_sel_hi:[0,1]
	v_pk_fma_f32 v[130:131], v[130:131], s[98:99], v[178:179] op_sel_hi:[1,0,1] neg_lo:[0,0,1]
	v_pk_add_f32 v[126:127], v[100:101], v[104:105]
	v_pk_add_f32 v[118:119], v[100:101], v[104:105] neg_lo:[0,1] neg_hi:[0,1]
	v_pk_add_f32 v[182:183], v[166:167], v[106:107]
	v_pk_add_f32 v[180:181], v[166:167], v[106:107] neg_lo:[0,1] neg_hi:[0,1]
	v_pk_add_f32 v[100:101], v[126:127], v[182:183]
	v_pk_add_f32 v[104:105], v[126:127], v[182:183] neg_lo:[0,1] neg_hi:[0,1]
	v_pk_add_f32 v[166:167], v[118:119], v[180:181] op_sel:[0,1] op_sel_hi:[1,0] neg_hi:[0,1]
	v_pk_add_f32 v[106:107], v[118:119], v[180:181] op_sel:[0,1] op_sel_hi:[1,0] neg_lo:[0,1]
	v_pk_add_f32 v[176:177], v[108:109], v[112:113]
	v_pk_add_f32 v[178:179], v[108:109], v[112:113] neg_lo:[0,1] neg_hi:[0,1]
	v_pk_add_f32 v[126:127], v[188:189], v[114:115]
	v_pk_add_f32 v[118:119], v[188:189], v[114:115] neg_lo:[0,1] neg_hi:[0,1]
	v_pk_add_f32 v[108:109], v[176:177], v[126:127]
	v_pk_add_f32 v[112:113], v[176:177], v[126:127] neg_lo:[0,1] neg_hi:[0,1]
	v_pk_add_f32 v[188:189], v[178:179], v[118:119] op_sel:[0,1] op_sel_hi:[1,0] neg_hi:[0,1]
	v_pk_add_f32 v[114:115], v[178:179], v[118:119] op_sel:[0,1] op_sel_hi:[1,0] neg_lo:[0,1]
	v_pk_add_f32 v[182:183], v[116:117], v[120:121] op_sel:[0,1] op_sel_hi:[1,0] neg_hi:[0,1]
	v_pk_add_f32 v[180:181], v[116:117], v[120:121] op_sel:[0,1] op_sel_hi:[1,0] neg_lo:[0,1]
	v_pk_add_f32 v[176:177], v[168:169], v[122:123]
	v_pk_add_f32 v[178:179], v[168:169], v[122:123] neg_lo:[0,1] neg_hi:[0,1]
	v_pk_add_f32 v[116:117], v[182:183], v[176:177]
	v_pk_add_f32 v[120:121], v[182:183], v[176:177] neg_lo:[0,1] neg_hi:[0,1]
	v_pk_add_f32 v[168:169], v[180:181], v[178:179] op_sel:[0,1] op_sel_hi:[1,0] neg_hi:[0,1]
	v_pk_add_f32 v[122:123], v[180:181], v[178:179] op_sel:[0,1] op_sel_hi:[1,0] neg_lo:[0,1]
	v_pk_add_f32 v[126:127], v[124:125], v[128:129]
	v_pk_add_f32 v[118:119], v[124:125], v[128:129] neg_lo:[0,1] neg_hi:[0,1]
	v_pk_add_f32 v[182:183], v[186:187], v[130:131]
	v_pk_add_f32 v[180:181], v[186:187], v[130:131] neg_lo:[0,1] neg_hi:[0,1]
	v_pk_add_f32 v[124:125], v[126:127], v[182:183]
	v_pk_add_f32 v[128:129], v[126:127], v[182:183] neg_lo:[0,1] neg_hi:[0,1]
	v_pk_add_f32 v[186:187], v[118:119], v[180:181] op_sel:[0,1] op_sel_hi:[1,0] neg_hi:[0,1]
	v_pk_add_f32 v[130:131], v[118:119], v[180:181] op_sel:[0,1] op_sel_hi:[1,0] neg_lo:[0,1]
	ds_write_b64 v5, v[100:101]
	ds_read_b64 v[176:177], v56 offset:1280
	ds_read_b64 v[178:179], v56 offset:1536
	ds_read_b64 v[126:127], v56 offset:1792
	ds_read_b64 v[118:119], v56 offset:2048
	s_waitcnt lgkmcnt(8)
; #define LAS __attribute__((address_space(3)))
; __device__ __forceinline__ f32x2 cmul(f32x2 a, f32x2 b) { return (f32x2){a.x * b.x - a.y * b.y, a.x * b.y + a.y * b.x}; }
; __device__ __forceinline__ void fft_fwd2(LAS f32x2* B, const LAS f32x2* TW2, int tid) {
;     asm volatile("" : "+v"(tid));
;     const int b = tid >> 5, n2 = tid & 31, base = 512 * b + n2; f32x2 x[16];
; #pragma unroll
;     for (int r = 0; r < 16; ++r) x[r] = B[fpad(base + 32 * r)];
;     dft16<false>(x);
;     B[fpad(base)] = x[0];
; #pragma unroll
;     for (int k = 1; k < 16; ++k) B[fpad(base + 32 * k)] = cmul(x[k], TW2[k * 32 + n2]);
; }
; template <int MODE> __device__ __forceinline__ void fft_pair32(LAS f32x2* B, const LAS f32x2* F, int wave, int lane) {
;     asm volatile("" : "+v"(lane));
;     constexpr float CS[16] = {1.f, 0.98078528040323043f, 0.92387953251128674f, 0.83146961230254524f, 0.70710678118654752f, 0.55557023301960218f, 0.38268343236508977f, 0.19509032201612825f,
;                               0.f, -0.19509032201612825f, -0.38268343236508977f, -0.55557023301960218f, -0.70710678118654752f, -0.83146961230254524f, -0.92387953251128674f, -0.98078528040323043f};
;     constexpr float SN[16] = {0.f, 0.19509032201612825f, 0.38268343236508977f, 0.55557023301960218f, 0.70710678118654752f, 0.83146961230254524f, 0.92387953251128674f, 0.98078528040323043f,
;                               1.f, 0.98078528040323043f, 0.92387953251128674f, 0.83146961230254524f, 0.70710678118654752f, 0.55557023301960218f, 0.38268343236508977f, 0.19509032201612825f};
;     const int hi = lane >> 5, blk = 32 * wave + (lane & 31); const float sg = hi ? -1.f : 1.f;
;     LAS f32x2* p = B + 33 * blk; f32x2 v[16];
; #pragma unroll
;     for (int j = 0; j < 16; ++j) { const f32x2 d = p[j] + p[j + 16] * sg;
;         const f32x2 w = {hi ? CS[j] : 1.f, hi ? -SN[j] : 0.f}; v[j] = j == 0 ? d : cmul(d, w); }
;     dft16<false>(v);
	v_pk_mul_f32 v[182:183], v[108:109], v[174:175] op_sel:[1,1] op_sel_hi:[0,1]
	v_pk_fma_f32 v[108:109], v[108:109], v[174:175], v[182:183] op_sel_hi:[1,0,1] neg_lo:[0,0,1]
	ds_write_b64 v5, v[108:109] offset:264
	s_waitcnt lgkmcnt(8)
	v_pk_mul_f32 v[180:181], v[116:117], v[184:185] op_sel:[1,1] op_sel_hi:[0,1]
	v_pk_fma_f32 v[116:117], v[116:117], v[184:185], v[180:181] op_sel_hi:[1,0,1] neg_lo:[0,0,1]
	ds_write_b64 v5, v[116:117] offset:528
	s_waitcnt lgkmcnt(8)
	v_pk_mul_f32 v[182:183], v[124:125], v[110:111] op_sel:[1,1] op_sel_hi:[0,1]
	v_pk_fma_f32 v[124:125], v[124:125], v[110:111], v[182:183] op_sel_hi:[1,0,1] neg_lo:[0,0,1]
	ds_write_b64 v5, v[124:125] offset:792
	s_waitcnt lgkmcnt(8)
	v_pk_mul_f32 v[180:181], v[166:167], v[102:103] op_sel:[1,1] op_sel_hi:[0,1]
	v_pk_fma_f32 v[166:167], v[166:167], v[102:103], v[180:181] op_sel_hi:[1,0,1] neg_lo:[0,0,1]
	ds_write_b64 v5, v[166:167] offset:1056
	ds_read_b64 v[182:183], v56 offset:2304
	ds_read_b64 v[180:181], v56 offset:2560
	ds_read_b64 v[174:175], v56 offset:2816
	ds_read_b64 v[184:185], v56 offset:3072
	s_waitcnt lgkmcnt(11)
	v_pk_mul_f32 v[110:111], v[188:189], v[176:177] op_sel:[1,1] op_sel_hi:[0,1]
	v_pk_fma_f32 v[188:189], v[188:189], v[176:177], v[110:111] op_sel_hi:[1,0,1] neg_lo:[0,0,1]
	ds_write_b64 v5, v[188:189] offset:1320
	s_waitcnt lgkmcnt(11)
	v_pk_mul_f32 v[102:103], v[168:169], v[178:179] op_sel:[1,1] op_sel_hi:[0,1]
	v_pk_fma_f32 v[168:169], v[168:169], v[178:179], v[102:103] op_sel_hi:[1,0,1] neg_lo:[0,0,1]
	ds_write_b64 v5, v[168:169] offset:1584
	s_waitcnt lgkmcnt(11)
	v_pk_mul_f32 v[110:111], v[186:187], v[126:127] op_sel:[1,1] op_sel_hi:[0,1]
	v_pk_fma_f32 v[186:187], v[186:187], v[126:127], v[110:111] op_sel_hi:[1,0,1] neg_lo:[0,0,1]
	ds_write_b64 v5, v[186:187] offset:1848
	s_waitcnt lgkmcnt(11)
	v_pk_mul_f32 v[102:103], v[104:105], v[118:119] op_sel:[1,1] op_sel_hi:[0,1]
	v_pk_fma_f32 v[104:105], v[104:105], v[118:119], v[102:103] op_sel_hi:[1,0,1] neg_lo:[0,0,1]
	ds_write_b64 v5, v[104:105] offset:2112
	ds_read_b64 v[110:111], v56 offset:3328
	ds_read_b64 v[102:103], v56 offset:3584
	ds_read_b64 v[176:177], v56 offset:3840
	s_waitcnt lgkmcnt(10)
	v_pk_mul_f32 v[178:179], v[112:113], v[182:183] op_sel:[1,1] op_sel_hi:[0,1]
	v_pk_fma_f32 v[112:113], v[112:113], v[182:183], v[178:179] op_sel_hi:[1,0,1] neg_lo:[0,0,1]
	ds_write_b64 v5, v[112:113] offset:2376
	s_waitcnt lgkmcnt(10)
	v_pk_mul_f32 v[126:127], v[120:121], v[180:181] op_sel:[1,1] op_sel_hi:[0,1]
	v_pk_fma_f32 v[120:121], v[120:121], v[180:181], v[126:127] op_sel_hi:[1,0,1] neg_lo:[0,0,1]
	ds_write_b64 v5, v[120:121] offset:2640
	s_waitcnt lgkmcnt(10)
	v_pk_mul_f32 v[118:119], v[128:129], v[174:175] op_sel:[1,1] op_sel_hi:[0,1]
	v_pk_fma_f32 v[128:129], v[128:129], v[174:175], v[118:119] op_sel_hi:[1,0,1] neg_lo:[0,0,1]
	ds_write_b64 v5, v[128:129] offset:2904
	s_waitcnt lgkmcnt(10)
	v_pk_mul_f32 v[178:179], v[106:107], v[184:185] op_sel:[1,1] op_sel_hi:[0,1]
	v_pk_fma_f32 v[106:107], v[106:107], v[184:185], v[178:179] op_sel_hi:[1,0,1] neg_lo:[0,0,1]
	ds_write_b64 v5, v[106:107] offset:3168
	s_waitcnt lgkmcnt(6)
	v_pk_mul_f32 v[126:127], v[114:115], v[110:111] op_sel:[1,1] op_sel_hi:[0,1]
	v_pk_fma_f32 v[114:115], v[114:115], v[110:111], v[126:127] op_sel_hi:[1,0,1] neg_lo:[0,0,1]
	ds_write_b64 v5, v[114:115] offset:3432
	s_waitcnt lgkmcnt(6)
	v_pk_mul_f32 v[118:119], v[122:123], v[102:103] op_sel:[1,1] op_sel_hi:[0,1]
	v_pk_fma_f32 v[122:123], v[122:123], v[102:103], v[118:119] op_sel_hi:[1,0,1] neg_lo:[0,0,1]
	ds_write_b64 v5, v[122:123] offset:3696
	s_waitcnt lgkmcnt(6)
	v_pk_mul_f32 v[178:179], v[130:131], v[176:177] op_sel:[1,1] op_sel_hi:[0,1]
	v_pk_fma_f32 v[130:131], v[130:131], v[176:177], v[178:179] op_sel_hi:[1,0,1] neg_lo:[0,0,1]
	ds_write_b64 v5, v[130:131] offset:3960
	s_waitcnt lgkmcnt(0)
	ds_read_b64 v[100:101], v156
	ds_read_b64 v[182:183], v156 offset:128
	ds_read_b64 v[108:109], v156 offset:8
	ds_read_b64 v[180:181], v156 offset:136
	ds_read_b64 v[116:117], v156 offset:16
	ds_read_b64 v[174:175], v156 offset:144
	ds_read_b64 v[124:125], v156 offset:24
	ds_read_b64 v[184:185], v156 offset:152
	ds_read_b64 v[166:167], v156 offset:32
	ds_read_b64 v[126:127], v156 offset:160
	ds_read_b64 v[188:189], v156 offset:40
	ds_read_b64 v[118:119], v156 offset:168
	ds_read_b64 v[168:169], v156 offset:48
	ds_read_b64 v[178:179], v156 offset:176
	ds_read_b64 v[186:187], v156 offset:56
	ds_read_b64 v[110:111], v156 offset:184
	s_waitcnt lgkmcnt(14)
	v_pk_fma_f32 v[100:101], v[182:183], v[190:191], v[100:101] op_sel_hi:[1,0,1]
	s_waitcnt lgkmcnt(12)
	v_pk_fma_f32 v[108:109], v[180:181], v[190:191], v[108:109] op_sel_hi:[1,0,1]
	v_pk_mul_f32 v[102:103], v[108:109], v[36:37] op_sel:[1,1] op_sel_hi:[0,1]
	v_pk_fma_f32 v[108:109], v[108:109], v[36:37], v[102:103] op_sel_hi:[1,0,1] neg_lo:[0,0,1]
	s_waitcnt lgkmcnt(10)
	v_pk_fma_f32 v[116:117], v[174:175], v[190:191], v[116:117] op_sel_hi:[1,0,1]
	v_pk_mul_f32 v[176:177], v[116:117], v[38:39] op_sel:[1,1] op_sel_hi:[0,1]
	v_pk_fma_f32 v[116:117], v[116:117], v[38:39], v[176:177] op_sel_hi:[1,0,1] neg_lo:[0,0,1]
	s_waitcnt lgkmcnt(8)
	v_pk_fma_f32 v[124:125], v[184:185], v[190:191], v[124:125] op_sel_hi:[1,0,1]
	v_pk_mul_f32 v[102:103], v[124:125], v[40:41] op_sel:[1,1] op_sel_hi:[0,1]
	v_pk_fma_f32 v[124:125], v[124:125], v[40:41], v[102:103] op_sel_hi:[1,0,1] neg_lo:[0,0,1]
	ds_read_b64 v[104:105], v156 offset:64
	ds_read_b64 v[176:177], v156 offset:192
	ds_read_b64 v[112:113], v156 offset:72
	ds_read_b64 v[102:103], v156 offset:200
	ds_read_b64 v[120:121], v156 offset:80
	ds_read_b64 v[182:183], v156 offset:208
	ds_read_b64 v[128:129], v156 offset:88
	ds_read_b64 v[180:181], v156 offset:216
	s_waitcnt lgkmcnt(14)
; #define LAS __attribute__((address_space(3)))
; __device__ __forceinline__ f32x2 cmul(f32x2 a, f32x2 b) { return (f32x2){a.x * b.x - a.y * b.y, a.x * b.y + a.y * b.x}; }
; template <bool INV> __device__ __forceinline__ f32x2 cmul_tw(f32x2 a, f32x2 w) { return INV ? cmulc(a, w) : cmul(a, w); }
; template <bool INV> __device__ __forceinline__ void dft16(f32x2 (&x)[16]) {
;     constexpr float C1 = 0.92387953251128674f, S1 = 0.38268343236508977f, C2 = 0.70710678118654752f;
; #pragma unroll
;     for (int b = 0; b < 4; ++b) dft4<INV>(x[b], x[4 + b], x[8 + b], x[12 + b]);
;     const f32x2 w1 = {C1, -S1}, w2 = {C2, -C2}, w3 = {S1, -C1}, w4 = {0.f, -1.f}, w6 = {-C2, -C2}, w9 = {-C1, S1};
;     x[4 * 1 + 1] = cmul_tw<INV>(x[5], w1); x[4 * 1 + 2] = cmul_tw<INV>(x[6], w2); x[4 * 1 + 3] = cmul_tw<INV>(x[7], w3);
;     x[4 * 2 + 1] = cmul_tw<INV>(x[9], w2); x[4 * 2 + 2] = cmul_tw<INV>(x[10], w4); x[4 * 2 + 3] = cmul_tw<INV>(x[11], w6);
;     x[4 * 3 + 1] = cmul_tw<INV>(x[13], w3); x[4 * 3 + 2] = cmul_tw<INV>(x[14], w6); x[4 * 3 + 3] = cmul_tw<INV>(x[15], w9);
; #pragma unroll
;     for (int c = 0; c < 4; ++c) dft4<INV>(x[4 * c], x[4 * c + 1], x[4 * c + 2], x[4 * c + 3]);
;     f32x2 y[16];
; #pragma unroll
;     for (int k = 0; k < 16; ++k) y[k] = x[4 * (k & 3) + (k >> 2)];
; #pragma unroll
;     for (int k = 0; k < 16; ++k) x[k] = y[k];
; }
; template <int MODE> __device__ __forceinline__ void fft_pair32(LAS f32x2* B, const LAS f32x2* F, int wave, int lane) {
;     ...
;     const int hi = lane >> 5, blk = 32 * wave + (lane & 31); const float sg = hi ? -1.f : 1.f;
;     LAS f32x2* p = B + 33 * blk; f32x2 v[16];
; #pragma unroll
;     for (int j = 0; j < 16; ++j) { const f32x2 d = p[j] + p[j + 16] * sg;
;         const f32x2 w = {hi ? CS[j] : 1.f, hi ? -SN[j] : 0.f}; v[j] = j == 0 ? d : cmul(d, w); }
;     dft16<false>(v);
	v_pk_fma_f32 v[166:167], v[126:127], v[190:191], v[166:167] op_sel_hi:[1,0,1]
	v_pk_mul_f32 v[174:175], v[166:167], v[42:43] op_sel:[1,1] op_sel_hi:[0,1]
	v_pk_fma_f32 v[166:167], v[166:167], v[42:43], v[174:175] op_sel_hi:[1,0,1] neg_lo:[0,0,1]
	s_waitcnt lgkmcnt(12)
	v_pk_fma_f32 v[188:189], v[118:119], v[190:191], v[188:189] op_sel_hi:[1,0,1]
	v_pk_mul_f32 v[184:185], v[188:189], v[44:45] op_sel:[1,1] op_sel_hi:[0,1]
	v_pk_fma_f32 v[188:189], v[188:189], v[44:45], v[184:185] op_sel_hi:[1,0,1] neg_lo:[0,0,1]
	s_waitcnt lgkmcnt(10)
	v_pk_fma_f32 v[168:169], v[178:179], v[190:191], v[168:169] op_sel_hi:[1,0,1]
	v_pk_mul_f32 v[174:175], v[168:169], v[46:47] op_sel:[1,1] op_sel_hi:[0,1]
	v_pk_fma_f32 v[168:169], v[168:169], v[46:47], v[174:175] op_sel_hi:[1,0,1] neg_lo:[0,0,1]
	s_waitcnt lgkmcnt(8)
	v_pk_fma_f32 v[186:187], v[110:111], v[190:191], v[186:187] op_sel_hi:[1,0,1]
	v_pk_mul_f32 v[184:185], v[186:187], v[48:49] op_sel:[1,1] op_sel_hi:[0,1]
	v_pk_fma_f32 v[186:187], v[186:187], v[48:49], v[184:185] op_sel_hi:[1,0,1] neg_lo:[0,0,1]
	ds_read_b64 v[106:107], v156 offset:96
	ds_read_b64 v[174:175], v156 offset:224
	ds_read_b64 v[114:115], v156 offset:104
	ds_read_b64 v[184:185], v156 offset:232
	ds_read_b64 v[122:123], v156 offset:112
	ds_read_b64 v[126:127], v156 offset:240
	ds_read_b64 v[130:131], v156 offset:120
	ds_read_b64 v[118:119], v156 offset:248
	s_waitcnt lgkmcnt(14)
	v_pk_fma_f32 v[104:105], v[176:177], v[190:191], v[104:105] op_sel_hi:[1,0,1]
	v_pk_mul_f32 v[178:179], v[104:105], v[50:51] op_sel:[1,1] op_sel_hi:[0,1]
	v_pk_fma_f32 v[104:105], v[104:105], v[50:51], v[178:179] op_sel_hi:[1,0,1] neg_lo:[0,0,1]
	s_waitcnt lgkmcnt(12)
	v_pk_fma_f32 v[112:113], v[102:103], v[190:191], v[112:113] op_sel_hi:[1,0,1]
	v_pk_mul_f32 v[110:111], v[112:113], v[52:53] op_sel:[1,1] op_sel_hi:[0,1]
	v_pk_fma_f32 v[112:113], v[112:113], v[52:53], v[110:111] op_sel_hi:[1,0,1] neg_lo:[0,0,1]
	s_waitcnt lgkmcnt(10)
	v_pk_fma_f32 v[120:121], v[182:183], v[190:191], v[120:121] op_sel_hi:[1,0,1]
	v_pk_mul_f32 v[178:179], v[120:121], v[54:55] op_sel:[1,1] op_sel_hi:[0,1]
	v_pk_fma_f32 v[120:121], v[120:121], v[54:55], v[178:179] op_sel_hi:[1,0,1] neg_lo:[0,0,1]
	s_waitcnt lgkmcnt(8)
	v_pk_fma_f32 v[128:129], v[180:181], v[190:191], v[128:129] op_sel_hi:[1,0,1]
	v_pk_mul_f32 v[110:111], v[128:129], v[90:91] op_sel:[1,1] op_sel_hi:[0,1]
	v_pk_fma_f32 v[128:129], v[128:129], v[90:91], v[110:111] op_sel_hi:[1,0,1] neg_lo:[0,0,1]
	s_waitcnt lgkmcnt(6)
	v_pk_fma_f32 v[106:107], v[174:175], v[190:191], v[106:107] op_sel_hi:[1,0,1]
	v_pk_mul_f32 v[178:179], v[106:107], v[92:93] op_sel:[1,1] op_sel_hi:[0,1]
	v_pk_fma_f32 v[106:107], v[106:107], v[92:93], v[178:179] op_sel_hi:[1,0,1] neg_lo:[0,0,1]
	s_waitcnt lgkmcnt(4)
	v_pk_fma_f32 v[114:115], v[184:185], v[190:191], v[114:115] op_sel_hi:[1,0,1]
	v_pk_mul_f32 v[110:111], v[114:115], v[94:95] op_sel:[1,1] op_sel_hi:[0,1]
	v_pk_fma_f32 v[114:115], v[114:115], v[94:95], v[110:111] op_sel_hi:[1,0,1] neg_lo:[0,0,1]
	s_waitcnt lgkmcnt(2)
	v_pk_fma_f32 v[122:123], v[126:127], v[190:191], v[122:123] op_sel_hi:[1,0,1]
	v_pk_mul_f32 v[176:177], v[122:123], v[96:97] op_sel:[1,1] op_sel_hi:[0,1]
	v_pk_fma_f32 v[122:123], v[122:123], v[96:97], v[176:177] op_sel_hi:[1,0,1] neg_lo:[0,0,1]
	s_waitcnt lgkmcnt(0)
	v_pk_fma_f32 v[130:131], v[118:119], v[190:191], v[130:131] op_sel_hi:[1,0,1]
	v_pk_mul_f32 v[102:103], v[130:131], v[98:99] op_sel:[1,1] op_sel_hi:[0,1]
	v_pk_fma_f32 v[130:131], v[130:131], v[98:99], v[102:103] op_sel_hi:[1,0,1] neg_lo:[0,0,1]
	v_pk_add_f32 v[182:183], v[100:101], v[104:105]
	v_pk_add_f32 v[180:181], v[100:101], v[104:105] neg_lo:[0,1] neg_hi:[0,1]
	v_pk_add_f32 v[178:179], v[166:167], v[106:107]
	v_pk_add_f32 v[110:111], v[166:167], v[106:107] neg_lo:[0,1] neg_hi:[0,1]
	v_pk_add_f32 v[100:101], v[182:183], v[178:179]
	v_pk_add_f32 v[104:105], v[182:183], v[178:179] neg_lo:[0,1] neg_hi:[0,1]
	v_pk_add_f32 v[166:167], v[180:181], v[110:111] op_sel:[0,1] op_sel_hi:[1,0] neg_hi:[0,1]
	v_pk_add_f32 v[106:107], v[180:181], v[110:111] op_sel:[0,1] op_sel_hi:[1,0] neg_lo:[0,1]
	v_pk_add_f32 v[176:177], v[108:109], v[112:113]
	v_pk_add_f32 v[102:103], v[108:109], v[112:113] neg_lo:[0,1] neg_hi:[0,1]
	v_pk_add_f32 v[174:175], v[188:189], v[114:115]
	v_pk_add_f32 v[184:185], v[188:189], v[114:115] neg_lo:[0,1] neg_hi:[0,1]
	v_pk_add_f32 v[108:109], v[176:177], v[174:175]
	v_pk_add_f32 v[112:113], v[176:177], v[174:175] neg_lo:[0,1] neg_hi:[0,1]
	v_pk_add_f32 v[188:189], v[102:103], v[184:185] op_sel:[0,1] op_sel_hi:[1,0] neg_hi:[0,1]
	v_pk_add_f32 v[114:115], v[102:103], v[184:185] op_sel:[0,1] op_sel_hi:[1,0] neg_lo:[0,1]
	v_pk_add_f32 v[126:127], v[116:117], v[120:121]
	v_pk_add_f32 v[118:119], v[116:117], v[120:121] neg_lo:[0,1] neg_hi:[0,1]
	v_pk_add_f32 v[182:183], v[168:169], v[122:123]
	v_pk_add_f32 v[180:181], v[168:169], v[122:123] neg_lo:[0,1] neg_hi:[0,1]
	v_pk_add_f32 v[116:117], v[126:127], v[182:183]
	v_pk_add_f32 v[120:121], v[126:127], v[182:183] neg_lo:[0,1] neg_hi:[0,1]
	v_pk_add_f32 v[168:169], v[118:119], v[180:181] op_sel:[0,1] op_sel_hi:[1,0] neg_hi:[0,1]
	v_pk_add_f32 v[122:123], v[118:119], v[180:181] op_sel:[0,1] op_sel_hi:[1,0] neg_lo:[0,1]
	v_pk_add_f32 v[178:179], v[124:125], v[128:129]
	v_pk_add_f32 v[110:111], v[124:125], v[128:129] neg_lo:[0,1] neg_hi:[0,1]
	v_pk_add_f32 v[176:177], v[186:187], v[130:131]
	v_pk_add_f32 v[102:103], v[186:187], v[130:131] neg_lo:[0,1] neg_hi:[0,1]
	v_pk_add_f32 v[124:125], v[178:179], v[176:177]
	v_pk_add_f32 v[128:129], v[178:179], v[176:177] neg_lo:[0,1] neg_hi:[0,1]
	v_pk_add_f32 v[186:187], v[110:111], v[102:103] op_sel:[0,1] op_sel_hi:[1,0] neg_hi:[0,1]
; #define LAS __attribute__((address_space(3)))
; __device__ __forceinline__ f32x2 cmul(f32x2 a, f32x2 b) { return (f32x2){a.x * b.x - a.y * b.y, a.x * b.y + a.y * b.x}; }
; template <bool INV> __device__ __forceinline__ f32x2 cmul_tw(f32x2 a, f32x2 w) { return INV ? cmulc(a, w) : cmul(a, w); }
; template <bool INV> __device__ __forceinline__ void dft16(f32x2 (&x)[16]) {
;     constexpr float C1 = 0.92387953251128674f, S1 = 0.38268343236508977f, C2 = 0.70710678118654752f;
; #pragma unroll
;     for (int b = 0; b < 4; ++b) dft4<INV>(x[b], x[4 + b], x[8 + b], x[12 + b]);
;     const f32x2 w1 = {C1, -S1}, w2 = {C2, -C2}, w3 = {S1, -C1}, w4 = {0.f, -1.f}, w6 = {-C2, -C2}, w9 = {-C1, S1};
;     x[4 * 1 + 1] = cmul_tw<INV>(x[5], w1); x[4 * 1 + 2] = cmul_tw<INV>(x[6], w2); x[4 * 1 + 3] = cmul_tw<INV>(x[7], w3);
;     x[4 * 2 + 1] = cmul_tw<INV>(x[9], w2); x[4 * 2 + 2] = cmul_tw<INV>(x[10], w4); x[4 * 2 + 3] = cmul_tw<INV>(x[11], w6);
;     x[4 * 3 + 1] = cmul_tw<INV>(x[13], w3); x[4 * 3 + 2] = cmul_tw<INV>(x[14], w6); x[4 * 3 + 3] = cmul_tw<INV>(x[15], w9);
; #pragma unroll
;     for (int c = 0; c < 4; ++c) dft4<INV>(x[4 * c], x[4 * c + 1], x[4 * c + 2], x[4 * c + 3]);
;     f32x2 y[16];
; #pragma unroll
;     for (int k = 0; k < 16; ++k) y[k] = x[4 * (k & 3) + (k >> 2)];
; #pragma unroll
;     for (int k = 0; k < 16; ++k) x[k] = y[k];
; }
; template <int MODE> __device__ __forceinline__ void fft_pair32(LAS f32x2* B, const LAS f32x2* F, int wave, int lane) {
;     ...
;     const int k1 = blk >> 4, k2 = blk & 15, kb1 = (16 - k1) & 15, b1 = k1 != 0 ? 1 : 0, kb2 = (16 - k2 - b1) & 15, b2 = (k2 != 0 || b1) ? 1 : 0;
;     const LAS f32x2* fa = F + 33 * blk; const LAS f32x2* fb = F + 33 * (16 * kb1 + kb2);
;     const LAS f32x2* fah = fa + hi; const LAS f32x2* fbh = fb + (1 - b2) - hi;
;     constexpr float SC = 1.0f / (2.0f * (float)FN);
; #pragma unroll
;     for (int k = 0; k < 16; ++k) { const f32x2 A = fah[2 * k]; f32x2 Bm = fbh[31 - 2 * k];
;         if (k == 0) { const f32x2 m0 = b2 ? fb[31] : fa[0]; Bm = hi ? Bm : m0; }
;         const f32x2 H = MODE == 0 ? (f32x2){(A.x + Bm.x) * SC, (A.y - Bm.y) * SC} : (f32x2){(A.y + Bm.y) * SC, (Bm.x - A.x) * SC};
;         v[k] = cmul(v[k], H); }
	v_pk_add_f32 v[130:131], v[110:111], v[102:103] op_sel:[0,1] op_sel_hi:[1,0] neg_lo:[0,1]
	v_pk_mul_f32 v[174:175], v[188:189], s[68:69] op_sel:[1,1] op_sel_hi:[0,1]
	v_pk_fma_f32 v[188:189], v[188:189], s[68:69], v[174:175] op_sel_hi:[1,0,1] neg_lo:[0,0,1]
	v_pk_mul_f32 v[184:185], v[168:169], s[84:85] op_sel:[1,1] op_sel_hi:[0,1]
	v_pk_fma_f32 v[168:169], v[168:169], s[84:85], v[184:185] op_sel_hi:[1,0,1] neg_lo:[0,0,1]
	v_pk_mul_f32 v[126:127], v[186:187], s[88:89] op_sel:[1,1] op_sel_hi:[0,1]
	v_pk_fma_f32 v[186:187], v[186:187], s[88:89], v[126:127] op_sel_hi:[1,0,1] neg_lo:[0,0,1]
	v_pk_mul_f32 v[118:119], v[112:113], s[84:85] op_sel:[1,1] op_sel_hi:[0,1]
	v_pk_fma_f32 v[112:113], v[112:113], s[84:85], v[118:119] op_sel_hi:[1,0,1] neg_lo:[0,0,1]
	v_pk_mul_f32 v[182:183], v[128:129], s[90:91] op_sel:[1,1] op_sel_hi:[0,1]
	v_pk_fma_f32 v[128:129], v[128:129], s[90:91], v[182:183] op_sel_hi:[1,0,1] neg_lo:[0,0,1]
	v_pk_mul_f32 v[180:181], v[114:115], s[88:89] op_sel:[1,1] op_sel_hi:[0,1]
	v_pk_fma_f32 v[114:115], v[114:115], s[88:89], v[180:181] op_sel_hi:[1,0,1] neg_lo:[0,0,1]
	v_pk_mul_f32 v[178:179], v[122:123], s[90:91] op_sel:[1,1] op_sel_hi:[0,1]
	v_pk_fma_f32 v[122:123], v[122:123], s[90:91], v[178:179] op_sel_hi:[1,0,1] neg_lo:[0,0,1]
	v_pk_mul_f32 v[110:111], v[130:131], s[98:99] op_sel:[1,1] op_sel_hi:[0,1]
	v_pk_fma_f32 v[130:131], v[130:131], s[98:99], v[110:111] op_sel_hi:[1,0,1] neg_lo:[0,0,1]
	v_pk_add_f32 v[176:177], v[100:101], v[116:117]
	v_pk_add_f32 v[102:103], v[100:101], v[116:117] neg_lo:[0,1] neg_hi:[0,1]
	v_pk_add_f32 v[174:175], v[108:109], v[124:125]
	v_pk_add_f32 v[184:185], v[108:109], v[124:125] neg_lo:[0,1] neg_hi:[0,1]
	v_pk_add_f32 v[100:101], v[176:177], v[174:175]
	v_pk_add_f32 v[116:117], v[176:177], v[174:175] neg_lo:[0,1] neg_hi:[0,1]
	v_pk_add_f32 v[108:109], v[102:103], v[184:185] op_sel:[0,1] op_sel_hi:[1,0] neg_hi:[0,1]
	v_pk_add_f32 v[124:125], v[102:103], v[184:185] op_sel:[0,1] op_sel_hi:[1,0] neg_lo:[0,1]
	v_pk_add_f32 v[126:127], v[166:167], v[168:169]
	v_pk_add_f32 v[118:119], v[166:167], v[168:169] neg_lo:[0,1] neg_hi:[0,1]
	v_pk_add_f32 v[182:183], v[188:189], v[186:187]
	v_pk_add_f32 v[180:181], v[188:189], v[186:187] neg_lo:[0,1] neg_hi:[0,1]
	v_pk_add_f32 v[166:167], v[126:127], v[182:183]
	v_pk_add_f32 v[168:169], v[126:127], v[182:183] neg_lo:[0,1] neg_hi:[0,1]
	v_pk_add_f32 v[188:189], v[118:119], v[180:181] op_sel:[0,1] op_sel_hi:[1,0] neg_hi:[0,1]
	v_pk_add_f32 v[186:187], v[118:119], v[180:181] op_sel:[0,1] op_sel_hi:[1,0] neg_lo:[0,1]
	v_pk_add_f32 v[178:179], v[104:105], v[120:121] op_sel:[0,1] op_sel_hi:[1,0] neg_hi:[0,1]
	v_pk_add_f32 v[110:111], v[104:105], v[120:121] op_sel:[0,1] op_sel_hi:[1,0] neg_lo:[0,1]
	v_pk_add_f32 v[176:177], v[112:113], v[128:129]
	v_pk_add_f32 v[102:103], v[112:113], v[128:129] neg_lo:[0,1] neg_hi:[0,1]
	v_pk_add_f32 v[104:105], v[178:179], v[176:177]
	v_pk_add_f32 v[120:121], v[178:179], v[176:177] neg_lo:[0,1] neg_hi:[0,1]
	v_pk_add_f32 v[112:113], v[110:111], v[102:103] op_sel:[0,1] op_sel_hi:[1,0] neg_hi:[0,1]
	v_pk_add_f32 v[128:129], v[110:111], v[102:103] op_sel:[0,1] op_sel_hi:[1,0] neg_lo:[0,1]
	v_pk_add_f32 v[174:175], v[106:107], v[122:123]
	v_pk_add_f32 v[184:185], v[106:107], v[122:123] neg_lo:[0,1] neg_hi:[0,1]
	v_pk_add_f32 v[126:127], v[114:115], v[130:131]
	v_pk_add_f32 v[118:119], v[114:115], v[130:131] neg_lo:[0,1] neg_hi:[0,1]
	v_pk_add_f32 v[106:107], v[174:175], v[126:127]
	v_pk_add_f32 v[122:123], v[174:175], v[126:127] neg_lo:[0,1] neg_hi:[0,1]
	v_pk_add_f32 v[114:115], v[184:185], v[118:119] op_sel:[0,1] op_sel_hi:[1,0] neg_hi:[0,1]
	v_pk_add_f32 v[130:131], v[184:185], v[118:119] op_sel:[0,1] op_sel_hi:[1,0] neg_lo:[0,1]
	ds_read_b64 v[182:183], v200
	ds_read_b64 v[178:179], v204
	ds_read_b64 v[180:181], v200 offset:16
	ds_read_b64 v[110:111], v202 offset:232
	ds_read_b64 v[176:177], v200 offset:32
	ds_read_b64 v[174:175], v202 offset:216
	ds_read_b64 v[102:103], v200 offset:48
	ds_read_b64 v[184:185], v202 offset:200
	s_waitcnt lgkmcnt(6)
	v_pk_add_f32 v[182:183], v[182:183], v[178:179] neg_hi:[0,1]
	v_pk_mul_f32 v[126:127], v[100:101], v[182:183] op_sel:[1,1] op_sel_hi:[0,1]
	v_pk_fma_f32 v[100:101], v[100:101], v[182:183], v[126:127] op_sel_hi:[1,0,1] neg_lo:[0,0,1]
	s_waitcnt lgkmcnt(4)
	v_pk_add_f32 v[180:181], v[180:181], v[110:111] neg_hi:[0,1]
	v_pk_mul_f32 v[118:119], v[166:167], v[180:181] op_sel:[1,1] op_sel_hi:[0,1]
	v_pk_fma_f32 v[166:167], v[166:167], v[180:181], v[118:119] op_sel_hi:[1,0,1] neg_lo:[0,0,1]
	ds_read_b64 v[126:127], v200 offset:64
	ds_read_b64 v[182:183], v202 offset:184
	ds_read_b64 v[118:119], v200 offset:80
	ds_read_b64 v[180:181], v202 offset:168
	s_waitcnt lgkmcnt(6)
	v_pk_add_f32 v[176:177], v[176:177], v[174:175] neg_hi:[0,1]
	v_pk_mul_f32 v[178:179], v[104:105], v[176:177] op_sel:[1,1] op_sel_hi:[0,1]
	v_pk_fma_f32 v[104:105], v[104:105], v[176:177], v[178:179] op_sel_hi:[1,0,1] neg_lo:[0,0,1]
	s_waitcnt lgkmcnt(4)
	v_pk_add_f32 v[102:103], v[102:103], v[184:185] neg_hi:[0,1]
	v_pk_mul_f32 v[110:111], v[106:107], v[102:103] op_sel:[1,1] op_sel_hi:[0,1]
	v_pk_fma_f32 v[106:107], v[106:107], v[102:103], v[110:111] op_sel_hi:[1,0,1] neg_lo:[0,0,1]
	ds_read_b64 v[178:179], v200 offset:96
	ds_read_b64 v[176:177], v202 offset:152
	ds_read_b64 v[110:111], v200 offset:112
	ds_read_b64 v[102:103], v202 offset:136
	s_waitcnt lgkmcnt(6)
	v_pk_add_f32 v[126:127], v[126:127], v[182:183] neg_hi:[0,1]
	v_pk_mul_f32 v[174:175], v[108:109], v[126:127] op_sel:[1,1] op_sel_hi:[0,1]
	v_pk_fma_f32 v[108:109], v[108:109], v[126:127], v[174:175] op_sel_hi:[1,0,1] neg_lo:[0,0,1]
	s_waitcnt lgkmcnt(4)
; #define LAS __attribute__((address_space(3)))
; __device__ __forceinline__ f32x2 cmul(f32x2 a, f32x2 b) { return (f32x2){a.x * b.x - a.y * b.y, a.x * b.y + a.y * b.x}; }
; template <bool INV> __device__ __forceinline__ f32x2 cmul_tw(f32x2 a, f32x2 w) { return INV ? cmulc(a, w) : cmul(a, w); }
; template <bool INV> __device__ __forceinline__ void dft16(f32x2 (&x)[16]) {
;     constexpr float C1 = 0.92387953251128674f, S1 = 0.38268343236508977f, C2 = 0.70710678118654752f;
; #pragma unroll
;     for (int b = 0; b < 4; ++b) dft4<INV>(x[b], x[4 + b], x[8 + b], x[12 + b]);
;     const f32x2 w1 = {C1, -S1}, w2 = {C2, -C2}, w3 = {S1, -C1}, w4 = {0.f, -1.f}, w6 = {-C2, -C2}, w9 = {-C1, S1};
;     x[4 * 1 + 1] = cmul_tw<INV>(x[5], w1); x[4 * 1 + 2] = cmul_tw<INV>(x[6], w2); x[4 * 1 + 3] = cmul_tw<INV>(x[7], w3);
;     x[4 * 2 + 1] = cmul_tw<INV>(x[9], w2); x[4 * 2 + 2] = cmul_tw<INV>(x[10], w4); x[4 * 2 + 3] = cmul_tw<INV>(x[11], w6);
;     x[4 * 3 + 1] = cmul_tw<INV>(x[13], w3); x[4 * 3 + 2] = cmul_tw<INV>(x[14], w6); x[4 * 3 + 3] = cmul_tw<INV>(x[15], w9);
; #pragma unroll
;     for (int c = 0; c < 4; ++c) dft4<INV>(x[4 * c], x[4 * c + 1], x[4 * c + 2], x[4 * c + 3]);
; template <int MODE> __device__ __forceinline__ void fft_pair32(LAS f32x2* B, const LAS f32x2* F, int wave, int lane) {
;     ...
;     const int k1 = blk >> 4, k2 = blk & 15, kb1 = (16 - k1) & 15, b1 = k1 != 0 ? 1 : 0, kb2 = (16 - k2 - b1) & 15, b2 = (k2 != 0 || b1) ? 1 : 0;
;     const LAS f32x2* fa = F + 33 * blk; const LAS f32x2* fb = F + 33 * (16 * kb1 + kb2);
;     const LAS f32x2* fah = fa + hi; const LAS f32x2* fbh = fb + (1 - b2) - hi;
;     constexpr float SC = 1.0f / (2.0f * (float)FN);
; #pragma unroll
;     for (int k = 0; k < 16; ++k) { const f32x2 A = fah[2 * k]; f32x2 Bm = fbh[31 - 2 * k];
;         if (k == 0) { const f32x2 m0 = b2 ? fb[31] : fa[0]; Bm = hi ? Bm : m0; }
;         const f32x2 H = MODE == 0 ? (f32x2){(A.x + Bm.x) * SC, (A.y - Bm.y) * SC} : (f32x2){(A.y + Bm.y) * SC, (Bm.x - A.x) * SC};
;         v[k] = cmul(v[k], H); }
;     dft16<true>(v);
	v_pk_add_f32 v[118:119], v[118:119], v[180:181] neg_hi:[0,1]
	v_pk_mul_f32 v[184:185], v[188:189], v[118:119] op_sel:[1,1] op_sel_hi:[0,1]
	v_pk_fma_f32 v[188:189], v[188:189], v[118:119], v[184:185] op_sel_hi:[1,0,1] neg_lo:[0,0,1]
	ds_read_b64 v[174:175], v200 offset:128
	ds_read_b64 v[126:127], v202 offset:120
	ds_read_b64 v[184:185], v200 offset:144
	ds_read_b64 v[118:119], v202 offset:104
	s_waitcnt lgkmcnt(6)
	v_pk_add_f32 v[178:179], v[178:179], v[176:177] neg_hi:[0,1]
	v_pk_mul_f32 v[182:183], v[112:113], v[178:179] op_sel:[1,1] op_sel_hi:[0,1]
	v_pk_fma_f32 v[112:113], v[112:113], v[178:179], v[182:183] op_sel_hi:[1,0,1] neg_lo:[0,0,1]
	s_waitcnt lgkmcnt(4)
	v_pk_add_f32 v[110:111], v[110:111], v[102:103] neg_hi:[0,1]
	v_pk_mul_f32 v[180:181], v[114:115], v[110:111] op_sel:[1,1] op_sel_hi:[0,1]
	v_pk_fma_f32 v[114:115], v[114:115], v[110:111], v[180:181] op_sel_hi:[1,0,1] neg_lo:[0,0,1]
	ds_read_b64 v[182:183], v200 offset:160
	ds_read_b64 v[178:179], v202 offset:88
	ds_read_b64 v[180:181], v200 offset:176
	ds_read_b64 v[110:111], v202 offset:72
	s_waitcnt lgkmcnt(6)
	v_pk_add_f32 v[174:175], v[174:175], v[126:127] neg_hi:[0,1]
	v_pk_mul_f32 v[176:177], v[116:117], v[174:175] op_sel:[1,1] op_sel_hi:[0,1]
	v_pk_fma_f32 v[116:117], v[116:117], v[174:175], v[176:177] op_sel_hi:[1,0,1] neg_lo:[0,0,1]
	s_waitcnt lgkmcnt(4)
	v_pk_add_f32 v[184:185], v[184:185], v[118:119] neg_hi:[0,1]
	v_pk_mul_f32 v[102:103], v[168:169], v[184:185] op_sel:[1,1] op_sel_hi:[0,1]
	v_pk_fma_f32 v[168:169], v[168:169], v[184:185], v[102:103] op_sel_hi:[1,0,1] neg_lo:[0,0,1]
	ds_read_b64 v[176:177], v200 offset:192
	ds_read_b64 v[174:175], v202 offset:56
	ds_read_b64 v[102:103], v200 offset:208
	ds_read_b64 v[184:185], v202 offset:40
	s_waitcnt lgkmcnt(6)
	v_pk_add_f32 v[182:183], v[182:183], v[178:179] neg_hi:[0,1]
	v_pk_mul_f32 v[126:127], v[120:121], v[182:183] op_sel:[1,1] op_sel_hi:[0,1]
	v_pk_fma_f32 v[120:121], v[120:121], v[182:183], v[126:127] op_sel_hi:[1,0,1] neg_lo:[0,0,1]
	s_waitcnt lgkmcnt(4)
	v_pk_add_f32 v[180:181], v[180:181], v[110:111] neg_hi:[0,1]
	v_pk_mul_f32 v[118:119], v[122:123], v[180:181] op_sel:[1,1] op_sel_hi:[0,1]
	v_pk_fma_f32 v[122:123], v[122:123], v[180:181], v[118:119] op_sel_hi:[1,0,1] neg_lo:[0,0,1]
	ds_read_b64 v[126:127], v200 offset:224
	ds_read_b64 v[182:183], v202 offset:24
	ds_read_b64 v[118:119], v200 offset:240
	ds_read_b64 v[180:181], v202 offset:8
	s_waitcnt lgkmcnt(6)
	v_pk_add_f32 v[176:177], v[176:177], v[174:175] neg_hi:[0,1]
	v_pk_mul_f32 v[178:179], v[124:125], v[176:177] op_sel:[1,1] op_sel_hi:[0,1]
	v_pk_fma_f32 v[124:125], v[124:125], v[176:177], v[178:179] op_sel_hi:[1,0,1] neg_lo:[0,0,1]
	s_waitcnt lgkmcnt(4)
	v_pk_add_f32 v[102:103], v[102:103], v[184:185] neg_hi:[0,1]
	v_pk_mul_f32 v[110:111], v[186:187], v[102:103] op_sel:[1,1] op_sel_hi:[0,1]
	v_pk_fma_f32 v[186:187], v[186:187], v[102:103], v[110:111] op_sel_hi:[1,0,1] neg_lo:[0,0,1]
	s_waitcnt lgkmcnt(2)
	v_pk_add_f32 v[126:127], v[126:127], v[182:183] neg_hi:[0,1]
	v_pk_mul_f32 v[178:179], v[128:129], v[126:127] op_sel:[1,1] op_sel_hi:[0,1]
	v_pk_fma_f32 v[128:129], v[128:129], v[126:127], v[178:179] op_sel_hi:[1,0,1] neg_lo:[0,0,1]
	s_waitcnt lgkmcnt(0)
	v_pk_add_f32 v[118:119], v[118:119], v[180:181] neg_hi:[0,1]
	v_pk_mul_f32 v[110:111], v[130:131], v[118:119] op_sel:[1,1] op_sel_hi:[0,1]
	v_pk_fma_f32 v[130:131], v[130:131], v[118:119], v[110:111] op_sel_hi:[1,0,1] neg_lo:[0,0,1]
	v_pk_add_f32 v[176:177], v[100:101], v[116:117]
	v_pk_add_f32 v[102:103], v[100:101], v[116:117] neg_lo:[0,1] neg_hi:[0,1]
	v_pk_add_f32 v[174:175], v[108:109], v[124:125]
	v_pk_add_f32 v[184:185], v[108:109], v[124:125] neg_lo:[0,1] neg_hi:[0,1]
	v_pk_add_f32 v[100:101], v[176:177], v[174:175]
	v_pk_add_f32 v[116:117], v[176:177], v[174:175] neg_lo:[0,1] neg_hi:[0,1]
	v_pk_add_f32 v[108:109], v[102:103], v[184:185] op_sel:[0,1] op_sel_hi:[1,0] neg_lo:[0,1]
	v_pk_add_f32 v[124:125], v[102:103], v[184:185] op_sel:[0,1] op_sel_hi:[1,0] neg_hi:[0,1]
	v_pk_add_f32 v[178:179], v[166:167], v[168:169]
	v_pk_add_f32 v[110:111], v[166:167], v[168:169] neg_lo:[0,1] neg_hi:[0,1]
	v_pk_add_f32 v[126:127], v[188:189], v[186:187]
	v_pk_add_f32 v[118:119], v[188:189], v[186:187] neg_lo:[0,1] neg_hi:[0,1]
	v_pk_add_f32 v[166:167], v[178:179], v[126:127]
	v_pk_add_f32 v[168:169], v[178:179], v[126:127] neg_lo:[0,1] neg_hi:[0,1]
	v_pk_add_f32 v[188:189], v[110:111], v[118:119] op_sel:[0,1] op_sel_hi:[1,0] neg_lo:[0,1]
	v_pk_add_f32 v[186:187], v[110:111], v[118:119] op_sel:[0,1] op_sel_hi:[1,0] neg_hi:[0,1]
	v_pk_add_f32 v[182:183], v[104:105], v[120:121]
	v_pk_add_f32 v[180:181], v[104:105], v[120:121] neg_lo:[0,1] neg_hi:[0,1]
	v_pk_add_f32 v[176:177], v[112:113], v[128:129]
	v_pk_add_f32 v[102:103], v[112:113], v[128:129] neg_lo:[0,1] neg_hi:[0,1]
	v_pk_add_f32 v[104:105], v[182:183], v[176:177]
	v_pk_add_f32 v[120:121], v[182:183], v[176:177] neg_lo:[0,1] neg_hi:[0,1]
	v_pk_add_f32 v[112:113], v[180:181], v[102:103] op_sel:[0,1] op_sel_hi:[1,0] neg_lo:[0,1]
	v_pk_add_f32 v[128:129], v[180:181], v[102:103] op_sel:[0,1] op_sel_hi:[1,0] neg_hi:[0,1]
	v_pk_add_f32 v[174:175], v[106:107], v[122:123]
	v_pk_add_f32 v[184:185], v[106:107], v[122:123] neg_lo:[0,1] neg_hi:[0,1]
	v_pk_add_f32 v[178:179], v[114:115], v[130:131]
	v_pk_add_f32 v[110:111], v[114:115], v[130:131] neg_lo:[0,1] neg_hi:[0,1]
	v_pk_add_f32 v[106:107], v[174:175], v[178:179]
	v_pk_add_f32 v[122:123], v[174:175], v[178:179] neg_lo:[0,1] neg_hi:[0,1]
	v_pk_add_f32 v[114:115], v[184:185], v[110:111] op_sel:[0,1] op_sel_hi:[1,0] neg_lo:[0,1]
	v_pk_add_f32 v[130:131], v[184:185], v[110:111] op_sel:[0,1] op_sel_hi:[1,0] neg_hi:[0,1]
; __device__ __forceinline__ f32x2 cmulc(f32x2 a, f32x2 b) { return (f32x2){a.x * b.x + a.y * b.y, a.y * b.x - a.x * b.y}; }
; template <bool INV> __device__ __forceinline__ f32x2 cmul_tw(f32x2 a, f32x2 w) { return INV ? cmulc(a, w) : cmul(a, w); }
; template <bool INV> __device__ __forceinline__ void dft16(f32x2 (&x)[16]) {
;     constexpr float C1 = 0.92387953251128674f, S1 = 0.38268343236508977f, C2 = 0.70710678118654752f;
; #pragma unroll
;     for (int b = 0; b < 4; ++b) dft4<INV>(x[b], x[4 + b], x[8 + b], x[12 + b]);
;     const f32x2 w1 = {C1, -S1}, w2 = {C2, -C2}, w3 = {S1, -C1}, w4 = {0.f, -1.f}, w6 = {-C2, -C2}, w9 = {-C1, S1};
;     x[4 * 1 + 1] = cmul_tw<INV>(x[5], w1); x[4 * 1 + 2] = cmul_tw<INV>(x[6], w2); x[4 * 1 + 3] = cmul_tw<INV>(x[7], w3);
;     x[4 * 2 + 1] = cmul_tw<INV>(x[9], w2); x[4 * 2 + 2] = cmul_tw<INV>(x[10], w4); x[4 * 2 + 3] = cmul_tw<INV>(x[11], w6);
;     x[4 * 3 + 1] = cmul_tw<INV>(x[13], w3); x[4 * 3 + 2] = cmul_tw<INV>(x[14], w6); x[4 * 3 + 3] = cmul_tw<INV>(x[15], w9);
; #pragma unroll
;     for (int c = 0; c < 4; ++c) dft4<INV>(x[4 * c], x[4 * c + 1], x[4 * c + 2], x[4 * c + 3]);
;     f32x2 y[16];
; #pragma unroll
;     for (int k = 0; k < 16; ++k) y[k] = x[4 * (k & 3) + (k >> 2)];
; #pragma unroll
;     for (int k = 0; k < 16; ++k) x[k] = y[k];
; }
; template <int MODE> __device__ __forceinline__ void fft_pair32(LAS f32x2* B, const LAS f32x2* F, int wave, int lane) {
;     ...
;     dft16<true>(v);
; #pragma unroll
;     for (int j = 0; j < 16; ++j) { const f32x2 w = {hi ? CS[j] : 1.f, hi ? -SN[j] : 0.f}; const f32x2 u = j == 0 ? v[j] : cmulc(v[j], w);
;         const auto rx = __builtin_amdgcn_permlane32_swap(__float_as_uint(u.x), __float_as_uint(u.x), false, false);
;         const auto ry = __builtin_amdgcn_permlane32_swap(__float_as_uint(u.y), __float_as_uint(u.y), false, false);
;         const f32x2 a = {__uint_as_float(rx[0]), __uint_as_float(ry[0])}, b = {__uint_as_float(rx[1]), __uint_as_float(ry[1])};
;         p[16 * hi + j] = a + b * sg; }
	v_pk_mul_f32 v[126:127], v[188:189], s[68:69] op_sel:[1,1] op_sel_hi:[0,1]
	v_pk_fma_f32 v[188:189], v[188:189], s[68:69], v[126:127] op_sel_hi:[1,0,1] neg_hi:[0,0,1]
	v_pk_mul_f32 v[118:119], v[112:113], s[84:85] op_sel:[1,1] op_sel_hi:[0,1]
	v_pk_fma_f32 v[112:113], v[112:113], s[84:85], v[118:119] op_sel_hi:[1,0,1] neg_hi:[0,0,1]
	v_pk_mul_f32 v[182:183], v[114:115], s[88:89] op_sel:[1,1] op_sel_hi:[0,1]
	v_pk_fma_f32 v[114:115], v[114:115], s[88:89], v[182:183] op_sel_hi:[1,0,1] neg_hi:[0,0,1]
	v_pk_mul_f32 v[180:181], v[168:169], s[84:85] op_sel:[1,1] op_sel_hi:[0,1]
	v_pk_fma_f32 v[168:169], v[168:169], s[84:85], v[180:181] op_sel_hi:[1,0,1] neg_hi:[0,0,1]
	v_pk_mul_f32 v[176:177], v[122:123], s[90:91] op_sel:[1,1] op_sel_hi:[0,1]
	v_pk_fma_f32 v[122:123], v[122:123], s[90:91], v[176:177] op_sel_hi:[1,0,1] neg_hi:[0,0,1]
	v_pk_mul_f32 v[102:103], v[186:187], s[88:89] op_sel:[1,1] op_sel_hi:[0,1]
	v_pk_fma_f32 v[186:187], v[186:187], s[88:89], v[102:103] op_sel_hi:[1,0,1] neg_hi:[0,0,1]
	v_pk_mul_f32 v[174:175], v[128:129], s[90:91] op_sel:[1,1] op_sel_hi:[0,1]
	v_pk_fma_f32 v[128:129], v[128:129], s[90:91], v[174:175] op_sel_hi:[1,0,1] neg_hi:[0,0,1]
	v_pk_mul_f32 v[184:185], v[130:131], s[98:99] op_sel:[1,1] op_sel_hi:[0,1]
	v_pk_fma_f32 v[130:131], v[130:131], s[98:99], v[184:185] op_sel_hi:[1,0,1] neg_hi:[0,0,1]
	v_pk_add_f32 v[178:179], v[100:101], v[104:105]
	v_pk_add_f32 v[110:111], v[100:101], v[104:105] neg_lo:[0,1] neg_hi:[0,1]
	v_pk_add_f32 v[126:127], v[166:167], v[106:107]
	v_pk_add_f32 v[118:119], v[166:167], v[106:107] neg_lo:[0,1] neg_hi:[0,1]
	v_pk_add_f32 v[100:101], v[178:179], v[126:127]
	v_pk_add_f32 v[104:105], v[178:179], v[126:127] neg_lo:[0,1] neg_hi:[0,1]
	v_pk_add_f32 v[166:167], v[110:111], v[118:119] op_sel:[0,1] op_sel_hi:[1,0] neg_lo:[0,1]
	v_pk_add_f32 v[106:107], v[110:111], v[118:119] op_sel:[0,1] op_sel_hi:[1,0] neg_hi:[0,1]
	v_pk_add_f32 v[182:183], v[108:109], v[112:113]
	v_pk_add_f32 v[180:181], v[108:109], v[112:113] neg_lo:[0,1] neg_hi:[0,1]
	v_pk_add_f32 v[176:177], v[188:189], v[114:115]
	v_pk_add_f32 v[102:103], v[188:189], v[114:115] neg_lo:[0,1] neg_hi:[0,1]
	v_pk_add_f32 v[108:109], v[182:183], v[176:177]
	v_pk_add_f32 v[112:113], v[182:183], v[176:177] neg_lo:[0,1] neg_hi:[0,1]
	v_pk_add_f32 v[188:189], v[180:181], v[102:103] op_sel:[0,1] op_sel_hi:[1,0] neg_lo:[0,1]
	v_pk_add_f32 v[114:115], v[180:181], v[102:103] op_sel:[0,1] op_sel_hi:[1,0] neg_hi:[0,1]
	v_pk_add_f32 v[174:175], v[116:117], v[120:121] op_sel:[0,1] op_sel_hi:[1,0] neg_lo:[0,1]
	v_pk_add_f32 v[184:185], v[116:117], v[120:121] op_sel:[0,1] op_sel_hi:[1,0] neg_hi:[0,1]
	v_pk_add_f32 v[178:179], v[168:169], v[122:123]
	v_pk_add_f32 v[110:111], v[168:169], v[122:123] neg_lo:[0,1] neg_hi:[0,1]
	v_pk_add_f32 v[116:117], v[174:175], v[178:179]
	v_pk_add_f32 v[120:121], v[174:175], v[178:179] neg_lo:[0,1] neg_hi:[0,1]
	v_pk_add_f32 v[168:169], v[184:185], v[110:111] op_sel:[0,1] op_sel_hi:[1,0] neg_lo:[0,1]
	v_pk_add_f32 v[122:123], v[184:185], v[110:111] op_sel:[0,1] op_sel_hi:[1,0] neg_hi:[0,1]
	v_pk_add_f32 v[126:127], v[124:125], v[128:129]
	v_pk_add_f32 v[118:119], v[124:125], v[128:129] neg_lo:[0,1] neg_hi:[0,1]
	v_pk_add_f32 v[182:183], v[186:187], v[130:131]
	v_pk_add_f32 v[180:181], v[186:187], v[130:131] neg_lo:[0,1] neg_hi:[0,1]
	v_pk_add_f32 v[124:125], v[126:127], v[182:183]
	v_pk_add_f32 v[128:129], v[126:127], v[182:183] neg_lo:[0,1] neg_hi:[0,1]
	v_pk_add_f32 v[186:187], v[118:119], v[180:181] op_sel:[0,1] op_sel_hi:[1,0] neg_lo:[0,1]
	v_pk_add_f32 v[130:131], v[118:119], v[180:181] op_sel:[0,1] op_sel_hi:[1,0] neg_hi:[0,1]
	v_mov_b32_e32 v176, v100
	v_mov_b32_e32 v177, v101
	v_pk_mul_f32 v[178:179], v[108:109], v[36:37] op_sel:[1,1] op_sel_hi:[0,1]
	v_pk_fma_f32 v[102:103], v[108:109], v[36:37], v[178:179] op_sel_hi:[1,0,1] neg_hi:[0,0,1]
	v_pk_fma_f32 v[108:109], v[108:109], v[36:37], v[178:179] op_sel_hi:[1,0,1] neg_hi:[0,0,1]
	v_pk_mul_f32 v[110:111], v[116:117], v[38:39] op_sel:[1,1] op_sel_hi:[0,1]
	v_pk_fma_f32 v[174:175], v[116:117], v[38:39], v[110:111] op_sel_hi:[1,0,1] neg_hi:[0,0,1]
	v_pk_fma_f32 v[116:117], v[116:117], v[38:39], v[110:111] op_sel_hi:[1,0,1] neg_hi:[0,0,1]
	v_pk_mul_f32 v[126:127], v[124:125], v[40:41] op_sel:[1,1] op_sel_hi:[0,1]
	v_pk_fma_f32 v[184:185], v[124:125], v[40:41], v[126:127] op_sel_hi:[1,0,1] neg_hi:[0,0,1]
	v_pk_fma_f32 v[124:125], v[124:125], v[40:41], v[126:127] op_sel_hi:[1,0,1] neg_hi:[0,0,1]
	s_nop 1
	v_permlane32_swap_b32_e32 v100, v176
	v_permlane32_swap_b32_e32 v101, v177
	v_permlane32_swap_b32_e32 v108, v102
	v_permlane32_swap_b32_e32 v109, v103
	v_permlane32_swap_b32_e32 v116, v174
	v_permlane32_swap_b32_e32 v117, v175
	v_permlane32_swap_b32_e32 v124, v184
	v_permlane32_swap_b32_e32 v125, v185
	v_pk_fma_f32 v[100:101], v[176:177], v[190:191], v[100:101] op_sel_hi:[1,0,1]
	ds_write_b64 v198, v[100:101]
	v_pk_fma_f32 v[108:109], v[102:103], v[190:191], v[108:109] op_sel_hi:[1,0,1]
	ds_write_b64 v198, v[108:109] offset:8
	v_pk_fma_f32 v[116:117], v[174:175], v[190:191], v[116:117] op_sel_hi:[1,0,1]
	ds_write_b64 v198, v[116:117] offset:16
	v_pk_fma_f32 v[124:125], v[184:185], v[190:191], v[124:125] op_sel_hi:[1,0,1]
	ds_write_b64 v198, v[124:125] offset:24
	v_pk_mul_f32 v[110:111], v[166:167], v[42:43] op_sel:[1,1] op_sel_hi:[0,1]
	v_pk_fma_f32 v[118:119], v[166:167], v[42:43], v[110:111] op_sel_hi:[1,0,1] neg_hi:[0,0,1]
	v_pk_fma_f32 v[166:167], v[166:167], v[42:43], v[110:111] op_sel_hi:[1,0,1] neg_hi:[0,0,1]
	v_pk_mul_f32 v[126:127], v[188:189], v[44:45] op_sel:[1,1] op_sel_hi:[0,1]
	v_pk_fma_f32 v[182:183], v[188:189], v[44:45], v[126:127] op_sel_hi:[1,0,1] neg_hi:[0,0,1]
; #define LAS __attribute__((address_space(3)))
; __device__ __forceinline__ f32x2 cmulc(f32x2 a, f32x2 b) { return (f32x2){a.x * b.x + a.y * b.y, a.y * b.x - a.x * b.y}; }
; __device__ __forceinline__ void fft_inv2(LAS f32x2* B, const LAS f32x2* TW2, int tid) {
;     asm volatile("" : "+v"(tid));
;     const int b = tid >> 5, n2 = tid & 31, base = 512 * b + n2; f32x2 x[16];
;     x[0] = B[fpad(base)];
; #pragma unroll
;     for (int k = 1; k < 16; ++k) x[k] = cmulc(B[fpad(base + 32 * k)], TW2[k * 32 + n2]);
;     dft16<true>(x);
; #pragma unroll
;     for (int r = 0; r < 16; ++r) B[fpad(base + 32 * r)] = x[r];
; }
; template <int MODE> __device__ __forceinline__ void fft_pair32(LAS f32x2* B, const LAS f32x2* F, int wave, int lane) {
;     ...
; #pragma unroll
;     for (int j = 0; j < 16; ++j) { const f32x2 w = {hi ? CS[j] : 1.f, hi ? -SN[j] : 0.f}; const f32x2 u = j == 0 ? v[j] : cmulc(v[j], w);
;         const auto rx = __builtin_amdgcn_permlane32_swap(__float_as_uint(u.x), __float_as_uint(u.x), false, false);
;         const auto ry = __builtin_amdgcn_permlane32_swap(__float_as_uint(u.y), __float_as_uint(u.y), false, false);
;         const f32x2 a = {__uint_as_float(rx[0]), __uint_as_float(ry[0])}, b = {__uint_as_float(rx[1]), __uint_as_float(ry[1])};
;         p[16 * hi + j] = a + b * sg; }
	v_pk_fma_f32 v[188:189], v[188:189], v[44:45], v[126:127] op_sel_hi:[1,0,1] neg_hi:[0,0,1]
	v_pk_mul_f32 v[176:177], v[168:169], v[46:47] op_sel:[1,1] op_sel_hi:[0,1]
	v_pk_fma_f32 v[180:181], v[168:169], v[46:47], v[176:177] op_sel_hi:[1,0,1] neg_hi:[0,0,1]
	v_pk_fma_f32 v[168:169], v[168:169], v[46:47], v[176:177] op_sel_hi:[1,0,1] neg_hi:[0,0,1]
	v_pk_mul_f32 v[102:103], v[186:187], v[48:49] op_sel:[1,1] op_sel_hi:[0,1]
	v_pk_fma_f32 v[178:179], v[186:187], v[48:49], v[102:103] op_sel_hi:[1,0,1] neg_hi:[0,0,1]
	v_pk_fma_f32 v[186:187], v[186:187], v[48:49], v[102:103] op_sel_hi:[1,0,1] neg_hi:[0,0,1]
	s_nop 1
	v_permlane32_swap_b32_e32 v166, v118
	v_permlane32_swap_b32_e32 v167, v119
	v_permlane32_swap_b32_e32 v188, v182
	v_permlane32_swap_b32_e32 v189, v183
	v_permlane32_swap_b32_e32 v168, v180
	v_permlane32_swap_b32_e32 v169, v181
	v_permlane32_swap_b32_e32 v186, v178
	v_permlane32_swap_b32_e32 v187, v179
	v_pk_fma_f32 v[166:167], v[118:119], v[190:191], v[166:167] op_sel_hi:[1,0,1]
	ds_write_b64 v198, v[166:167] offset:32
	v_pk_fma_f32 v[188:189], v[182:183], v[190:191], v[188:189] op_sel_hi:[1,0,1]
	ds_write_b64 v198, v[188:189] offset:40
	v_pk_fma_f32 v[168:169], v[180:181], v[190:191], v[168:169] op_sel_hi:[1,0,1]
	ds_write_b64 v198, v[168:169] offset:48
	v_pk_fma_f32 v[186:187], v[178:179], v[190:191], v[186:187] op_sel_hi:[1,0,1]
	ds_write_b64 v198, v[186:187] offset:56
	v_pk_mul_f32 v[176:177], v[104:105], v[50:51] op_sel:[1,1] op_sel_hi:[0,1]
	v_pk_fma_f32 v[174:175], v[104:105], v[50:51], v[176:177] op_sel_hi:[1,0,1] neg_hi:[0,0,1]
	v_pk_fma_f32 v[104:105], v[104:105], v[50:51], v[176:177] op_sel_hi:[1,0,1] neg_hi:[0,0,1]
	v_pk_mul_f32 v[102:103], v[112:113], v[52:53] op_sel:[1,1] op_sel_hi:[0,1]
	v_pk_fma_f32 v[184:185], v[112:113], v[52:53], v[102:103] op_sel_hi:[1,0,1] neg_hi:[0,0,1]
	v_pk_fma_f32 v[112:113], v[112:113], v[52:53], v[102:103] op_sel_hi:[1,0,1] neg_hi:[0,0,1]
	v_pk_mul_f32 v[118:119], v[120:121], v[54:55] op_sel:[1,1] op_sel_hi:[0,1]
	v_pk_fma_f32 v[110:111], v[120:121], v[54:55], v[118:119] op_sel_hi:[1,0,1] neg_hi:[0,0,1]
	v_pk_fma_f32 v[120:121], v[120:121], v[54:55], v[118:119] op_sel_hi:[1,0,1] neg_hi:[0,0,1]
	v_pk_mul_f32 v[182:183], v[128:129], v[90:91] op_sel:[1,1] op_sel_hi:[0,1]
	v_pk_fma_f32 v[126:127], v[128:129], v[90:91], v[182:183] op_sel_hi:[1,0,1] neg_hi:[0,0,1]
	v_pk_fma_f32 v[128:129], v[128:129], v[90:91], v[182:183] op_sel_hi:[1,0,1] neg_hi:[0,0,1]
	s_nop 1
	v_permlane32_swap_b32_e32 v104, v174
	v_permlane32_swap_b32_e32 v105, v175
	v_permlane32_swap_b32_e32 v112, v184
	v_permlane32_swap_b32_e32 v113, v185
	v_permlane32_swap_b32_e32 v120, v110
	v_permlane32_swap_b32_e32 v121, v111
	v_permlane32_swap_b32_e32 v128, v126
	v_permlane32_swap_b32_e32 v129, v127
	v_pk_fma_f32 v[104:105], v[174:175], v[190:191], v[104:105] op_sel_hi:[1,0,1]
	ds_write_b64 v198, v[104:105] offset:64
	v_pk_fma_f32 v[112:113], v[184:185], v[190:191], v[112:113] op_sel_hi:[1,0,1]
	ds_write_b64 v198, v[112:113] offset:72
	v_pk_fma_f32 v[120:121], v[110:111], v[190:191], v[120:121] op_sel_hi:[1,0,1]
	ds_write_b64 v198, v[120:121] offset:80
	v_pk_fma_f32 v[128:129], v[126:127], v[190:191], v[128:129] op_sel_hi:[1,0,1]
	ds_write_b64 v198, v[128:129] offset:88
	v_pk_mul_f32 v[118:119], v[106:107], v[92:93] op_sel:[1,1] op_sel_hi:[0,1]
	v_pk_fma_f32 v[180:181], v[106:107], v[92:93], v[118:119] op_sel_hi:[1,0,1] neg_hi:[0,0,1]
	v_pk_fma_f32 v[106:107], v[106:107], v[92:93], v[118:119] op_sel_hi:[1,0,1] neg_hi:[0,0,1]
	v_pk_mul_f32 v[182:183], v[114:115], v[94:95] op_sel:[1,1] op_sel_hi:[0,1]
	v_pk_fma_f32 v[178:179], v[114:115], v[94:95], v[182:183] op_sel_hi:[1,0,1] neg_hi:[0,0,1]
	v_pk_fma_f32 v[114:115], v[114:115], v[94:95], v[182:183] op_sel_hi:[1,0,1] neg_hi:[0,0,1]
	v_pk_mul_f32 v[174:175], v[122:123], v[96:97] op_sel:[1,1] op_sel_hi:[0,1]
	v_pk_fma_f32 v[176:177], v[122:123], v[96:97], v[174:175] op_sel_hi:[1,0,1] neg_hi:[0,0,1]
	v_pk_fma_f32 v[122:123], v[122:123], v[96:97], v[174:175] op_sel_hi:[1,0,1] neg_hi:[0,0,1]
	v_pk_mul_f32 v[184:185], v[130:131], v[98:99] op_sel:[1,1] op_sel_hi:[0,1]
	v_pk_fma_f32 v[102:103], v[130:131], v[98:99], v[184:185] op_sel_hi:[1,0,1] neg_hi:[0,0,1]
	v_pk_fma_f32 v[130:131], v[130:131], v[98:99], v[184:185] op_sel_hi:[1,0,1] neg_hi:[0,0,1]
	s_nop 1
	v_permlane32_swap_b32_e32 v106, v180
	v_permlane32_swap_b32_e32 v107, v181
	v_permlane32_swap_b32_e32 v114, v178
	v_permlane32_swap_b32_e32 v115, v179
	v_permlane32_swap_b32_e32 v122, v176
	v_permlane32_swap_b32_e32 v123, v177
	v_permlane32_swap_b32_e32 v130, v102
	v_permlane32_swap_b32_e32 v131, v103
	v_pk_fma_f32 v[106:107], v[180:181], v[190:191], v[106:107] op_sel_hi:[1,0,1]
	ds_write_b64 v198, v[106:107] offset:96
	v_pk_fma_f32 v[114:115], v[178:179], v[190:191], v[114:115] op_sel_hi:[1,0,1]
	ds_write_b64 v198, v[114:115] offset:104
	v_pk_fma_f32 v[122:123], v[176:177], v[190:191], v[122:123] op_sel_hi:[1,0,1]
	ds_write_b64 v198, v[122:123] offset:112
	v_pk_fma_f32 v[130:131], v[102:103], v[190:191], v[130:131] op_sel_hi:[1,0,1]
	ds_write_b64 v198, v[130:131] offset:120
	s_waitcnt lgkmcnt(0)
	ds_read_b64 v[100:101], v5
	ds_read_b64 v[108:109], v5 offset:264
	ds_read_b64 v[110:111], v56 offset:256
	ds_read_b64 v[116:117], v5 offset:528
	ds_read_b64 v[126:127], v56 offset:512
	ds_read_b64 v[124:125], v5 offset:792
	ds_read_b64 v[118:119], v56 offset:768
	ds_read_b64 v[166:167], v5 offset:1056
	ds_read_b64 v[182:183], v56 offset:1024
	ds_read_b64 v[188:189], v5 offset:1320
	ds_read_b64 v[174:175], v56 offset:1280
	ds_read_b64 v[168:169], v5 offset:1584
	ds_read_b64 v[184:185], v56 offset:1536
	ds_read_b64 v[186:187], v5 offset:1848
	ds_read_b64 v[180:181], v56 offset:1792
	ds_read_b64 v[104:105], v5 offset:2112
	ds_read_b64 v[178:179], v56 offset:2048
	s_waitcnt lgkmcnt(14)
; #define LAS __attribute__((address_space(3)))
; __device__ __forceinline__ f32x2 cmulc(f32x2 a, f32x2 b) { return (f32x2){a.x * b.x + a.y * b.y, a.y * b.x - a.x * b.y}; }
; template <bool INV> __device__ __forceinline__ f32x2 cmul_tw(f32x2 a, f32x2 w) { return INV ? cmulc(a, w) : cmul(a, w); }
; template <bool INV> __device__ __forceinline__ void dft16(f32x2 (&x)[16]) {
;     constexpr float C1 = 0.92387953251128674f, S1 = 0.38268343236508977f, C2 = 0.70710678118654752f;
; #pragma unroll
;     for (int b = 0; b < 4; ++b) dft4<INV>(x[b], x[4 + b], x[8 + b], x[12 + b]);
;     const f32x2 w1 = {C1, -S1}, w2 = {C2, -C2}, w3 = {S1, -C1}, w4 = {0.f, -1.f}, w6 = {-C2, -C2}, w9 = {-C1, S1};
;     x[4 * 1 + 1] = cmul_tw<INV>(x[5], w1); x[4 * 1 + 2] = cmul_tw<INV>(x[6], w2); x[4 * 1 + 3] = cmul_tw<INV>(x[7], w3);
;     x[4 * 2 + 1] = cmul_tw<INV>(x[9], w2); x[4 * 2 + 2] = cmul_tw<INV>(x[10], w4); x[4 * 2 + 3] = cmul_tw<INV>(x[11], w6);
;     x[4 * 3 + 1] = cmul_tw<INV>(x[13], w3); x[4 * 3 + 2] = cmul_tw<INV>(x[14], w6); x[4 * 3 + 3] = cmul_tw<INV>(x[15], w9);
; #pragma unroll
;     for (int c = 0; c < 4; ++c) dft4<INV>(x[4 * c], x[4 * c + 1], x[4 * c + 2], x[4 * c + 3]);
;     f32x2 y[16];
; #pragma unroll
;     for (int k = 0; k < 16; ++k) y[k] = x[4 * (k & 3) + (k >> 2)];
; #pragma unroll
;     for (int k = 0; k < 16; ++k) x[k] = y[k];
; }
; __device__ __forceinline__ void fft_inv2(LAS f32x2* B, const LAS f32x2* TW2, int tid) {
;     asm volatile("" : "+v"(tid));
;     const int b = tid >> 5, n2 = tid & 31, base = 512 * b + n2; f32x2 x[16];
;     x[0] = B[fpad(base)];
; #pragma unroll
;     for (int k = 1; k < 16; ++k) x[k] = cmulc(B[fpad(base + 32 * k)], TW2[k * 32 + n2]);
;     dft16<true>(x);
; #pragma unroll
;     for (int r = 0; r < 16; ++r) B[fpad(base + 32 * r)] = x[r];
; }
	v_pk_mul_f32 v[176:177], v[108:109], v[110:111] op_sel:[1,1] op_sel_hi:[0,1]
	v_pk_fma_f32 v[108:109], v[108:109], v[110:111], v[176:177] op_sel_hi:[1,0,1] neg_hi:[0,0,1]
	s_waitcnt lgkmcnt(12)
	v_pk_mul_f32 v[102:103], v[116:117], v[126:127] op_sel:[1,1] op_sel_hi:[0,1]
	v_pk_fma_f32 v[116:117], v[116:117], v[126:127], v[102:103] op_sel_hi:[1,0,1] neg_hi:[0,0,1]
	s_waitcnt lgkmcnt(10)
	v_pk_mul_f32 v[176:177], v[124:125], v[118:119] op_sel:[1,1] op_sel_hi:[0,1]
	v_pk_fma_f32 v[124:125], v[124:125], v[118:119], v[176:177] op_sel_hi:[1,0,1] neg_hi:[0,0,1]
	s_waitcnt lgkmcnt(8)
	v_pk_mul_f32 v[102:103], v[166:167], v[182:183] op_sel:[1,1] op_sel_hi:[0,1]
	v_pk_fma_f32 v[166:167], v[166:167], v[182:183], v[102:103] op_sel_hi:[1,0,1] neg_hi:[0,0,1]
	ds_read_b64 v[112:113], v5 offset:2376
	ds_read_b64 v[176:177], v56 offset:2304
	ds_read_b64 v[120:121], v5 offset:2640
	ds_read_b64 v[102:103], v56 offset:2560
	ds_read_b64 v[128:129], v5 offset:2904
	ds_read_b64 v[110:111], v56 offset:2816
	ds_read_b64 v[106:107], v5 offset:3168
	ds_read_b64 v[126:127], v56 offset:3072
	s_waitcnt lgkmcnt(14)
	v_pk_mul_f32 v[118:119], v[188:189], v[174:175] op_sel:[1,1] op_sel_hi:[0,1]
	v_pk_fma_f32 v[188:189], v[188:189], v[174:175], v[118:119] op_sel_hi:[1,0,1] neg_hi:[0,0,1]
	s_waitcnt lgkmcnt(12)
	v_pk_mul_f32 v[182:183], v[168:169], v[184:185] op_sel:[1,1] op_sel_hi:[0,1]
	v_pk_fma_f32 v[168:169], v[168:169], v[184:185], v[182:183] op_sel_hi:[1,0,1] neg_hi:[0,0,1]
	s_waitcnt lgkmcnt(10)
	v_pk_mul_f32 v[118:119], v[186:187], v[180:181] op_sel:[1,1] op_sel_hi:[0,1]
	v_pk_fma_f32 v[186:187], v[186:187], v[180:181], v[118:119] op_sel_hi:[1,0,1] neg_hi:[0,0,1]
	s_waitcnt lgkmcnt(8)
	v_pk_mul_f32 v[182:183], v[104:105], v[178:179] op_sel:[1,1] op_sel_hi:[0,1]
	v_pk_fma_f32 v[104:105], v[104:105], v[178:179], v[182:183] op_sel_hi:[1,0,1] neg_hi:[0,0,1]
	ds_read_b64 v[114:115], v5 offset:3432
	ds_read_b64 v[118:119], v56 offset:3328
	ds_read_b64 v[122:123], v5 offset:3696
	ds_read_b64 v[182:183], v56 offset:3584
	ds_read_b64 v[130:131], v5 offset:3960
	ds_read_b64 v[174:175], v56 offset:3840
	s_waitcnt lgkmcnt(12)
	v_pk_mul_f32 v[184:185], v[112:113], v[176:177] op_sel:[1,1] op_sel_hi:[0,1]
	v_pk_fma_f32 v[112:113], v[112:113], v[176:177], v[184:185] op_sel_hi:[1,0,1] neg_hi:[0,0,1]
	s_waitcnt lgkmcnt(10)
	v_pk_mul_f32 v[180:181], v[120:121], v[102:103] op_sel:[1,1] op_sel_hi:[0,1]
	v_pk_fma_f32 v[120:121], v[120:121], v[102:103], v[180:181] op_sel_hi:[1,0,1] neg_hi:[0,0,1]
	s_waitcnt lgkmcnt(8)
	v_pk_mul_f32 v[178:179], v[128:129], v[110:111] op_sel:[1,1] op_sel_hi:[0,1]
	v_pk_fma_f32 v[128:129], v[128:129], v[110:111], v[178:179] op_sel_hi:[1,0,1] neg_hi:[0,0,1]
	s_waitcnt lgkmcnt(6)
	v_pk_mul_f32 v[184:185], v[106:107], v[126:127] op_sel:[1,1] op_sel_hi:[0,1]
	v_pk_fma_f32 v[106:107], v[106:107], v[126:127], v[184:185] op_sel_hi:[1,0,1] neg_hi:[0,0,1]
	s_waitcnt lgkmcnt(4)
	v_pk_mul_f32 v[180:181], v[114:115], v[118:119] op_sel:[1,1] op_sel_hi:[0,1]
	v_pk_fma_f32 v[114:115], v[114:115], v[118:119], v[180:181] op_sel_hi:[1,0,1] neg_hi:[0,0,1]
	s_waitcnt lgkmcnt(2)
	v_pk_mul_f32 v[178:179], v[122:123], v[182:183] op_sel:[1,1] op_sel_hi:[0,1]
	v_pk_fma_f32 v[122:123], v[122:123], v[182:183], v[178:179] op_sel_hi:[1,0,1] neg_hi:[0,0,1]
	s_waitcnt lgkmcnt(0)
	v_pk_mul_f32 v[184:185], v[130:131], v[174:175] op_sel:[1,1] op_sel_hi:[0,1]
	v_pk_fma_f32 v[130:131], v[130:131], v[174:175], v[184:185] op_sel_hi:[1,0,1] neg_hi:[0,0,1]
	v_pk_add_f32 v[176:177], v[100:101], v[104:105]
	v_pk_add_f32 v[102:103], v[100:101], v[104:105] neg_lo:[0,1] neg_hi:[0,1]
	v_pk_add_f32 v[110:111], v[166:167], v[106:107]
	v_pk_add_f32 v[126:127], v[166:167], v[106:107] neg_lo:[0,1] neg_hi:[0,1]
	v_pk_add_f32 v[100:101], v[176:177], v[110:111]
	v_pk_add_f32 v[104:105], v[176:177], v[110:111] neg_lo:[0,1] neg_hi:[0,1]
	v_pk_add_f32 v[166:167], v[102:103], v[126:127] op_sel:[0,1] op_sel_hi:[1,0] neg_lo:[0,1]
	v_pk_add_f32 v[106:107], v[102:103], v[126:127] op_sel:[0,1] op_sel_hi:[1,0] neg_hi:[0,1]
	v_pk_add_f32 v[180:181], v[108:109], v[112:113]
	v_pk_add_f32 v[178:179], v[108:109], v[112:113] neg_lo:[0,1] neg_hi:[0,1]
	v_pk_add_f32 v[184:185], v[188:189], v[114:115]
	v_pk_add_f32 v[118:119], v[188:189], v[114:115] neg_lo:[0,1] neg_hi:[0,1]
	v_pk_add_f32 v[108:109], v[180:181], v[184:185]
	v_pk_add_f32 v[112:113], v[180:181], v[184:185] neg_lo:[0,1] neg_hi:[0,1]
	v_pk_add_f32 v[188:189], v[178:179], v[118:119] op_sel:[0,1] op_sel_hi:[1,0] neg_lo:[0,1]
	v_pk_add_f32 v[114:115], v[178:179], v[118:119] op_sel:[0,1] op_sel_hi:[1,0] neg_hi:[0,1]
	v_pk_add_f32 v[182:183], v[116:117], v[120:121]
	v_pk_add_f32 v[174:175], v[116:117], v[120:121] neg_lo:[0,1] neg_hi:[0,1]
	v_pk_add_f32 v[176:177], v[168:169], v[122:123]
	v_pk_add_f32 v[102:103], v[168:169], v[122:123] neg_lo:[0,1] neg_hi:[0,1]
	v_pk_add_f32 v[116:117], v[182:183], v[176:177]
	v_pk_add_f32 v[120:121], v[182:183], v[176:177] neg_lo:[0,1] neg_hi:[0,1]
	v_pk_add_f32 v[168:169], v[174:175], v[102:103] op_sel:[0,1] op_sel_hi:[1,0] neg_lo:[0,1]
	v_pk_add_f32 v[122:123], v[174:175], v[102:103] op_sel:[0,1] op_sel_hi:[1,0] neg_hi:[0,1]
	v_pk_add_f32 v[110:111], v[124:125], v[128:129]
	v_pk_add_f32 v[126:127], v[124:125], v[128:129] neg_lo:[0,1] neg_hi:[0,1]
	v_pk_add_f32 v[180:181], v[186:187], v[130:131]
	v_pk_add_f32 v[178:179], v[186:187], v[130:131] neg_lo:[0,1] neg_hi:[0,1]
	v_pk_add_f32 v[124:125], v[110:111], v[180:181]
	v_pk_add_f32 v[128:129], v[110:111], v[180:181] neg_lo:[0,1] neg_hi:[0,1]
	v_pk_add_f32 v[186:187], v[126:127], v[178:179] op_sel:[0,1] op_sel_hi:[1,0] neg_lo:[0,1]
	v_pk_add_f32 v[130:131], v[126:127], v[178:179] op_sel:[0,1] op_sel_hi:[1,0] neg_hi:[0,1]
; #define LAS __attribute__((address_space(3)))
; __device__ __forceinline__ f32x2 cmulc(f32x2 a, f32x2 b) { return (f32x2){a.x * b.x + a.y * b.y, a.y * b.x - a.x * b.y}; }
; template <bool INV> __device__ __forceinline__ f32x2 cmul_tw(f32x2 a, f32x2 w) { return INV ? cmulc(a, w) : cmul(a, w); }
; template <bool INV> __device__ __forceinline__ void dft16(f32x2 (&x)[16]) {
;     constexpr float C1 = 0.92387953251128674f, S1 = 0.38268343236508977f, C2 = 0.70710678118654752f;
; #pragma unroll
;     for (int b = 0; b < 4; ++b) dft4<INV>(x[b], x[4 + b], x[8 + b], x[12 + b]);
;     const f32x2 w1 = {C1, -S1}, w2 = {C2, -C2}, w3 = {S1, -C1}, w4 = {0.f, -1.f}, w6 = {-C2, -C2}, w9 = {-C1, S1};
;     x[4 * 1 + 1] = cmul_tw<INV>(x[5], w1); x[4 * 1 + 2] = cmul_tw<INV>(x[6], w2); x[4 * 1 + 3] = cmul_tw<INV>(x[7], w3);
;     x[4 * 2 + 1] = cmul_tw<INV>(x[9], w2); x[4 * 2 + 2] = cmul_tw<INV>(x[10], w4); x[4 * 2 + 3] = cmul_tw<INV>(x[11], w6);
;     x[4 * 3 + 1] = cmul_tw<INV>(x[13], w3); x[4 * 3 + 2] = cmul_tw<INV>(x[14], w6); x[4 * 3 + 3] = cmul_tw<INV>(x[15], w9);
; #pragma unroll
;     for (int c = 0; c < 4; ++c) dft4<INV>(x[4 * c], x[4 * c + 1], x[4 * c + 2], x[4 * c + 3]);
;     f32x2 y[16];
; #pragma unroll
;     for (int k = 0; k < 16; ++k) y[k] = x[4 * (k & 3) + (k >> 2)];
; #pragma unroll
;     for (int k = 0; k < 16; ++k) x[k] = y[k];
; }
; __device__ __forceinline__ void fft_inv2(LAS f32x2* B, const LAS f32x2* TW2, int tid) {
;     asm volatile("" : "+v"(tid));
;     const int b = tid >> 5, n2 = tid & 31, base = 512 * b + n2; f32x2 x[16];
;     x[0] = B[fpad(base)];
; #pragma unroll
;     for (int k = 1; k < 16; ++k) x[k] = cmulc(B[fpad(base + 32 * k)], TW2[k * 32 + n2]);
;     dft16<true>(x);
; #pragma unroll
;     for (int r = 0; r < 16; ++r) B[fpad(base + 32 * r)] = x[r];
; }
	v_pk_mul_f32 v[184:185], v[188:189], s[68:69] op_sel:[1,1] op_sel_hi:[0,1]
	v_pk_fma_f32 v[188:189], v[188:189], s[68:69], v[184:185] op_sel_hi:[1,0,1] neg_hi:[0,0,1]
	v_pk_mul_f32 v[118:119], v[168:169], s[84:85] op_sel:[1,1] op_sel_hi:[0,1]
	v_pk_fma_f32 v[168:169], v[168:169], s[84:85], v[118:119] op_sel_hi:[1,0,1] neg_hi:[0,0,1]
	v_pk_mul_f32 v[182:183], v[186:187], s[88:89] op_sel:[1,1] op_sel_hi:[0,1]
	v_pk_fma_f32 v[186:187], v[186:187], s[88:89], v[182:183] op_sel_hi:[1,0,1] neg_hi:[0,0,1]
	v_pk_mul_f32 v[174:175], v[112:113], s[84:85] op_sel:[1,1] op_sel_hi:[0,1]
	v_pk_fma_f32 v[112:113], v[112:113], s[84:85], v[174:175] op_sel_hi:[1,0,1] neg_hi:[0,0,1]
	v_pk_mul_f32 v[176:177], v[128:129], s[90:91] op_sel:[1,1] op_sel_hi:[0,1]
	v_pk_fma_f32 v[128:129], v[128:129], s[90:91], v[176:177] op_sel_hi:[1,0,1] neg_hi:[0,0,1]
	v_pk_mul_f32 v[102:103], v[114:115], s[88:89] op_sel:[1,1] op_sel_hi:[0,1]
	v_pk_fma_f32 v[114:115], v[114:115], s[88:89], v[102:103] op_sel_hi:[1,0,1] neg_hi:[0,0,1]
	v_pk_mul_f32 v[110:111], v[122:123], s[90:91] op_sel:[1,1] op_sel_hi:[0,1]
	v_pk_fma_f32 v[122:123], v[122:123], s[90:91], v[110:111] op_sel_hi:[1,0,1] neg_hi:[0,0,1]
	v_pk_mul_f32 v[126:127], v[130:131], s[98:99] op_sel:[1,1] op_sel_hi:[0,1]
	v_pk_fma_f32 v[130:131], v[130:131], s[98:99], v[126:127] op_sel_hi:[1,0,1] neg_hi:[0,0,1]
	v_pk_add_f32 v[180:181], v[100:101], v[116:117]
	v_pk_add_f32 v[178:179], v[100:101], v[116:117] neg_lo:[0,1] neg_hi:[0,1]
	v_pk_add_f32 v[184:185], v[108:109], v[124:125]
	v_pk_add_f32 v[118:119], v[108:109], v[124:125] neg_lo:[0,1] neg_hi:[0,1]
	v_pk_add_f32 v[100:101], v[180:181], v[184:185]
	v_pk_add_f32 v[116:117], v[180:181], v[184:185] neg_lo:[0,1] neg_hi:[0,1]
	v_pk_add_f32 v[108:109], v[178:179], v[118:119] op_sel:[0,1] op_sel_hi:[1,0] neg_lo:[0,1]
	v_pk_add_f32 v[124:125], v[178:179], v[118:119] op_sel:[0,1] op_sel_hi:[1,0] neg_hi:[0,1]
	v_pk_add_f32 v[182:183], v[166:167], v[168:169]
	v_pk_add_f32 v[174:175], v[166:167], v[168:169] neg_lo:[0,1] neg_hi:[0,1]
	v_pk_add_f32 v[176:177], v[188:189], v[186:187]
	v_pk_add_f32 v[102:103], v[188:189], v[186:187] neg_lo:[0,1] neg_hi:[0,1]
	v_pk_add_f32 v[166:167], v[182:183], v[176:177]
	v_pk_add_f32 v[168:169], v[182:183], v[176:177] neg_lo:[0,1] neg_hi:[0,1]
	v_pk_add_f32 v[188:189], v[174:175], v[102:103] op_sel:[0,1] op_sel_hi:[1,0] neg_lo:[0,1]
	v_pk_add_f32 v[186:187], v[174:175], v[102:103] op_sel:[0,1] op_sel_hi:[1,0] neg_hi:[0,1]
	v_pk_add_f32 v[110:111], v[104:105], v[120:121] op_sel:[0,1] op_sel_hi:[1,0] neg_lo:[0,1]
	v_pk_add_f32 v[126:127], v[104:105], v[120:121] op_sel:[0,1] op_sel_hi:[1,0] neg_hi:[0,1]
	v_pk_add_f32 v[180:181], v[112:113], v[128:129]
	v_pk_add_f32 v[178:179], v[112:113], v[128:129] neg_lo:[0,1] neg_hi:[0,1]
	v_pk_add_f32 v[104:105], v[110:111], v[180:181]
	v_pk_add_f32 v[120:121], v[110:111], v[180:181] neg_lo:[0,1] neg_hi:[0,1]
	v_pk_add_f32 v[112:113], v[126:127], v[178:179] op_sel:[0,1] op_sel_hi:[1,0] neg_lo:[0,1]
	v_pk_add_f32 v[128:129], v[126:127], v[178:179] op_sel:[0,1] op_sel_hi:[1,0] neg_hi:[0,1]
	v_pk_add_f32 v[184:185], v[106:107], v[122:123]
	v_pk_add_f32 v[118:119], v[106:107], v[122:123] neg_lo:[0,1] neg_hi:[0,1]
	v_pk_add_f32 v[182:183], v[114:115], v[130:131]
	v_pk_add_f32 v[174:175], v[114:115], v[130:131] neg_lo:[0,1] neg_hi:[0,1]
	v_pk_add_f32 v[106:107], v[184:185], v[182:183]
	v_pk_add_f32 v[122:123], v[184:185], v[182:183] neg_lo:[0,1] neg_hi:[0,1]
	v_pk_add_f32 v[114:115], v[118:119], v[174:175] op_sel:[0,1] op_sel_hi:[1,0] neg_lo:[0,1]
	v_pk_add_f32 v[130:131], v[118:119], v[174:175] op_sel:[0,1] op_sel_hi:[1,0] neg_hi:[0,1]
	ds_write_b64 v5, v[100:101]
	ds_write_b64 v5, v[166:167] offset:264
	ds_write_b64 v5, v[104:105] offset:528
	ds_write_b64 v5, v[106:107] offset:792
	ds_write_b64 v5, v[108:109] offset:1056
	ds_write_b64 v5, v[188:189] offset:1320
	ds_write_b64 v5, v[112:113] offset:1584
	ds_write_b64 v5, v[114:115] offset:1848
	ds_write_b64 v5, v[116:117] offset:2112
	ds_write_b64 v5, v[168:169] offset:2376
	ds_write_b64 v5, v[120:121] offset:2640
	ds_write_b64 v5, v[122:123] offset:2904
	ds_write_b64 v5, v[124:125] offset:3168
	ds_write_b64 v5, v[186:187] offset:3432
	ds_write_b64 v5, v[128:129] offset:3696
	ds_write_b64 v5, v[130:131] offset:3960
	s_waitcnt lgkmcnt(0)
	s_barrier
; #define LAS __attribute__((address_space(3)))
; __device__ __forceinline__ f32x2 cmulc(f32x2 a, f32x2 b) { return (f32x2){a.x * b.x + a.y * b.y, a.y * b.x - a.x * b.y}; }
; __device__ __forceinline__ void dft16_inv_lo(f32x2 (&x)[16]) {
;     constexpr float C1 = 0.92387953251128674f, S1 = 0.38268343236508977f, C2 = 0.70710678118654752f;
; #pragma unroll
;     for (int b = 0; b < 4; ++b) dft4<true>(x[b], x[4 + b], x[8 + b], x[12 + b]);
;     const f32x2 w1 = {C1, -S1}, w2 = {C2, -C2}, w3 = {S1, -C1}, w4 = {0.f, -1.f}, w6 = {-C2, -C2}, w9 = {-C1, S1};
;     x[5] = cmulc(x[5], w1); x[6] = cmulc(x[6], w2); x[7] = cmulc(x[7], w3);
;     x[9] = cmulc(x[9], w2); x[10] = cmulc(x[10], w4); x[11] = cmulc(x[11], w6);
;     x[13] = cmulc(x[13], w3); x[14] = cmulc(x[14], w6); x[15] = cmulc(x[15], w9);
;     f32x2 y[8];
; #pragma unroll
;     for (int c = 0; c < 4; ++c) { const f32x2 t0 = x[4 * c] + x[4 * c + 2], t1 = x[4 * c] - x[4 * c + 2], t2 = x[4 * c + 1] + x[4 * c + 3], t3 = x[4 * c + 1] - x[4 * c + 3];
;         y[c] = t0 + t2; y[4 + c] = t1 + (f32x2){-t3.y, t3.x}; }
; #pragma unroll
;     for (int k = 0; k < 8; ++k) x[k] = y[k];
; }
; __device__ __forceinline__ void fft_inv1(f32x2 (&x)[16], const LAS f32x2* B, int n2, const f32x2 (&w)[16]) {
;     asm volatile("" : "+v"(n2));
;     x[0] = B[fpad(n2)];
; #pragma unroll
;     for (int k = 1; k < 16; ++k) x[k] = cmulc(B[fpad(512 * k + n2)], w[k]);
;     dft16_inv_lo(x);
; }
	ds_read_b64 v[100:101], v3
	ds_read_b64 v[108:109], v3 offset:16896
	ds_read_b64 v[116:117], v3 offset:33792
	ds_read_b64 v[124:125], v3 offset:50688
	ds_read_b64 v[166:167], v3 offset:4224
	ds_read_b64 v[188:189], v3 offset:21120
	ds_read_b64 v[168:169], v3 offset:38016
	ds_read_b64 v[186:187], v3 offset:54912
	ds_read_b64 v[104:105], v3 offset:8448
	ds_read_b64 v[112:113], v3 offset:25344
	ds_read_b64 v[120:121], v3 offset:42240
	ds_read_b64 v[128:129], v3 offset:59136
	ds_read_b64 v[106:107], v3 offset:12672
	ds_read_b64 v[114:115], v3 offset:29568
	ds_read_b64 v[122:123], v3 offset:46464
	ds_read_b64 v[130:131], v3 offset:63360
	s_waitcnt lgkmcnt(14)
	v_pk_mul_f32 v[176:177], v[108:109], v[12:13] op_sel:[1,1] op_sel_hi:[0,1]
	v_pk_fma_f32 v[108:109], v[108:109], v[12:13], v[176:177] op_sel_hi:[1,0,1] neg_hi:[0,0,1]
	s_waitcnt lgkmcnt(13)
	v_pk_mul_f32 v[102:103], v[116:117], v[20:21] op_sel:[1,1] op_sel_hi:[0,1]
	v_pk_fma_f32 v[116:117], v[116:117], v[20:21], v[102:103] op_sel_hi:[1,0,1] neg_hi:[0,0,1]
	s_waitcnt lgkmcnt(12)
	v_pk_mul_f32 v[110:111], v[124:125], v[28:29] op_sel:[1,1] op_sel_hi:[0,1]
	v_pk_fma_f32 v[124:125], v[124:125], v[28:29], v[110:111] op_sel_hi:[1,0,1] neg_hi:[0,0,1]
	s_waitcnt lgkmcnt(11)
	v_pk_mul_f32 v[126:127], v[166:167], v[6:7] op_sel:[1,1] op_sel_hi:[0,1]
	v_pk_fma_f32 v[166:167], v[166:167], v[6:7], v[126:127] op_sel_hi:[1,0,1] neg_hi:[0,0,1]
	s_waitcnt lgkmcnt(10)
	v_pk_mul_f32 v[180:181], v[188:189], v[14:15] op_sel:[1,1] op_sel_hi:[0,1]
	v_pk_fma_f32 v[188:189], v[188:189], v[14:15], v[180:181] op_sel_hi:[1,0,1] neg_hi:[0,0,1]
	s_waitcnt lgkmcnt(9)
	v_pk_mul_f32 v[178:179], v[168:169], v[22:23] op_sel:[1,1] op_sel_hi:[0,1]
	v_pk_fma_f32 v[168:169], v[168:169], v[22:23], v[178:179] op_sel_hi:[1,0,1] neg_hi:[0,0,1]
	s_waitcnt lgkmcnt(8)
	v_pk_mul_f32 v[184:185], v[186:187], v[30:31] op_sel:[1,1] op_sel_hi:[0,1]
	v_pk_fma_f32 v[186:187], v[186:187], v[30:31], v[184:185] op_sel_hi:[1,0,1] neg_hi:[0,0,1]
	s_waitcnt lgkmcnt(7)
	v_pk_mul_f32 v[118:119], v[104:105], v[8:9] op_sel:[1,1] op_sel_hi:[0,1]
	v_pk_fma_f32 v[104:105], v[104:105], v[8:9], v[118:119] op_sel_hi:[1,0,1] neg_hi:[0,0,1]
	s_waitcnt lgkmcnt(6)
	v_pk_mul_f32 v[182:183], v[112:113], v[16:17] op_sel:[1,1] op_sel_hi:[0,1]
	v_pk_fma_f32 v[112:113], v[112:113], v[16:17], v[182:183] op_sel_hi:[1,0,1] neg_hi:[0,0,1]
	s_waitcnt lgkmcnt(5)
	v_pk_mul_f32 v[174:175], v[120:121], v[24:25] op_sel:[1,1] op_sel_hi:[0,1]
	v_pk_fma_f32 v[120:121], v[120:121], v[24:25], v[174:175] op_sel_hi:[1,0,1] neg_hi:[0,0,1]
	s_waitcnt lgkmcnt(4)
	v_pk_mul_f32 v[176:177], v[128:129], v[32:33] op_sel:[1,1] op_sel_hi:[0,1]
	v_pk_fma_f32 v[128:129], v[128:129], v[32:33], v[176:177] op_sel_hi:[1,0,1] neg_hi:[0,0,1]
	s_waitcnt lgkmcnt(3)
	v_pk_mul_f32 v[102:103], v[106:107], v[10:11] op_sel:[1,1] op_sel_hi:[0,1]
	v_pk_fma_f32 v[106:107], v[106:107], v[10:11], v[102:103] op_sel_hi:[1,0,1] neg_hi:[0,0,1]
	s_waitcnt lgkmcnt(2)
	v_pk_mul_f32 v[110:111], v[114:115], v[18:19] op_sel:[1,1] op_sel_hi:[0,1]
	v_pk_fma_f32 v[114:115], v[114:115], v[18:19], v[110:111] op_sel_hi:[1,0,1] neg_hi:[0,0,1]
	s_waitcnt lgkmcnt(1)
	v_pk_mul_f32 v[126:127], v[122:123], v[26:27] op_sel:[1,1] op_sel_hi:[0,1]
	v_pk_fma_f32 v[122:123], v[122:123], v[26:27], v[126:127] op_sel_hi:[1,0,1] neg_hi:[0,0,1]
	s_waitcnt lgkmcnt(0)
	v_pk_mul_f32 v[180:181], v[130:131], v[34:35] op_sel:[1,1] op_sel_hi:[0,1]
	v_pk_fma_f32 v[130:131], v[130:131], v[34:35], v[180:181] op_sel_hi:[1,0,1] neg_hi:[0,0,1]
	v_pk_add_f32 v[178:179], v[100:101], v[116:117]
	v_pk_add_f32 v[184:185], v[100:101], v[116:117] neg_lo:[0,1] neg_hi:[0,1]
	v_pk_add_f32 v[118:119], v[108:109], v[124:125]
	v_pk_add_f32 v[182:183], v[108:109], v[124:125] neg_lo:[0,1] neg_hi:[0,1]
	v_pk_add_f32 v[100:101], v[178:179], v[118:119]
	v_pk_add_f32 v[116:117], v[178:179], v[118:119] neg_lo:[0,1] neg_hi:[0,1]
	v_pk_add_f32 v[108:109], v[184:185], v[182:183] op_sel:[0,1] op_sel_hi:[1,0] neg_lo:[0,1]
	v_pk_add_f32 v[124:125], v[184:185], v[182:183] op_sel:[0,1] op_sel_hi:[1,0] neg_hi:[0,1]
	v_pk_add_f32 v[174:175], v[166:167], v[168:169]
	v_pk_add_f32 v[176:177], v[166:167], v[168:169] neg_lo:[0,1] neg_hi:[0,1]
	v_pk_add_f32 v[102:103], v[188:189], v[186:187]
	v_pk_add_f32 v[110:111], v[188:189], v[186:187] neg_lo:[0,1] neg_hi:[0,1]
	v_pk_add_f32 v[166:167], v[174:175], v[102:103]
	v_pk_add_f32 v[168:169], v[174:175], v[102:103] neg_lo:[0,1] neg_hi:[0,1]
	v_pk_add_f32 v[188:189], v[176:177], v[110:111] op_sel:[0,1] op_sel_hi:[1,0] neg_lo:[0,1]
	v_pk_add_f32 v[186:187], v[176:177], v[110:111] op_sel:[0,1] op_sel_hi:[1,0] neg_hi:[0,1]
	v_pk_add_f32 v[126:127], v[104:105], v[120:121]
	v_pk_add_f32 v[180:181], v[104:105], v[120:121] neg_lo:[0,1] neg_hi:[0,1]
	v_pk_add_f32 v[178:179], v[112:113], v[128:129]
	v_pk_add_f32 v[184:185], v[112:113], v[128:129] neg_lo:[0,1] neg_hi:[0,1]
	v_pk_add_f32 v[104:105], v[126:127], v[178:179]
	v_pk_add_f32 v[120:121], v[126:127], v[178:179] neg_lo:[0,1] neg_hi:[0,1]
	v_pk_add_f32 v[112:113], v[180:181], v[184:185] op_sel:[0,1] op_sel_hi:[1,0] neg_lo:[0,1]
	v_pk_add_f32 v[128:129], v[180:181], v[184:185] op_sel:[0,1] op_sel_hi:[1,0] neg_hi:[0,1]
	v_pk_add_f32 v[118:119], v[106:107], v[122:123]
	v_pk_add_f32 v[182:183], v[106:107], v[122:123] neg_lo:[0,1] neg_hi:[0,1]
	v_pk_add_f32 v[174:175], v[114:115], v[130:131]
	v_pk_add_f32 v[176:177], v[114:115], v[130:131] neg_lo:[0,1] neg_hi:[0,1]
	v_pk_add_f32 v[106:107], v[118:119], v[174:175]
	v_pk_add_f32 v[122:123], v[118:119], v[174:175] neg_lo:[0,1] neg_hi:[0,1]
	v_pk_add_f32 v[114:115], v[182:183], v[176:177] op_sel:[0,1] op_sel_hi:[1,0] neg_lo:[0,1]
; __device__ __forceinline__ f32x2 cmulc(f32x2 a, f32x2 b) { return (f32x2){a.x * b.x + a.y * b.y, a.y * b.x - a.x * b.y}; }
; #define WG_SYNC() do { asm volatile("s_waitcnt lgkmcnt(0)" ::: "memory"); __builtin_amdgcn_s_barrier(); asm volatile("" ::: "memory"); } while (0)
; __device__ __forceinline__ void dft16_inv_lo(f32x2 (&x)[16]) {
;     ...
;     for (int b = 0; b < 4; ++b) dft4<true>(x[b], x[4 + b], x[8 + b], x[12 + b]);
;     const f32x2 w1 = {C1, -S1}, w2 = {C2, -C2}, w3 = {S1, -C1}, w4 = {0.f, -1.f}, w6 = {-C2, -C2}, w9 = {-C1, S1};
;     x[5] = cmulc(x[5], w1); x[6] = cmulc(x[6], w2); x[7] = cmulc(x[7], w3);
;     x[9] = cmulc(x[9], w2); x[10] = cmulc(x[10], w4); x[11] = cmulc(x[11], w6);
;     x[13] = cmulc(x[13], w3); x[14] = cmulc(x[14], w6); x[15] = cmulc(x[15], w9);
;     f32x2 y[8];
; #pragma unroll
;     for (int c = 0; c < 4; ++c) { const f32x2 t0 = x[4 * c] + x[4 * c + 2], t1 = x[4 * c] - x[4 * c + 2], t2 = x[4 * c + 1] + x[4 * c + 3], t3 = x[4 * c + 1] - x[4 * c + 3];
;         y[c] = t0 + t2; y[4 + c] = t1 + (f32x2){-t3.y, t3.x}; }
; #pragma unroll
;     for (int k = 0; k < 8; ++k) x[k] = y[k];
; }
; __device__ __forceinline__ void hyena_fft(LAS unsigned char* lds, int layer, int G, const int wave_s) {
;     ...
;             { const float fb0 = fbias[c];
; #pragma unroll
;               for (int r = 0; r < 8; ++r) { uz[r][0] = ux[r][0] * (x[r].x + fb0 * uz[r][0]); uz[r][1] = ux[r][1] * (x[r].y + fb0 * uz[r][1]); } }
;             WG_SYNC();
;             hy_stage(pl0, PHY, (HY / 4) + unit, jc, tid);
;             WG_SYNC();
	v_pk_add_f32 v[130:131], v[182:183], v[176:177] op_sel:[0,1] op_sel_hi:[1,0] neg_hi:[0,1]
	v_pk_mul_f32 v[102:103], v[188:189], s[68:69] op_sel:[1,1] op_sel_hi:[0,1]
	v_pk_fma_f32 v[188:189], v[188:189], s[68:69], v[102:103] op_sel_hi:[1,0,1] neg_hi:[0,0,1]
	v_pk_mul_f32 v[110:111], v[112:113], s[84:85] op_sel:[1,1] op_sel_hi:[0,1]
	v_pk_fma_f32 v[112:113], v[112:113], s[84:85], v[110:111] op_sel_hi:[1,0,1] neg_hi:[0,0,1]
	v_pk_mul_f32 v[126:127], v[114:115], s[88:89] op_sel:[1,1] op_sel_hi:[0,1]
	v_pk_fma_f32 v[114:115], v[114:115], s[88:89], v[126:127] op_sel_hi:[1,0,1] neg_hi:[0,0,1]
	v_pk_mul_f32 v[180:181], v[168:169], s[84:85] op_sel:[1,1] op_sel_hi:[0,1]
	v_pk_fma_f32 v[168:169], v[168:169], s[84:85], v[180:181] op_sel_hi:[1,0,1] neg_hi:[0,0,1]
	v_pk_mul_f32 v[178:179], v[122:123], s[90:91] op_sel:[1,1] op_sel_hi:[0,1]
	v_pk_fma_f32 v[122:123], v[122:123], s[90:91], v[178:179] op_sel_hi:[1,0,1] neg_hi:[0,0,1]
	v_pk_mul_f32 v[184:185], v[186:187], s[88:89] op_sel:[1,1] op_sel_hi:[0,1]
	v_pk_fma_f32 v[186:187], v[186:187], s[88:89], v[184:185] op_sel_hi:[1,0,1] neg_hi:[0,0,1]
	v_pk_mul_f32 v[118:119], v[128:129], s[90:91] op_sel:[1,1] op_sel_hi:[0,1]
	v_pk_fma_f32 v[128:129], v[128:129], s[90:91], v[118:119] op_sel_hi:[1,0,1] neg_hi:[0,0,1]
	v_pk_mul_f32 v[182:183], v[130:131], s[98:99] op_sel:[1,1] op_sel_hi:[0,1]
	v_pk_fma_f32 v[130:131], v[130:131], s[98:99], v[182:183] op_sel_hi:[1,0,1] neg_hi:[0,0,1]
	v_pk_add_f32 v[174:175], v[100:101], v[104:105]
	v_pk_add_f32 v[176:177], v[100:101], v[104:105] neg_lo:[0,1] neg_hi:[0,1]
	v_pk_add_f32 v[102:103], v[166:167], v[106:107]
	v_pk_add_f32 v[110:111], v[166:167], v[106:107] neg_lo:[0,1] neg_hi:[0,1]
	v_pk_add_f32 v[100:101], v[174:175], v[102:103]
	v_pk_add_f32 v[166:167], v[176:177], v[110:111] op_sel:[0,1] op_sel_hi:[1,0] neg_lo:[0,1]
	v_pk_add_f32 v[126:127], v[108:109], v[112:113]
	v_pk_add_f32 v[180:181], v[108:109], v[112:113] neg_lo:[0,1] neg_hi:[0,1]
	v_pk_add_f32 v[178:179], v[188:189], v[114:115]
	v_pk_add_f32 v[184:185], v[188:189], v[114:115] neg_lo:[0,1] neg_hi:[0,1]
	v_pk_add_f32 v[108:109], v[126:127], v[178:179]
	v_pk_add_f32 v[188:189], v[180:181], v[184:185] op_sel:[0,1] op_sel_hi:[1,0] neg_lo:[0,1]
	v_pk_add_f32 v[118:119], v[116:117], v[120:121] op_sel:[0,1] op_sel_hi:[1,0] neg_lo:[0,1]
	v_pk_add_f32 v[182:183], v[116:117], v[120:121] op_sel:[0,1] op_sel_hi:[1,0] neg_hi:[0,1]
	v_pk_add_f32 v[174:175], v[168:169], v[122:123]
	v_pk_add_f32 v[176:177], v[168:169], v[122:123] neg_lo:[0,1] neg_hi:[0,1]
	v_pk_add_f32 v[116:117], v[118:119], v[174:175]
	v_pk_add_f32 v[168:169], v[182:183], v[176:177] op_sel:[0,1] op_sel_hi:[1,0] neg_lo:[0,1]
	v_pk_add_f32 v[102:103], v[124:125], v[128:129]
	v_pk_add_f32 v[110:111], v[124:125], v[128:129] neg_lo:[0,1] neg_hi:[0,1]
	v_pk_add_f32 v[126:127], v[186:187], v[130:131]
	v_pk_add_f32 v[180:181], v[186:187], v[130:131] neg_lo:[0,1] neg_hi:[0,1]
	v_pk_add_f32 v[124:125], v[102:103], v[126:127]
	v_pk_add_f32 v[186:187], v[110:111], v[180:181] op_sel:[0,1] op_sel_hi:[1,0] neg_lo:[0,1]
	s_load_dword s35, s[50:51], 0x0
	s_waitcnt lgkmcnt(0)
	v_mov_b32_e32 v194, s35
	v_pk_fma_f32 v[178:179], v[132:133], v[194:195], v[100:101] op_sel_hi:[1,0,1]
	v_pk_mul_f32 v[132:133], v[148:149], v[178:179]
	v_pk_fma_f32 v[184:185], v[134:135], v[194:195], v[108:109] op_sel_hi:[1,0,1]
	v_pk_mul_f32 v[134:135], v[150:151], v[184:185]
	v_pk_fma_f32 v[118:119], v[136:137], v[194:195], v[116:117] op_sel_hi:[1,0,1]
	v_pk_mul_f32 v[136:137], v[152:153], v[118:119]
	v_pk_fma_f32 v[182:183], v[138:139], v[194:195], v[124:125] op_sel_hi:[1,0,1]
	v_pk_mul_f32 v[138:139], v[154:155], v[182:183]
	v_pk_fma_f32 v[174:175], v[140:141], v[194:195], v[166:167] op_sel_hi:[1,0,1]
	v_pk_mul_f32 v[140:141], v[158:159], v[174:175]
	v_pk_fma_f32 v[176:177], v[142:143], v[194:195], v[188:189] op_sel_hi:[1,0,1]
	v_pk_mul_f32 v[142:143], v[160:161], v[176:177]
	v_pk_fma_f32 v[102:103], v[144:145], v[194:195], v[168:169] op_sel_hi:[1,0,1]
	v_pk_mul_f32 v[144:145], v[162:163], v[102:103]
	v_pk_fma_f32 v[110:111], v[146:147], v[194:195], v[186:187] op_sel_hi:[1,0,1]
	v_pk_mul_f32 v[146:147], v[164:165], v[110:111]
	s_waitcnt lgkmcnt(0)
	s_barrier
	s_waitcnt vmcnt(7)
	v_perm_b32 v126, 0, v58, s15
	v_perm_b32 v127, 0, v60, s15
	ds_write_b64 v206, v[126:127]
	s_waitcnt vmcnt(6)
	v_perm_b32 v180, 0, v62, s15
	v_perm_b32 v181, 0, v64, s15
	ds_write_b64 v206, v[180:181] offset:4096
	s_waitcnt vmcnt(5)
	v_perm_b32 v178, 0, v66, s15
	v_perm_b32 v179, 0, v68, s15
	ds_write_b64 v206, v[178:179] offset:8192
	s_waitcnt vmcnt(4)
	v_perm_b32 v184, 0, v70, s15
	v_perm_b32 v185, 0, v72, s15
	ds_write_b64 v206, v[184:185] offset:12288
	s_waitcnt vmcnt(3)
	v_perm_b32 v118, 0, v74, s15
	v_perm_b32 v119, 0, v76, s15
	ds_write_b64 v206, v[118:119] offset:16384
	s_waitcnt vmcnt(2)
	v_perm_b32 v182, 0, v78, s15
	v_perm_b32 v183, 0, v80, s15
	ds_write_b64 v206, v[182:183] offset:20480
	s_waitcnt vmcnt(1)
	v_perm_b32 v174, 0, v82, s15
	v_perm_b32 v175, 0, v84, s15
	ds_write_b64 v206, v[174:175] offset:24576
	s_waitcnt vmcnt(0)
	v_perm_b32 v176, 0, v86, s15
	v_perm_b32 v177, 0, v88, s15
	ds_write_b64 v206, v[176:177] offset:28672
	s_waitcnt lgkmcnt(0)
	s_barrier
; #define LAS __attribute__((address_space(3)))
; __device__ __forceinline__ void hy_sconv(const LAS float* plane, float w0, float w1, float w2, float cb, int n2, float (&u)[8][2]) {
;     asm volatile("" : "+v"(n2));
; #pragma unroll
;     for (int r = 0; r < 8; ++r)
; #pragma unroll
;         for (int b = 0; b < 2; ++b) { const int t = n2 + 512 * r, row = b * SEQ + t;
;             float a = cb + w1 * plane[row];
;             if (t > 0) a += w0 * plane[row - 1];
;             if (t < SEQ - 1) a += w2 * plane[row + 1];
;             u[r][b] = a; }
; }
; __device__ __forceinline__ void hyena_fft(LAS unsigned char* lds, int layer, int G, const int wave_s) {
;     ...
;             hy_sconv(pl0, cw[HY + c], cw[3 * HY + HY + c], cw[6 * HY + HY + c], cb[HY + c], n2, ux);
	v_mov_b32_e32 v102, s17
	v_mov_b32_e32 v103, s23
	v_mov_b32_e32 v110, s25
	v_mov_b32_e32 v111, s26
	ds_read_b32 v126, v208
	ds_read_b32 v180, v210
	ds_read_b32 v178, v208 offset:4
	ds_read_b32 v127, v208 offset:16384
	ds_read_b32 v181, v210 offset:16384
	ds_read_b32 v179, v208 offset:16388
	ds_read_b32 v184, v208 offset:2048
	ds_read_b32 v118, v208 offset:2044
	ds_read_b32 v182, v208 offset:2052
	ds_read_b32 v185, v208 offset:18432
	ds_read_b32 v119, v208 offset:18428
	ds_read_b32 v183, v208 offset:18436
	s_waitcnt lgkmcnt(10)
	v_cndmask_b32_e64 v180, v180, 0, s[10:11]
	s_waitcnt lgkmcnt(7)
	v_cndmask_b32_e64 v181, v181, 0, s[10:11]
	v_pk_fma_f32 v[148:149], v[102:103], v[126:127], v[110:111] op_sel:[1,0,1]
	v_pk_fma_f32 v[148:149], v[102:103], v[180:181], v[148:149] op_sel_hi:[0,1,1]
	s_waitcnt lgkmcnt(6)
	v_pk_fma_f32 v[148:149], v[110:111], v[178:179], v[148:149] op_sel_hi:[0,1,1]
	ds_read_b32 v174, v208 offset:4096
	ds_read_b32 v176, v208 offset:4092
	ds_read_b32 v126, v208 offset:4100
	ds_read_b32 v175, v208 offset:20480
	ds_read_b32 v177, v208 offset:20476
	ds_read_b32 v127, v208 offset:20484
	s_waitcnt lgkmcnt(8)
	v_pk_fma_f32 v[150:151], v[102:103], v[184:185], v[110:111] op_sel:[1,0,1]
	s_waitcnt lgkmcnt(7)
	v_pk_fma_f32 v[150:151], v[102:103], v[118:119], v[150:151] op_sel_hi:[0,1,1]
	s_waitcnt lgkmcnt(6)
	v_pk_fma_f32 v[150:151], v[110:111], v[182:183], v[150:151] op_sel_hi:[0,1,1]
	ds_read_b32 v180, v208 offset:6144
	ds_read_b32 v178, v208 offset:6140
	ds_read_b32 v184, v208 offset:6148
	ds_read_b32 v181, v208 offset:22528
	ds_read_b32 v179, v208 offset:22524
	ds_read_b32 v185, v208 offset:22532
	s_waitcnt lgkmcnt(8)
	v_pk_fma_f32 v[152:153], v[102:103], v[174:175], v[110:111] op_sel:[1,0,1]
	s_waitcnt lgkmcnt(7)
	v_pk_fma_f32 v[152:153], v[102:103], v[176:177], v[152:153] op_sel_hi:[0,1,1]
	s_waitcnt lgkmcnt(6)
	v_pk_fma_f32 v[152:153], v[110:111], v[126:127], v[152:153] op_sel_hi:[0,1,1]
	ds_read_b32 v118, v208 offset:8192
	ds_read_b32 v182, v208 offset:8188
	ds_read_b32 v174, v208 offset:8196
	ds_read_b32 v119, v208 offset:24576
	ds_read_b32 v183, v208 offset:24572
	ds_read_b32 v175, v208 offset:24580
	s_waitcnt lgkmcnt(8)
	v_pk_fma_f32 v[154:155], v[102:103], v[180:181], v[110:111] op_sel:[1,0,1]
	s_waitcnt lgkmcnt(7)
	v_pk_fma_f32 v[154:155], v[102:103], v[178:179], v[154:155] op_sel_hi:[0,1,1]
	s_waitcnt lgkmcnt(6)
	v_pk_fma_f32 v[154:155], v[110:111], v[184:185], v[154:155] op_sel_hi:[0,1,1]
	ds_read_b32 v176, v208 offset:10240
	ds_read_b32 v126, v208 offset:10236
	ds_read_b32 v180, v208 offset:10244
	ds_read_b32 v177, v208 offset:26624
	ds_read_b32 v127, v208 offset:26620
	ds_read_b32 v181, v208 offset:26628
	s_waitcnt lgkmcnt(8)
	v_pk_fma_f32 v[158:159], v[102:103], v[118:119], v[110:111] op_sel:[1,0,1]
	s_waitcnt lgkmcnt(7)
	v_pk_fma_f32 v[158:159], v[102:103], v[182:183], v[158:159] op_sel_hi:[0,1,1]
	s_waitcnt lgkmcnt(6)
	v_pk_fma_f32 v[158:159], v[110:111], v[174:175], v[158:159] op_sel_hi:[0,1,1]
	ds_read_b32 v178, v208 offset:12288
	ds_read_b32 v184, v208 offset:12284
	ds_read_b32 v118, v208 offset:12292
	ds_read_b32 v179, v208 offset:28672
	ds_read_b32 v185, v208 offset:28668
	ds_read_b32 v119, v208 offset:28676
	s_waitcnt lgkmcnt(8)
	v_pk_fma_f32 v[160:161], v[102:103], v[176:177], v[110:111] op_sel:[1,0,1]
	s_waitcnt lgkmcnt(7)
	v_pk_fma_f32 v[160:161], v[102:103], v[126:127], v[160:161] op_sel_hi:[0,1,1]
	s_waitcnt lgkmcnt(6)
	v_pk_fma_f32 v[160:161], v[110:111], v[180:181], v[160:161] op_sel_hi:[0,1,1]
	ds_read_b32 v182, v208 offset:14336
	ds_read_b32 v174, v208 offset:14332
	ds_read_b32 v176, v208 offset:14340
	ds_read_b32 v183, v208 offset:30720
	ds_read_b32 v175, v208 offset:30716
	ds_read_b32 v177, v208 offset:30724
	s_waitcnt lgkmcnt(8)
	v_pk_fma_f32 v[162:163], v[102:103], v[178:179], v[110:111] op_sel:[1,0,1]
	s_waitcnt lgkmcnt(7)
	v_pk_fma_f32 v[162:163], v[102:103], v[184:185], v[162:163] op_sel_hi:[0,1,1]
	s_waitcnt lgkmcnt(6)
	v_pk_fma_f32 v[162:163], v[110:111], v[118:119], v[162:163] op_sel_hi:[0,1,1]
	s_waitcnt lgkmcnt(3)
	v_cndmask_b32_e64 v176, v176, 0, s[28:29]
	s_waitcnt lgkmcnt(0)
	v_cndmask_b32_e64 v177, v177, 0, s[28:29]
	v_pk_fma_f32 v[164:165], v[102:103], v[182:183], v[110:111] op_sel:[1,0,1]
	v_pk_fma_f32 v[164:165], v[102:103], v[174:175], v[164:165] op_sel_hi:[0,1,1]
	v_pk_fma_f32 v[164:165], v[110:111], v[176:177], v[164:165] op_sel_hi:[0,1,1]
	s_waitcnt lgkmcnt(0)
	s_barrier
; #define LAS __attribute__((address_space(3)))
; __device__ __forceinline__ f32x2 cmul(f32x2 a, f32x2 b) { return (f32x2){a.x * b.x - a.y * b.y, a.x * b.y + a.y * b.x}; }
; __device__ __forceinline__ void dft16_fwd_lo(f32x2 (&x)[16]) {
;     constexpr float C1 = 0.92387953251128674f, S1 = 0.38268343236508977f, C2 = 0.70710678118654752f;
; #pragma unroll
;     for (int b = 0; b < 4; ++b) { const f32x2 x0 = x[b], x1 = x[4 + b]; const f32x2 j1 = {x1.y, -x1.x};
;         x[b] = x0 + x1; x[4 + b] = x0 + j1; x[8 + b] = x0 - x1; x[12 + b] = x0 - j1; }
;     const f32x2 w1 = {C1, -S1}, w2 = {C2, -C2}, w3 = {S1, -C1}, w4 = {0.f, -1.f}, w6 = {-C2, -C2}, w9 = {-C1, S1};
;     x[5] = cmul(x[5], w1); x[6] = cmul(x[6], w2); x[7] = cmul(x[7], w3);
;     x[9] = cmul(x[9], w2); x[10] = cmul(x[10], w4); x[11] = cmul(x[11], w6);
;     x[13] = cmul(x[13], w3); x[14] = cmul(x[14], w6); x[15] = cmul(x[15], w9);
; #pragma unroll
;     for (int c = 0; c < 4; ++c) dft4<false>(x[4 * c], x[4 * c + 1], x[4 * c + 2], x[4 * c + 3]);
;     f32x2 y[16];
; #pragma unroll
;     for (int k = 0; k < 16; ++k) y[k] = x[4 * (k & 3) + (k >> 2)];
; #pragma unroll
;     for (int k = 0; k < 16; ++k) x[k] = y[k];
; }
; template <bool LO> __device__ __forceinline__ void fft_fwd1(f32x2 (&x)[16], LAS f32x2* B, int n2, const f32x2 (&w)[16]) {
;     asm volatile("" : "+v"(n2));
;     if (LO) dft16_fwd_lo(x); else dft16<false>(x);
;     B[fpad(n2)] = x[0];
; #pragma unroll
;     for (int k = 1; k < 16; ++k) B[fpad(512 * k + n2)] = cmul(x[k], w[k]);
; }
	v_pk_add_f32 v[104:105], v[132:133], v[140:141] neg_lo:[0,1] neg_hi:[0,1]
	v_pk_add_f32 v[106:107], v[132:133], v[140:141] op_sel:[0,1] op_sel_hi:[1,0] neg_lo:[0,1]
	v_pk_add_f32 v[126:127], v[132:133], v[140:141] op_sel:[0,1] op_sel_hi:[1,0] neg_hi:[0,1]
	v_pk_add_f32 v[100:101], v[132:133], v[140:141]
	v_pk_add_f32 v[112:113], v[134:135], v[142:143] neg_lo:[0,1] neg_hi:[0,1]
	v_pk_add_f32 v[114:115], v[134:135], v[142:143] op_sel:[0,1] op_sel_hi:[1,0] neg_lo:[0,1]
	v_pk_add_f32 v[180:181], v[134:135], v[142:143] op_sel:[0,1] op_sel_hi:[1,0] neg_hi:[0,1]
	v_pk_add_f32 v[108:109], v[134:135], v[142:143]
	v_pk_add_f32 v[120:121], v[136:137], v[144:145] neg_lo:[0,1] neg_hi:[0,1]
	v_pk_add_f32 v[122:123], v[136:137], v[144:145] op_sel:[0,1] op_sel_hi:[1,0] neg_lo:[0,1]
	v_pk_add_f32 v[178:179], v[136:137], v[144:145] op_sel:[0,1] op_sel_hi:[1,0] neg_hi:[0,1]
	v_pk_add_f32 v[116:117], v[136:137], v[144:145]
	v_pk_add_f32 v[128:129], v[138:139], v[146:147] neg_lo:[0,1] neg_hi:[0,1]
	v_pk_add_f32 v[130:131], v[138:139], v[146:147] op_sel:[0,1] op_sel_hi:[1,0] neg_lo:[0,1]
	v_pk_add_f32 v[184:185], v[138:139], v[146:147] op_sel:[0,1] op_sel_hi:[1,0] neg_hi:[0,1]
	v_pk_add_f32 v[124:125], v[138:139], v[146:147]
	v_pk_mul_f32 v[118:119], v[180:181], s[68:69] op_sel:[1,1] op_sel_hi:[0,1]
	v_pk_fma_f32 v[180:181], v[180:181], s[68:69], v[118:119] op_sel_hi:[1,0,1] neg_lo:[0,0,1]
	v_pk_mul_f32 v[182:183], v[178:179], s[84:85] op_sel:[1,1] op_sel_hi:[0,1]
	v_pk_fma_f32 v[178:179], v[178:179], s[84:85], v[182:183] op_sel_hi:[1,0,1] neg_lo:[0,0,1]
	v_pk_mul_f32 v[174:175], v[184:185], s[88:89] op_sel:[1,1] op_sel_hi:[0,1]
	v_pk_fma_f32 v[184:185], v[184:185], s[88:89], v[174:175] op_sel_hi:[1,0,1] neg_lo:[0,0,1]
	v_pk_mul_f32 v[176:177], v[112:113], s[84:85] op_sel:[1,1] op_sel_hi:[0,1]
	v_pk_fma_f32 v[112:113], v[112:113], s[84:85], v[176:177] op_sel_hi:[1,0,1] neg_lo:[0,0,1]
	v_pk_mul_f32 v[102:103], v[128:129], s[90:91] op_sel:[1,1] op_sel_hi:[0,1]
	v_pk_fma_f32 v[128:129], v[128:129], s[90:91], v[102:103] op_sel_hi:[1,0,1] neg_lo:[0,0,1]
	v_pk_mul_f32 v[110:111], v[114:115], s[88:89] op_sel:[1,1] op_sel_hi:[0,1]
	v_pk_fma_f32 v[114:115], v[114:115], s[88:89], v[110:111] op_sel_hi:[1,0,1] neg_lo:[0,0,1]
	v_pk_mul_f32 v[166:167], v[122:123], s[90:91] op_sel:[1,1] op_sel_hi:[0,1]
	v_pk_fma_f32 v[122:123], v[122:123], s[90:91], v[166:167] op_sel_hi:[1,0,1] neg_lo:[0,0,1]
	v_pk_mul_f32 v[188:189], v[130:131], s[98:99] op_sel:[1,1] op_sel_hi:[0,1]
	v_pk_fma_f32 v[130:131], v[130:131], s[98:99], v[188:189] op_sel_hi:[1,0,1] neg_lo:[0,0,1]
	v_pk_add_f32 v[168:169], v[100:101], v[116:117]
	v_pk_add_f32 v[186:187], v[100:101], v[116:117] neg_lo:[0,1] neg_hi:[0,1]
	v_pk_add_f32 v[118:119], v[108:109], v[124:125]
	v_pk_add_f32 v[182:183], v[108:109], v[124:125] neg_lo:[0,1] neg_hi:[0,1]
	v_pk_add_f32 v[100:101], v[168:169], v[118:119]
	v_pk_add_f32 v[116:117], v[168:169], v[118:119] neg_lo:[0,1] neg_hi:[0,1]
	v_pk_add_f32 v[108:109], v[186:187], v[182:183] op_sel:[0,1] op_sel_hi:[1,0] neg_hi:[0,1]
	v_pk_add_f32 v[124:125], v[186:187], v[182:183] op_sel:[0,1] op_sel_hi:[1,0] neg_lo:[0,1]
	v_pk_add_f32 v[174:175], v[126:127], v[178:179]
	v_pk_add_f32 v[176:177], v[126:127], v[178:179] neg_lo:[0,1] neg_hi:[0,1]
	v_pk_add_f32 v[102:103], v[180:181], v[184:185]
	v_pk_add_f32 v[110:111], v[180:181], v[184:185] neg_lo:[0,1] neg_hi:[0,1]
	v_pk_add_f32 v[126:127], v[174:175], v[102:103]
	v_pk_add_f32 v[178:179], v[174:175], v[102:103] neg_lo:[0,1] neg_hi:[0,1]
	v_pk_add_f32 v[180:181], v[176:177], v[110:111] op_sel:[0,1] op_sel_hi:[1,0] neg_hi:[0,1]
	v_pk_add_f32 v[184:185], v[176:177], v[110:111] op_sel:[0,1] op_sel_hi:[1,0] neg_lo:[0,1]
	v_pk_add_f32 v[166:167], v[104:105], v[120:121] op_sel:[0,1] op_sel_hi:[1,0] neg_hi:[0,1]
	v_pk_add_f32 v[188:189], v[104:105], v[120:121] op_sel:[0,1] op_sel_hi:[1,0] neg_lo:[0,1]
	v_pk_add_f32 v[168:169], v[112:113], v[128:129]
	v_pk_add_f32 v[186:187], v[112:113], v[128:129] neg_lo:[0,1] neg_hi:[0,1]
	v_pk_add_f32 v[104:105], v[166:167], v[168:169]
	v_pk_add_f32 v[120:121], v[166:167], v[168:169] neg_lo:[0,1] neg_hi:[0,1]
	v_pk_add_f32 v[112:113], v[188:189], v[186:187] op_sel:[0,1] op_sel_hi:[1,0] neg_hi:[0,1]
	v_pk_add_f32 v[128:129], v[188:189], v[186:187] op_sel:[0,1] op_sel_hi:[1,0] neg_lo:[0,1]
	v_pk_add_f32 v[118:119], v[106:107], v[122:123]
	v_pk_add_f32 v[182:183], v[106:107], v[122:123] neg_lo:[0,1] neg_hi:[0,1]
	v_pk_add_f32 v[174:175], v[114:115], v[130:131]
	v_pk_add_f32 v[176:177], v[114:115], v[130:131] neg_lo:[0,1] neg_hi:[0,1]
	v_pk_add_f32 v[106:107], v[118:119], v[174:175]
	v_pk_add_f32 v[122:123], v[118:119], v[174:175] neg_lo:[0,1] neg_hi:[0,1]
	v_pk_add_f32 v[114:115], v[182:183], v[176:177] op_sel:[0,1] op_sel_hi:[1,0] neg_hi:[0,1]
	v_pk_add_f32 v[130:131], v[182:183], v[176:177] op_sel:[0,1] op_sel_hi:[1,0] neg_lo:[0,1]
	ds_write_b64 v3, v[100:101]
	v_pk_mul_f32 v[110:111], v[126:127], v[6:7] op_sel:[1,1] op_sel_hi:[0,1]
	v_pk_fma_f32 v[102:103], v[126:127], v[6:7], v[110:111] op_sel_hi:[1,0,1] neg_lo:[0,0,1]
	ds_write_b64 v3, v[102:103] offset:4224
	v_pk_mul_f32 v[188:189], v[104:105], v[8:9] op_sel:[1,1] op_sel_hi:[0,1]
	v_pk_fma_f32 v[166:167], v[104:105], v[8:9], v[188:189] op_sel_hi:[1,0,1] neg_lo:[0,0,1]
	ds_write_b64 v3, v[166:167] offset:8448
	v_pk_mul_f32 v[186:187], v[106:107], v[10:11] op_sel:[1,1] op_sel_hi:[0,1]
	v_pk_fma_f32 v[168:169], v[106:107], v[10:11], v[186:187] op_sel_hi:[1,0,1] neg_lo:[0,0,1]
	ds_write_b64 v3, v[168:169] offset:12672
	v_pk_mul_f32 v[182:183], v[108:109], v[12:13] op_sel:[1,1] op_sel_hi:[0,1]
	v_pk_fma_f32 v[118:119], v[108:109], v[12:13], v[182:183] op_sel_hi:[1,0,1] neg_lo:[0,0,1]
; #define LAS __attribute__((address_space(3)))
; __device__ __forceinline__ f32x2 cmul(f32x2 a, f32x2 b) { return (f32x2){a.x * b.x - a.y * b.y, a.x * b.y + a.y * b.x}; }
; template <bool LO> __device__ __forceinline__ void fft_fwd1(f32x2 (&x)[16], LAS f32x2* B, int n2, const f32x2 (&w)[16]) {
;     asm volatile("" : "+v"(n2));
;     if (LO) dft16_fwd_lo(x); else dft16<false>(x);
;     B[fpad(n2)] = x[0];
; #pragma unroll
;     for (int k = 1; k < 16; ++k) B[fpad(512 * k + n2)] = cmul(x[k], w[k]);
; }
; __device__ __forceinline__ void fft_fwd2(LAS f32x2* B, const LAS f32x2* TW2, int tid) {
;     asm volatile("" : "+v"(tid));
;     const int b = tid >> 5, n2 = tid & 31, base = 512 * b + n2; f32x2 x[16];
; #pragma unroll
;     for (int r = 0; r < 16; ++r) x[r] = B[fpad(base + 32 * r)];
;     dft16<false>(x);
;     B[fpad(base)] = x[0];
; #pragma unroll
;     for (int k = 1; k < 16; ++k) B[fpad(base + 32 * k)] = cmul(x[k], TW2[k * 32 + n2]);
; }
	ds_write_b64 v3, v[118:119] offset:16896
	v_pk_mul_f32 v[176:177], v[180:181], v[14:15] op_sel:[1,1] op_sel_hi:[0,1]
	v_pk_fma_f32 v[174:175], v[180:181], v[14:15], v[176:177] op_sel_hi:[1,0,1] neg_lo:[0,0,1]
	ds_write_b64 v3, v[174:175] offset:21120
	v_pk_mul_f32 v[102:103], v[112:113], v[16:17] op_sel:[1,1] op_sel_hi:[0,1]
	v_pk_fma_f32 v[110:111], v[112:113], v[16:17], v[102:103] op_sel_hi:[1,0,1] neg_lo:[0,0,1]
	ds_write_b64 v3, v[110:111] offset:25344
	v_pk_mul_f32 v[166:167], v[114:115], v[18:19] op_sel:[1,1] op_sel_hi:[0,1]
	v_pk_fma_f32 v[188:189], v[114:115], v[18:19], v[166:167] op_sel_hi:[1,0,1] neg_lo:[0,0,1]
	ds_write_b64 v3, v[188:189] offset:29568
	v_pk_mul_f32 v[168:169], v[116:117], v[20:21] op_sel:[1,1] op_sel_hi:[0,1]
	v_pk_fma_f32 v[186:187], v[116:117], v[20:21], v[168:169] op_sel_hi:[1,0,1] neg_lo:[0,0,1]
	ds_write_b64 v3, v[186:187] offset:33792
	v_pk_mul_f32 v[118:119], v[178:179], v[22:23] op_sel:[1,1] op_sel_hi:[0,1]
	v_pk_fma_f32 v[182:183], v[178:179], v[22:23], v[118:119] op_sel_hi:[1,0,1] neg_lo:[0,0,1]
	ds_write_b64 v3, v[182:183] offset:38016
	v_pk_mul_f32 v[174:175], v[120:121], v[24:25] op_sel:[1,1] op_sel_hi:[0,1]
	v_pk_fma_f32 v[176:177], v[120:121], v[24:25], v[174:175] op_sel_hi:[1,0,1] neg_lo:[0,0,1]
	ds_write_b64 v3, v[176:177] offset:42240
	v_pk_mul_f32 v[110:111], v[122:123], v[26:27] op_sel:[1,1] op_sel_hi:[0,1]
	v_pk_fma_f32 v[102:103], v[122:123], v[26:27], v[110:111] op_sel_hi:[1,0,1] neg_lo:[0,0,1]
	ds_write_b64 v3, v[102:103] offset:46464
	v_pk_mul_f32 v[188:189], v[124:125], v[28:29] op_sel:[1,1] op_sel_hi:[0,1]
	v_pk_fma_f32 v[166:167], v[124:125], v[28:29], v[188:189] op_sel_hi:[1,0,1] neg_lo:[0,0,1]
	ds_write_b64 v3, v[166:167] offset:50688
	v_pk_mul_f32 v[186:187], v[184:185], v[30:31] op_sel:[1,1] op_sel_hi:[0,1]
	v_pk_fma_f32 v[168:169], v[184:185], v[30:31], v[186:187] op_sel_hi:[1,0,1] neg_lo:[0,0,1]
	ds_write_b64 v3, v[168:169] offset:54912
	v_pk_mul_f32 v[182:183], v[128:129], v[32:33] op_sel:[1,1] op_sel_hi:[0,1]
	v_pk_fma_f32 v[118:119], v[128:129], v[32:33], v[182:183] op_sel_hi:[1,0,1] neg_lo:[0,0,1]
	ds_write_b64 v3, v[118:119] offset:59136
	v_pk_mul_f32 v[176:177], v[130:131], v[34:35] op_sel:[1,1] op_sel_hi:[0,1]
	v_pk_fma_f32 v[174:175], v[130:131], v[34:35], v[176:177] op_sel_hi:[1,0,1] neg_lo:[0,0,1]
	ds_write_b64 v3, v[174:175] offset:63360
	s_waitcnt lgkmcnt(0)
	s_barrier
	ds_read_b64 v[100:101], v5
	ds_read_b64 v[108:109], v5 offset:1056
	ds_read_b64 v[116:117], v5 offset:2112
	ds_read_b64 v[124:125], v5 offset:3168
	ds_read_b64 v[126:127], v5 offset:264
	ds_read_b64 v[180:181], v5 offset:1320
	ds_read_b64 v[178:179], v5 offset:2376
	ds_read_b64 v[184:185], v5 offset:3432
	ds_read_b64 v[104:105], v5 offset:528
	ds_read_b64 v[112:113], v5 offset:1584
	ds_read_b64 v[120:121], v5 offset:2640
	ds_read_b64 v[128:129], v5 offset:3696
	s_waitcnt lgkmcnt(8)
	ds_read_b64 v[106:107], v5 offset:792
	ds_read_b64 v[114:115], v5 offset:1848
	ds_read_b64 v[122:123], v5 offset:2904
	ds_read_b64 v[130:131], v5 offset:3960
	ds_read_b64 v[110:111], v56 offset:256
	ds_read_b64 v[102:103], v56 offset:512
	ds_read_b64 v[188:189], v56 offset:768
	ds_read_b64 v[166:167], v56 offset:1024
	v_pk_add_f32 v[186:187], v[100:101], v[116:117]
	v_pk_add_f32 v[168:169], v[100:101], v[116:117] neg_lo:[0,1] neg_hi:[0,1]
	v_pk_add_f32 v[182:183], v[108:109], v[124:125]
	v_pk_add_f32 v[118:119], v[108:109], v[124:125] neg_lo:[0,1] neg_hi:[0,1]
	v_pk_add_f32 v[100:101], v[186:187], v[182:183]
	v_pk_add_f32 v[116:117], v[186:187], v[182:183] neg_lo:[0,1] neg_hi:[0,1]
	v_pk_add_f32 v[108:109], v[168:169], v[118:119] op_sel:[0,1] op_sel_hi:[1,0] neg_hi:[0,1]
	v_pk_add_f32 v[124:125], v[168:169], v[118:119] op_sel:[0,1] op_sel_hi:[1,0] neg_lo:[0,1]
	s_waitcnt lgkmcnt(13)
	v_pk_add_f32 v[176:177], v[126:127], v[178:179]
	v_pk_add_f32 v[174:175], v[126:127], v[178:179] neg_lo:[0,1] neg_hi:[0,1]
	s_waitcnt lgkmcnt(12)
	v_pk_add_f32 v[186:187], v[180:181], v[184:185]
	v_pk_add_f32 v[168:169], v[180:181], v[184:185] neg_lo:[0,1] neg_hi:[0,1]
	v_pk_add_f32 v[126:127], v[176:177], v[186:187]
	v_pk_add_f32 v[178:179], v[176:177], v[186:187] neg_lo:[0,1] neg_hi:[0,1]
	v_pk_add_f32 v[180:181], v[174:175], v[168:169] op_sel:[0,1] op_sel_hi:[1,0] neg_hi:[0,1]
	v_pk_add_f32 v[184:185], v[174:175], v[168:169] op_sel:[0,1] op_sel_hi:[1,0] neg_lo:[0,1]
	s_waitcnt lgkmcnt(9)
	v_pk_add_f32 v[182:183], v[104:105], v[120:121]
	v_pk_add_f32 v[118:119], v[104:105], v[120:121] neg_lo:[0,1] neg_hi:[0,1]
	s_waitcnt lgkmcnt(8)
	v_pk_add_f32 v[176:177], v[112:113], v[128:129]
	v_pk_add_f32 v[174:175], v[112:113], v[128:129] neg_lo:[0,1] neg_hi:[0,1]
	v_pk_add_f32 v[104:105], v[182:183], v[176:177]
	v_pk_add_f32 v[120:121], v[182:183], v[176:177] neg_lo:[0,1] neg_hi:[0,1]
	v_pk_add_f32 v[112:113], v[118:119], v[174:175] op_sel:[0,1] op_sel_hi:[1,0] neg_hi:[0,1]
	v_pk_add_f32 v[128:129], v[118:119], v[174:175] op_sel:[0,1] op_sel_hi:[1,0] neg_lo:[0,1]
	s_waitcnt lgkmcnt(5)
	v_pk_add_f32 v[186:187], v[106:107], v[122:123]
	v_pk_add_f32 v[168:169], v[106:107], v[122:123] neg_lo:[0,1] neg_hi:[0,1]
	s_waitcnt lgkmcnt(4)
; #define LAS __attribute__((address_space(3)))
; __device__ __forceinline__ f32x2 cmul(f32x2 a, f32x2 b) { return (f32x2){a.x * b.x - a.y * b.y, a.x * b.y + a.y * b.x}; }
; template <bool INV> __device__ __forceinline__ f32x2 cmul_tw(f32x2 a, f32x2 w) { return INV ? cmulc(a, w) : cmul(a, w); }
; template <bool INV> __device__ __forceinline__ void dft16(f32x2 (&x)[16]) {
;     constexpr float C1 = 0.92387953251128674f, S1 = 0.38268343236508977f, C2 = 0.70710678118654752f;
; #pragma unroll
;     for (int b = 0; b < 4; ++b) dft4<INV>(x[b], x[4 + b], x[8 + b], x[12 + b]);
;     const f32x2 w1 = {C1, -S1}, w2 = {C2, -C2}, w3 = {S1, -C1}, w4 = {0.f, -1.f}, w6 = {-C2, -C2}, w9 = {-C1, S1};
;     x[4 * 1 + 1] = cmul_tw<INV>(x[5], w1); x[4 * 1 + 2] = cmul_tw<INV>(x[6], w2); x[4 * 1 + 3] = cmul_tw<INV>(x[7], w3);
;     x[4 * 2 + 1] = cmul_tw<INV>(x[9], w2); x[4 * 2 + 2] = cmul_tw<INV>(x[10], w4); x[4 * 2 + 3] = cmul_tw<INV>(x[11], w6);
;     x[4 * 3 + 1] = cmul_tw<INV>(x[13], w3); x[4 * 3 + 2] = cmul_tw<INV>(x[14], w6); x[4 * 3 + 3] = cmul_tw<INV>(x[15], w9);
; #pragma unroll
;     for (int c = 0; c < 4; ++c) dft4<INV>(x[4 * c], x[4 * c + 1], x[4 * c + 2], x[4 * c + 3]);
;     f32x2 y[16];
; #pragma unroll
;     for (int k = 0; k < 16; ++k) y[k] = x[4 * (k & 3) + (k >> 2)];
; #pragma unroll
;     for (int k = 0; k < 16; ++k) x[k] = y[k];
; __device__ __forceinline__ void fft_fwd2(LAS f32x2* B, const LAS f32x2* TW2, int tid) {
;     asm volatile("" : "+v"(tid));
;     const int b = tid >> 5, n2 = tid & 31, base = 512 * b + n2; f32x2 x[16];
; #pragma unroll
;     for (int r = 0; r < 16; ++r) x[r] = B[fpad(base + 32 * r)];
;     dft16<false>(x);
;     B[fpad(base)] = x[0];
; #pragma unroll
;     for (int k = 1; k < 16; ++k) B[fpad(base + 32 * k)] = cmul(x[k], TW2[k * 32 + n2]);
; }
	v_pk_add_f32 v[182:183], v[114:115], v[130:131]
	v_pk_add_f32 v[118:119], v[114:115], v[130:131] neg_lo:[0,1] neg_hi:[0,1]
	v_pk_add_f32 v[106:107], v[186:187], v[182:183]
	v_pk_add_f32 v[122:123], v[186:187], v[182:183] neg_lo:[0,1] neg_hi:[0,1]
	v_pk_add_f32 v[114:115], v[168:169], v[118:119] op_sel:[0,1] op_sel_hi:[1,0] neg_hi:[0,1]
	v_pk_add_f32 v[130:131], v[168:169], v[118:119] op_sel:[0,1] op_sel_hi:[1,0] neg_lo:[0,1]
	v_pk_mul_f32 v[176:177], v[180:181], s[68:69] op_sel:[1,1] op_sel_hi:[0,1]
	v_pk_fma_f32 v[180:181], v[180:181], s[68:69], v[176:177] op_sel_hi:[1,0,1] neg_lo:[0,0,1]
	v_pk_mul_f32 v[174:175], v[112:113], s[84:85] op_sel:[1,1] op_sel_hi:[0,1]
	v_pk_fma_f32 v[112:113], v[112:113], s[84:85], v[174:175] op_sel_hi:[1,0,1] neg_lo:[0,0,1]
	v_pk_mul_f32 v[186:187], v[114:115], s[88:89] op_sel:[1,1] op_sel_hi:[0,1]
	v_pk_fma_f32 v[114:115], v[114:115], s[88:89], v[186:187] op_sel_hi:[1,0,1] neg_lo:[0,0,1]
	v_pk_mul_f32 v[168:169], v[178:179], s[84:85] op_sel:[1,1] op_sel_hi:[0,1]
	v_pk_fma_f32 v[178:179], v[178:179], s[84:85], v[168:169] op_sel_hi:[1,0,1] neg_lo:[0,0,1]
	v_pk_mul_f32 v[182:183], v[122:123], s[90:91] op_sel:[1,1] op_sel_hi:[0,1]
	v_pk_fma_f32 v[122:123], v[122:123], s[90:91], v[182:183] op_sel_hi:[1,0,1] neg_lo:[0,0,1]
	v_pk_mul_f32 v[118:119], v[184:185], s[88:89] op_sel:[1,1] op_sel_hi:[0,1]
	v_pk_fma_f32 v[184:185], v[184:185], s[88:89], v[118:119] op_sel_hi:[1,0,1] neg_lo:[0,0,1]
	v_pk_mul_f32 v[176:177], v[128:129], s[90:91] op_sel:[1,1] op_sel_hi:[0,1]
	v_pk_fma_f32 v[128:129], v[128:129], s[90:91], v[176:177] op_sel_hi:[1,0,1] neg_lo:[0,0,1]
	v_pk_mul_f32 v[174:175], v[130:131], s[98:99] op_sel:[1,1] op_sel_hi:[0,1]
	v_pk_fma_f32 v[130:131], v[130:131], s[98:99], v[174:175] op_sel_hi:[1,0,1] neg_lo:[0,0,1]
	v_pk_add_f32 v[186:187], v[100:101], v[104:105]
	v_pk_add_f32 v[168:169], v[100:101], v[104:105] neg_lo:[0,1] neg_hi:[0,1]
	v_pk_add_f32 v[182:183], v[126:127], v[106:107]
	v_pk_add_f32 v[118:119], v[126:127], v[106:107] neg_lo:[0,1] neg_hi:[0,1]
	v_pk_add_f32 v[100:101], v[186:187], v[182:183]
	v_pk_add_f32 v[104:105], v[186:187], v[182:183] neg_lo:[0,1] neg_hi:[0,1]
	v_pk_add_f32 v[126:127], v[168:169], v[118:119] op_sel:[0,1] op_sel_hi:[1,0] neg_hi:[0,1]
	v_pk_add_f32 v[106:107], v[168:169], v[118:119] op_sel:[0,1] op_sel_hi:[1,0] neg_lo:[0,1]
	v_pk_add_f32 v[176:177], v[108:109], v[112:113]
	v_pk_add_f32 v[174:175], v[108:109], v[112:113] neg_lo:[0,1] neg_hi:[0,1]
	v_pk_add_f32 v[186:187], v[180:181], v[114:115]
	v_pk_add_f32 v[168:169], v[180:181], v[114:115] neg_lo:[0,1] neg_hi:[0,1]
	v_pk_add_f32 v[108:109], v[176:177], v[186:187]
	v_pk_add_f32 v[112:113], v[176:177], v[186:187] neg_lo:[0,1] neg_hi:[0,1]
	v_pk_add_f32 v[180:181], v[174:175], v[168:169] op_sel:[0,1] op_sel_hi:[1,0] neg_hi:[0,1]
	v_pk_add_f32 v[114:115], v[174:175], v[168:169] op_sel:[0,1] op_sel_hi:[1,0] neg_lo:[0,1]
	v_pk_add_f32 v[182:183], v[116:117], v[120:121] op_sel:[0,1] op_sel_hi:[1,0] neg_hi:[0,1]
	v_pk_add_f32 v[118:119], v[116:117], v[120:121] op_sel:[0,1] op_sel_hi:[1,0] neg_lo:[0,1]
	v_pk_add_f32 v[176:177], v[178:179], v[122:123]
	v_pk_add_f32 v[174:175], v[178:179], v[122:123] neg_lo:[0,1] neg_hi:[0,1]
	v_pk_add_f32 v[116:117], v[182:183], v[176:177]
	v_pk_add_f32 v[120:121], v[182:183], v[176:177] neg_lo:[0,1] neg_hi:[0,1]
	v_pk_add_f32 v[178:179], v[118:119], v[174:175] op_sel:[0,1] op_sel_hi:[1,0] neg_hi:[0,1]
	v_pk_add_f32 v[122:123], v[118:119], v[174:175] op_sel:[0,1] op_sel_hi:[1,0] neg_lo:[0,1]
	v_pk_add_f32 v[186:187], v[124:125], v[128:129]
	v_pk_add_f32 v[168:169], v[124:125], v[128:129] neg_lo:[0,1] neg_hi:[0,1]
	v_pk_add_f32 v[182:183], v[184:185], v[130:131]
	v_pk_add_f32 v[118:119], v[184:185], v[130:131] neg_lo:[0,1] neg_hi:[0,1]
	v_pk_add_f32 v[124:125], v[186:187], v[182:183]
	v_pk_add_f32 v[128:129], v[186:187], v[182:183] neg_lo:[0,1] neg_hi:[0,1]
	v_pk_add_f32 v[184:185], v[168:169], v[118:119] op_sel:[0,1] op_sel_hi:[1,0] neg_hi:[0,1]
	v_pk_add_f32 v[130:131], v[168:169], v[118:119] op_sel:[0,1] op_sel_hi:[1,0] neg_lo:[0,1]
	ds_write_b64 v5, v[100:101]
	ds_read_b64 v[176:177], v56 offset:1280
	ds_read_b64 v[174:175], v56 offset:1536
	ds_read_b64 v[186:187], v56 offset:1792
	ds_read_b64 v[168:169], v56 offset:2048
	s_waitcnt lgkmcnt(8)
	v_pk_mul_f32 v[182:183], v[108:109], v[110:111] op_sel:[1,1] op_sel_hi:[0,1]
	v_pk_fma_f32 v[108:109], v[108:109], v[110:111], v[182:183] op_sel_hi:[1,0,1] neg_lo:[0,0,1]
	ds_write_b64 v5, v[108:109] offset:264
	s_waitcnt lgkmcnt(8)
	v_pk_mul_f32 v[118:119], v[116:117], v[102:103] op_sel:[1,1] op_sel_hi:[0,1]
	v_pk_fma_f32 v[116:117], v[116:117], v[102:103], v[118:119] op_sel_hi:[1,0,1] neg_lo:[0,0,1]
	ds_write_b64 v5, v[116:117] offset:528
	s_waitcnt lgkmcnt(8)
	v_pk_mul_f32 v[182:183], v[124:125], v[188:189] op_sel:[1,1] op_sel_hi:[0,1]
	v_pk_fma_f32 v[124:125], v[124:125], v[188:189], v[182:183] op_sel_hi:[1,0,1] neg_lo:[0,0,1]
	ds_write_b64 v5, v[124:125] offset:792
	s_waitcnt lgkmcnt(8)
	v_pk_mul_f32 v[118:119], v[126:127], v[166:167] op_sel:[1,1] op_sel_hi:[0,1]
	v_pk_fma_f32 v[126:127], v[126:127], v[166:167], v[118:119] op_sel_hi:[1,0,1] neg_lo:[0,0,1]
	ds_write_b64 v5, v[126:127] offset:1056
	ds_read_b64 v[182:183], v56 offset:2304
	ds_read_b64 v[118:119], v56 offset:2560
	ds_read_b64 v[110:111], v56 offset:2816
	ds_read_b64 v[102:103], v56 offset:3072
	s_waitcnt lgkmcnt(11)
	v_pk_mul_f32 v[188:189], v[180:181], v[176:177] op_sel:[1,1] op_sel_hi:[0,1]
	v_pk_fma_f32 v[180:181], v[180:181], v[176:177], v[188:189] op_sel_hi:[1,0,1] neg_lo:[0,0,1]
	ds_write_b64 v5, v[180:181] offset:1320
	s_waitcnt lgkmcnt(11)
; #define LAS __attribute__((address_space(3)))
; __device__ __forceinline__ f32x2 cmul(f32x2 a, f32x2 b) { return (f32x2){a.x * b.x - a.y * b.y, a.x * b.y + a.y * b.x}; }
; __device__ __forceinline__ void fft_fwd2(LAS f32x2* B, const LAS f32x2* TW2, int tid) {
;     ...
;     B[fpad(base)] = x[0];
; #pragma unroll
;     for (int k = 1; k < 16; ++k) B[fpad(base + 32 * k)] = cmul(x[k], TW2[k * 32 + n2]);
; }
; template <int MODE> __device__ __forceinline__ void fft_pair32(LAS f32x2* B, const LAS f32x2* F, int wave, int lane) {
;     asm volatile("" : "+v"(lane));
;     constexpr float CS[16] = {1.f, 0.98078528040323043f, 0.92387953251128674f, 0.83146961230254524f, 0.70710678118654752f, 0.55557023301960218f, 0.38268343236508977f, 0.19509032201612825f,
;                               0.f, -0.19509032201612825f, -0.38268343236508977f, -0.55557023301960218f, -0.70710678118654752f, -0.83146961230254524f, -0.92387953251128674f, -0.98078528040323043f};
;     constexpr float SN[16] = {0.f, 0.19509032201612825f, 0.38268343236508977f, 0.55557023301960218f, 0.70710678118654752f, 0.83146961230254524f, 0.92387953251128674f, 0.98078528040323043f,
;                               1.f, 0.98078528040323043f, 0.92387953251128674f, 0.83146961230254524f, 0.70710678118654752f, 0.55557023301960218f, 0.38268343236508977f, 0.19509032201612825f};
;     const int hi = lane >> 5, blk = 32 * wave + (lane & 31); const float sg = hi ? -1.f : 1.f;
;     LAS f32x2* p = B + 33 * blk; f32x2 v[16];
; #pragma unroll
;     for (int j = 0; j < 16; ++j) { const f32x2 d = p[j] + p[j + 16] * sg;
;         const f32x2 w = {hi ? CS[j] : 1.f, hi ? -SN[j] : 0.f}; v[j] = j == 0 ? d : cmul(d, w); }
;     dft16<false>(v);
	v_pk_mul_f32 v[166:167], v[178:179], v[174:175] op_sel:[1,1] op_sel_hi:[0,1]
	v_pk_fma_f32 v[178:179], v[178:179], v[174:175], v[166:167] op_sel_hi:[1,0,1] neg_lo:[0,0,1]
	ds_write_b64 v5, v[178:179] offset:1584
	s_waitcnt lgkmcnt(11)
	v_pk_mul_f32 v[188:189], v[184:185], v[186:187] op_sel:[1,1] op_sel_hi:[0,1]
	v_pk_fma_f32 v[184:185], v[184:185], v[186:187], v[188:189] op_sel_hi:[1,0,1] neg_lo:[0,0,1]
	ds_write_b64 v5, v[184:185] offset:1848
	s_waitcnt lgkmcnt(11)
	v_pk_mul_f32 v[166:167], v[104:105], v[168:169] op_sel:[1,1] op_sel_hi:[0,1]
	v_pk_fma_f32 v[104:105], v[104:105], v[168:169], v[166:167] op_sel_hi:[1,0,1] neg_lo:[0,0,1]
	ds_write_b64 v5, v[104:105] offset:2112
	ds_read_b64 v[188:189], v56 offset:3328
	ds_read_b64 v[166:167], v56 offset:3584
	ds_read_b64 v[176:177], v56 offset:3840
	s_waitcnt lgkmcnt(10)
	v_pk_mul_f32 v[174:175], v[112:113], v[182:183] op_sel:[1,1] op_sel_hi:[0,1]
	v_pk_fma_f32 v[112:113], v[112:113], v[182:183], v[174:175] op_sel_hi:[1,0,1] neg_lo:[0,0,1]
	ds_write_b64 v5, v[112:113] offset:2376
	s_waitcnt lgkmcnt(10)
	v_pk_mul_f32 v[186:187], v[120:121], v[118:119] op_sel:[1,1] op_sel_hi:[0,1]
	v_pk_fma_f32 v[120:121], v[120:121], v[118:119], v[186:187] op_sel_hi:[1,0,1] neg_lo:[0,0,1]
	ds_write_b64 v5, v[120:121] offset:2640
	s_waitcnt lgkmcnt(10)
	v_pk_mul_f32 v[168:169], v[128:129], v[110:111] op_sel:[1,1] op_sel_hi:[0,1]
	v_pk_fma_f32 v[128:129], v[128:129], v[110:111], v[168:169] op_sel_hi:[1,0,1] neg_lo:[0,0,1]
	ds_write_b64 v5, v[128:129] offset:2904
	s_waitcnt lgkmcnt(10)
	v_pk_mul_f32 v[174:175], v[106:107], v[102:103] op_sel:[1,1] op_sel_hi:[0,1]
	v_pk_fma_f32 v[106:107], v[106:107], v[102:103], v[174:175] op_sel_hi:[1,0,1] neg_lo:[0,0,1]
	ds_write_b64 v5, v[106:107] offset:3168
	s_waitcnt lgkmcnt(6)
	v_pk_mul_f32 v[186:187], v[114:115], v[188:189] op_sel:[1,1] op_sel_hi:[0,1]
	v_pk_fma_f32 v[114:115], v[114:115], v[188:189], v[186:187] op_sel_hi:[1,0,1] neg_lo:[0,0,1]
	ds_write_b64 v5, v[114:115] offset:3432
	s_waitcnt lgkmcnt(6)
	v_pk_mul_f32 v[168:169], v[122:123], v[166:167] op_sel:[1,1] op_sel_hi:[0,1]
	v_pk_fma_f32 v[122:123], v[122:123], v[166:167], v[168:169] op_sel_hi:[1,0,1] neg_lo:[0,0,1]
	ds_write_b64 v5, v[122:123] offset:3696
	s_waitcnt lgkmcnt(6)
	v_pk_mul_f32 v[174:175], v[130:131], v[176:177] op_sel:[1,1] op_sel_hi:[0,1]
	v_pk_fma_f32 v[130:131], v[130:131], v[176:177], v[174:175] op_sel_hi:[1,0,1] neg_lo:[0,0,1]
	ds_write_b64 v5, v[130:131] offset:3960
	s_waitcnt lgkmcnt(0)
	ds_read_b64 v[100:101], v156
	ds_read_b64 v[182:183], v156 offset:128
	ds_read_b64 v[108:109], v156 offset:8
	ds_read_b64 v[118:119], v156 offset:136
	ds_read_b64 v[116:117], v156 offset:16
	ds_read_b64 v[110:111], v156 offset:144
	ds_read_b64 v[124:125], v156 offset:24
	ds_read_b64 v[102:103], v156 offset:152
	ds_read_b64 v[126:127], v156 offset:32
	ds_read_b64 v[186:187], v156 offset:160
	ds_read_b64 v[180:181], v156 offset:40
	ds_read_b64 v[168:169], v156 offset:168
	ds_read_b64 v[178:179], v156 offset:48
	ds_read_b64 v[174:175], v156 offset:176
	ds_read_b64 v[184:185], v156 offset:56
	ds_read_b64 v[188:189], v156 offset:184
	s_waitcnt lgkmcnt(14)
	v_pk_fma_f32 v[100:101], v[182:183], v[190:191], v[100:101] op_sel_hi:[1,0,1]
	s_waitcnt lgkmcnt(12)
	v_pk_fma_f32 v[108:109], v[118:119], v[190:191], v[108:109] op_sel_hi:[1,0,1]
	v_pk_mul_f32 v[166:167], v[108:109], v[36:37] op_sel:[1,1] op_sel_hi:[0,1]
	v_pk_fma_f32 v[108:109], v[108:109], v[36:37], v[166:167] op_sel_hi:[1,0,1] neg_lo:[0,0,1]
	s_waitcnt lgkmcnt(10)
	v_pk_fma_f32 v[116:117], v[110:111], v[190:191], v[116:117] op_sel_hi:[1,0,1]
	v_pk_mul_f32 v[176:177], v[116:117], v[38:39] op_sel:[1,1] op_sel_hi:[0,1]
	v_pk_fma_f32 v[116:117], v[116:117], v[38:39], v[176:177] op_sel_hi:[1,0,1] neg_lo:[0,0,1]
	s_waitcnt lgkmcnt(8)
	v_pk_fma_f32 v[124:125], v[102:103], v[190:191], v[124:125] op_sel_hi:[1,0,1]
	v_pk_mul_f32 v[166:167], v[124:125], v[40:41] op_sel:[1,1] op_sel_hi:[0,1]
	v_pk_fma_f32 v[124:125], v[124:125], v[40:41], v[166:167] op_sel_hi:[1,0,1] neg_lo:[0,0,1]
	ds_read_b64 v[104:105], v156 offset:64
	ds_read_b64 v[176:177], v156 offset:192
	ds_read_b64 v[112:113], v156 offset:72
	ds_read_b64 v[166:167], v156 offset:200
	ds_read_b64 v[120:121], v156 offset:80
	ds_read_b64 v[182:183], v156 offset:208
	ds_read_b64 v[128:129], v156 offset:88
	ds_read_b64 v[118:119], v156 offset:216
	s_waitcnt lgkmcnt(14)
	v_pk_fma_f32 v[126:127], v[186:187], v[190:191], v[126:127] op_sel_hi:[1,0,1]
	v_pk_mul_f32 v[110:111], v[126:127], v[42:43] op_sel:[1,1] op_sel_hi:[0,1]
	v_pk_fma_f32 v[126:127], v[126:127], v[42:43], v[110:111] op_sel_hi:[1,0,1] neg_lo:[0,0,1]
	s_waitcnt lgkmcnt(12)
	v_pk_fma_f32 v[180:181], v[168:169], v[190:191], v[180:181] op_sel_hi:[1,0,1]
	v_pk_mul_f32 v[102:103], v[180:181], v[44:45] op_sel:[1,1] op_sel_hi:[0,1]
	v_pk_fma_f32 v[180:181], v[180:181], v[44:45], v[102:103] op_sel_hi:[1,0,1] neg_lo:[0,0,1]
	s_waitcnt lgkmcnt(10)
	v_pk_fma_f32 v[178:179], v[174:175], v[190:191], v[178:179] op_sel_hi:[1,0,1]
	v_pk_mul_f32 v[110:111], v[178:179], v[46:47] op_sel:[1,1] op_sel_hi:[0,1]
	v_pk_fma_f32 v[178:179], v[178:179], v[46:47], v[110:111] op_sel_hi:[1,0,1] neg_lo:[0,0,1]
	s_waitcnt lgkmcnt(8)
	v_pk_fma_f32 v[184:185], v[188:189], v[190:191], v[184:185] op_sel_hi:[1,0,1]
	v_pk_mul_f32 v[102:103], v[184:185], v[48:49] op_sel:[1,1] op_sel_hi:[0,1]
	v_pk_fma_f32 v[184:185], v[184:185], v[48:49], v[102:103] op_sel_hi:[1,0,1] neg_lo:[0,0,1]
	ds_read_b64 v[106:107], v156 offset:96
	ds_read_b64 v[110:111], v156 offset:224
	ds_read_b64 v[114:115], v156 offset:104
	ds_read_b64 v[102:103], v156 offset:232
	ds_read_b64 v[122:123], v156 offset:112
	ds_read_b64 v[186:187], v156 offset:240
	ds_read_b64 v[130:131], v156 offset:120
	ds_read_b64 v[168:169], v156 offset:248
	s_waitcnt lgkmcnt(14)
; __device__ __forceinline__ f32x2 cmul(f32x2 a, f32x2 b) { return (f32x2){a.x * b.x - a.y * b.y, a.x * b.y + a.y * b.x}; }
; template <bool INV> __device__ __forceinline__ f32x2 cmul_tw(f32x2 a, f32x2 w) { return INV ? cmulc(a, w) : cmul(a, w); }
; template <bool INV> __device__ __forceinline__ void dft16(f32x2 (&x)[16]) {
;     constexpr float C1 = 0.92387953251128674f, S1 = 0.38268343236508977f, C2 = 0.70710678118654752f;
; #pragma unroll
;     for (int b = 0; b < 4; ++b) dft4<INV>(x[b], x[4 + b], x[8 + b], x[12 + b]);
;     const f32x2 w1 = {C1, -S1}, w2 = {C2, -C2}, w3 = {S1, -C1}, w4 = {0.f, -1.f}, w6 = {-C2, -C2}, w9 = {-C1, S1};
;     x[4 * 1 + 1] = cmul_tw<INV>(x[5], w1); x[4 * 1 + 2] = cmul_tw<INV>(x[6], w2); x[4 * 1 + 3] = cmul_tw<INV>(x[7], w3);
;     x[4 * 2 + 1] = cmul_tw<INV>(x[9], w2); x[4 * 2 + 2] = cmul_tw<INV>(x[10], w4); x[4 * 2 + 3] = cmul_tw<INV>(x[11], w6);
;     x[4 * 3 + 1] = cmul_tw<INV>(x[13], w3); x[4 * 3 + 2] = cmul_tw<INV>(x[14], w6); x[4 * 3 + 3] = cmul_tw<INV>(x[15], w9);
; #pragma unroll
;     for (int c = 0; c < 4; ++c) dft4<INV>(x[4 * c], x[4 * c + 1], x[4 * c + 2], x[4 * c + 3]);
;     f32x2 y[16];
; #pragma unroll
;     for (int k = 0; k < 16; ++k) y[k] = x[4 * (k & 3) + (k >> 2)];
; #pragma unroll
;     for (int k = 0; k < 16; ++k) x[k] = y[k];
; template <int MODE> __device__ __forceinline__ void fft_pair32(LAS f32x2* B, const LAS f32x2* F, int wave, int lane) {
;     ...
;     for (int j = 0; j < 16; ++j) { const f32x2 d = p[j] + p[j + 16] * sg;
;         const f32x2 w = {hi ? CS[j] : 1.f, hi ? -SN[j] : 0.f}; v[j] = j == 0 ? d : cmul(d, w); }
;     dft16<false>(v);
	v_pk_fma_f32 v[104:105], v[176:177], v[190:191], v[104:105] op_sel_hi:[1,0,1]
	v_pk_mul_f32 v[174:175], v[104:105], v[50:51] op_sel:[1,1] op_sel_hi:[0,1]
	v_pk_fma_f32 v[104:105], v[104:105], v[50:51], v[174:175] op_sel_hi:[1,0,1] neg_lo:[0,0,1]
	s_waitcnt lgkmcnt(12)
	v_pk_fma_f32 v[112:113], v[166:167], v[190:191], v[112:113] op_sel_hi:[1,0,1]
	v_pk_mul_f32 v[188:189], v[112:113], v[52:53] op_sel:[1,1] op_sel_hi:[0,1]
	v_pk_fma_f32 v[112:113], v[112:113], v[52:53], v[188:189] op_sel_hi:[1,0,1] neg_lo:[0,0,1]
	s_waitcnt lgkmcnt(10)
	v_pk_fma_f32 v[120:121], v[182:183], v[190:191], v[120:121] op_sel_hi:[1,0,1]
	v_pk_mul_f32 v[174:175], v[120:121], v[54:55] op_sel:[1,1] op_sel_hi:[0,1]
	v_pk_fma_f32 v[120:121], v[120:121], v[54:55], v[174:175] op_sel_hi:[1,0,1] neg_lo:[0,0,1]
	s_waitcnt lgkmcnt(8)
	v_pk_fma_f32 v[128:129], v[118:119], v[190:191], v[128:129] op_sel_hi:[1,0,1]
	v_pk_mul_f32 v[188:189], v[128:129], v[90:91] op_sel:[1,1] op_sel_hi:[0,1]
	v_pk_fma_f32 v[128:129], v[128:129], v[90:91], v[188:189] op_sel_hi:[1,0,1] neg_lo:[0,0,1]
	s_waitcnt lgkmcnt(6)
	v_pk_fma_f32 v[106:107], v[110:111], v[190:191], v[106:107] op_sel_hi:[1,0,1]
	v_pk_mul_f32 v[174:175], v[106:107], v[92:93] op_sel:[1,1] op_sel_hi:[0,1]
	v_pk_fma_f32 v[106:107], v[106:107], v[92:93], v[174:175] op_sel_hi:[1,0,1] neg_lo:[0,0,1]
	s_waitcnt lgkmcnt(4)
	v_pk_fma_f32 v[114:115], v[102:103], v[190:191], v[114:115] op_sel_hi:[1,0,1]
	v_pk_mul_f32 v[188:189], v[114:115], v[94:95] op_sel:[1,1] op_sel_hi:[0,1]
	v_pk_fma_f32 v[114:115], v[114:115], v[94:95], v[188:189] op_sel_hi:[1,0,1] neg_lo:[0,0,1]
	s_waitcnt lgkmcnt(2)
	v_pk_fma_f32 v[122:123], v[186:187], v[190:191], v[122:123] op_sel_hi:[1,0,1]
	v_pk_mul_f32 v[176:177], v[122:123], v[96:97] op_sel:[1,1] op_sel_hi:[0,1]
	v_pk_fma_f32 v[122:123], v[122:123], v[96:97], v[176:177] op_sel_hi:[1,0,1] neg_lo:[0,0,1]
	s_waitcnt lgkmcnt(0)
	v_pk_fma_f32 v[130:131], v[168:169], v[190:191], v[130:131] op_sel_hi:[1,0,1]
	v_pk_mul_f32 v[166:167], v[130:131], v[98:99] op_sel:[1,1] op_sel_hi:[0,1]
	v_pk_fma_f32 v[130:131], v[130:131], v[98:99], v[166:167] op_sel_hi:[1,0,1] neg_lo:[0,0,1]
	v_pk_add_f32 v[182:183], v[100:101], v[104:105]
	v_pk_add_f32 v[118:119], v[100:101], v[104:105] neg_lo:[0,1] neg_hi:[0,1]
	v_pk_add_f32 v[174:175], v[126:127], v[106:107]
	v_pk_add_f32 v[188:189], v[126:127], v[106:107] neg_lo:[0,1] neg_hi:[0,1]
	v_pk_add_f32 v[100:101], v[182:183], v[174:175]
	v_pk_add_f32 v[104:105], v[182:183], v[174:175] neg_lo:[0,1] neg_hi:[0,1]
	v_pk_add_f32 v[126:127], v[118:119], v[188:189] op_sel:[0,1] op_sel_hi:[1,0] neg_hi:[0,1]
	v_pk_add_f32 v[106:107], v[118:119], v[188:189] op_sel:[0,1] op_sel_hi:[1,0] neg_lo:[0,1]
	v_pk_add_f32 v[176:177], v[108:109], v[112:113]
	v_pk_add_f32 v[166:167], v[108:109], v[112:113] neg_lo:[0,1] neg_hi:[0,1]
	v_pk_add_f32 v[110:111], v[180:181], v[114:115]
	v_pk_add_f32 v[102:103], v[180:181], v[114:115] neg_lo:[0,1] neg_hi:[0,1]
	v_pk_add_f32 v[108:109], v[176:177], v[110:111]
	v_pk_add_f32 v[112:113], v[176:177], v[110:111] neg_lo:[0,1] neg_hi:[0,1]
	v_pk_add_f32 v[180:181], v[166:167], v[102:103] op_sel:[0,1] op_sel_hi:[1,0] neg_hi:[0,1]
	v_pk_add_f32 v[114:115], v[166:167], v[102:103] op_sel:[0,1] op_sel_hi:[1,0] neg_lo:[0,1]
	v_pk_add_f32 v[186:187], v[116:117], v[120:121]
	v_pk_add_f32 v[168:169], v[116:117], v[120:121] neg_lo:[0,1] neg_hi:[0,1]
	v_pk_add_f32 v[182:183], v[178:179], v[122:123]
	v_pk_add_f32 v[118:119], v[178:179], v[122:123] neg_lo:[0,1] neg_hi:[0,1]
	v_pk_add_f32 v[116:117], v[186:187], v[182:183]
	v_pk_add_f32 v[120:121], v[186:187], v[182:183] neg_lo:[0,1] neg_hi:[0,1]
	v_pk_add_f32 v[178:179], v[168:169], v[118:119] op_sel:[0,1] op_sel_hi:[1,0] neg_hi:[0,1]
	v_pk_add_f32 v[122:123], v[168:169], v[118:119] op_sel:[0,1] op_sel_hi:[1,0] neg_lo:[0,1]
	v_pk_add_f32 v[174:175], v[124:125], v[128:129]
	v_pk_add_f32 v[188:189], v[124:125], v[128:129] neg_lo:[0,1] neg_hi:[0,1]
	v_pk_add_f32 v[176:177], v[184:185], v[130:131]
	v_pk_add_f32 v[166:167], v[184:185], v[130:131] neg_lo:[0,1] neg_hi:[0,1]
	v_pk_add_f32 v[124:125], v[174:175], v[176:177]
	v_pk_add_f32 v[128:129], v[174:175], v[176:177] neg_lo:[0,1] neg_hi:[0,1]
	v_pk_add_f32 v[184:185], v[188:189], v[166:167] op_sel:[0,1] op_sel_hi:[1,0] neg_hi:[0,1]
	v_pk_add_f32 v[130:131], v[188:189], v[166:167] op_sel:[0,1] op_sel_hi:[1,0] neg_lo:[0,1]
	v_pk_mul_f32 v[110:111], v[180:181], s[68:69] op_sel:[1,1] op_sel_hi:[0,1]
	v_pk_fma_f32 v[180:181], v[180:181], s[68:69], v[110:111] op_sel_hi:[1,0,1] neg_lo:[0,0,1]
	v_pk_mul_f32 v[102:103], v[178:179], s[84:85] op_sel:[1,1] op_sel_hi:[0,1]
	v_pk_fma_f32 v[178:179], v[178:179], s[84:85], v[102:103] op_sel_hi:[1,0,1] neg_lo:[0,0,1]
	v_pk_mul_f32 v[186:187], v[184:185], s[88:89] op_sel:[1,1] op_sel_hi:[0,1]
	v_pk_fma_f32 v[184:185], v[184:185], s[88:89], v[186:187] op_sel_hi:[1,0,1] neg_lo:[0,0,1]
	v_pk_mul_f32 v[168:169], v[112:113], s[84:85] op_sel:[1,1] op_sel_hi:[0,1]
	v_pk_fma_f32 v[112:113], v[112:113], s[84:85], v[168:169] op_sel_hi:[1,0,1] neg_lo:[0,0,1]
	v_pk_mul_f32 v[182:183], v[128:129], s[90:91] op_sel:[1,1] op_sel_hi:[0,1]
	v_pk_fma_f32 v[128:129], v[128:129], s[90:91], v[182:183] op_sel_hi:[1,0,1] neg_lo:[0,0,1]
	v_pk_mul_f32 v[118:119], v[114:115], s[88:89] op_sel:[1,1] op_sel_hi:[0,1]
	v_pk_fma_f32 v[114:115], v[114:115], s[88:89], v[118:119] op_sel_hi:[1,0,1] neg_lo:[0,0,1]
	v_pk_mul_f32 v[174:175], v[122:123], s[90:91] op_sel:[1,1] op_sel_hi:[0,1]
	v_pk_fma_f32 v[122:123], v[122:123], s[90:91], v[174:175] op_sel_hi:[1,0,1] neg_lo:[0,0,1]
	v_pk_mul_f32 v[188:189], v[130:131], s[98:99] op_sel:[1,1] op_sel_hi:[0,1]
; #define LAS __attribute__((address_space(3)))
; __device__ __forceinline__ f32x2 cmul(f32x2 a, f32x2 b) { return (f32x2){a.x * b.x - a.y * b.y, a.x * b.y + a.y * b.x}; }
; template <bool INV> __device__ __forceinline__ f32x2 cmul_tw(f32x2 a, f32x2 w) { return INV ? cmulc(a, w) : cmul(a, w); }
; template <bool INV> __device__ __forceinline__ void dft16(f32x2 (&x)[16]) {
;     constexpr float C1 = 0.92387953251128674f, S1 = 0.38268343236508977f, C2 = 0.70710678118654752f;
; #pragma unroll
;     for (int b = 0; b < 4; ++b) dft4<INV>(x[b], x[4 + b], x[8 + b], x[12 + b]);
;     const f32x2 w1 = {C1, -S1}, w2 = {C2, -C2}, w3 = {S1, -C1}, w4 = {0.f, -1.f}, w6 = {-C2, -C2}, w9 = {-C1, S1};
;     x[4 * 1 + 1] = cmul_tw<INV>(x[5], w1); x[4 * 1 + 2] = cmul_tw<INV>(x[6], w2); x[4 * 1 + 3] = cmul_tw<INV>(x[7], w3);
;     x[4 * 2 + 1] = cmul_tw<INV>(x[9], w2); x[4 * 2 + 2] = cmul_tw<INV>(x[10], w4); x[4 * 2 + 3] = cmul_tw<INV>(x[11], w6);
;     x[4 * 3 + 1] = cmul_tw<INV>(x[13], w3); x[4 * 3 + 2] = cmul_tw<INV>(x[14], w6); x[4 * 3 + 3] = cmul_tw<INV>(x[15], w9);
; #pragma unroll
;     for (int c = 0; c < 4; ++c) dft4<INV>(x[4 * c], x[4 * c + 1], x[4 * c + 2], x[4 * c + 3]);
;     f32x2 y[16];
; #pragma unroll
;     for (int k = 0; k < 16; ++k) y[k] = x[4 * (k & 3) + (k >> 2)];
; #pragma unroll
;     for (int k = 0; k < 16; ++k) x[k] = y[k];
; template <int MODE> __device__ __forceinline__ void fft_pair32(LAS f32x2* B, const LAS f32x2* F, int wave, int lane) {
;     ...
;     const int k1 = blk >> 4, k2 = blk & 15, kb1 = (16 - k1) & 15, b1 = k1 != 0 ? 1 : 0, kb2 = (16 - k2 - b1) & 15, b2 = (k2 != 0 || b1) ? 1 : 0;
;     const LAS f32x2* fa = F + 33 * blk; const LAS f32x2* fb = F + 33 * (16 * kb1 + kb2);
;     const LAS f32x2* fah = fa + hi; const LAS f32x2* fbh = fb + (1 - b2) - hi;
;     constexpr float SC = 1.0f / (2.0f * (float)FN);
; #pragma unroll
;     for (int k = 0; k < 16; ++k) { const f32x2 A = fah[2 * k]; f32x2 Bm = fbh[31 - 2 * k];
;         if (k == 0) { const f32x2 m0 = b2 ? fb[31] : fa[0]; Bm = hi ? Bm : m0; }
;         const f32x2 H = MODE == 0 ? (f32x2){(A.x + Bm.x) * SC, (A.y - Bm.y) * SC} : (f32x2){(A.y + Bm.y) * SC, (Bm.x - A.x) * SC};
;         v[k] = cmul(v[k], H); }
	v_pk_fma_f32 v[130:131], v[130:131], s[98:99], v[188:189] op_sel_hi:[1,0,1] neg_lo:[0,0,1]
	v_pk_add_f32 v[176:177], v[100:101], v[116:117]
	v_pk_add_f32 v[166:167], v[100:101], v[116:117] neg_lo:[0,1] neg_hi:[0,1]
	v_pk_add_f32 v[110:111], v[108:109], v[124:125]
	v_pk_add_f32 v[102:103], v[108:109], v[124:125] neg_lo:[0,1] neg_hi:[0,1]
	v_pk_add_f32 v[100:101], v[176:177], v[110:111]
	v_pk_add_f32 v[116:117], v[176:177], v[110:111] neg_lo:[0,1] neg_hi:[0,1]
	v_pk_add_f32 v[108:109], v[166:167], v[102:103] op_sel:[0,1] op_sel_hi:[1,0] neg_hi:[0,1]
	v_pk_add_f32 v[124:125], v[166:167], v[102:103] op_sel:[0,1] op_sel_hi:[1,0] neg_lo:[0,1]
	v_pk_add_f32 v[186:187], v[126:127], v[178:179]
	v_pk_add_f32 v[168:169], v[126:127], v[178:179] neg_lo:[0,1] neg_hi:[0,1]
	v_pk_add_f32 v[182:183], v[180:181], v[184:185]
	v_pk_add_f32 v[118:119], v[180:181], v[184:185] neg_lo:[0,1] neg_hi:[0,1]
	v_pk_add_f32 v[126:127], v[186:187], v[182:183]
	v_pk_add_f32 v[178:179], v[186:187], v[182:183] neg_lo:[0,1] neg_hi:[0,1]
	v_pk_add_f32 v[180:181], v[168:169], v[118:119] op_sel:[0,1] op_sel_hi:[1,0] neg_hi:[0,1]
	v_pk_add_f32 v[184:185], v[168:169], v[118:119] op_sel:[0,1] op_sel_hi:[1,0] neg_lo:[0,1]
	v_pk_add_f32 v[174:175], v[104:105], v[120:121] op_sel:[0,1] op_sel_hi:[1,0] neg_hi:[0,1]
	v_pk_add_f32 v[188:189], v[104:105], v[120:121] op_sel:[0,1] op_sel_hi:[1,0] neg_lo:[0,1]
	v_pk_add_f32 v[176:177], v[112:113], v[128:129]
	v_pk_add_f32 v[166:167], v[112:113], v[128:129] neg_lo:[0,1] neg_hi:[0,1]
	v_pk_add_f32 v[104:105], v[174:175], v[176:177]
	v_pk_add_f32 v[120:121], v[174:175], v[176:177] neg_lo:[0,1] neg_hi:[0,1]
	v_pk_add_f32 v[112:113], v[188:189], v[166:167] op_sel:[0,1] op_sel_hi:[1,0] neg_hi:[0,1]
	v_pk_add_f32 v[128:129], v[188:189], v[166:167] op_sel:[0,1] op_sel_hi:[1,0] neg_lo:[0,1]
	v_pk_add_f32 v[110:111], v[106:107], v[122:123]
	v_pk_add_f32 v[102:103], v[106:107], v[122:123] neg_lo:[0,1] neg_hi:[0,1]
	v_pk_add_f32 v[186:187], v[114:115], v[130:131]
	v_pk_add_f32 v[168:169], v[114:115], v[130:131] neg_lo:[0,1] neg_hi:[0,1]
	v_pk_add_f32 v[106:107], v[110:111], v[186:187]
	v_pk_add_f32 v[122:123], v[110:111], v[186:187] neg_lo:[0,1] neg_hi:[0,1]
	v_pk_add_f32 v[114:115], v[102:103], v[168:169] op_sel:[0,1] op_sel_hi:[1,0] neg_hi:[0,1]
	v_pk_add_f32 v[130:131], v[102:103], v[168:169] op_sel:[0,1] op_sel_hi:[1,0] neg_lo:[0,1]
	ds_read_b64 v[182:183], v200
	ds_read_b64 v[174:175], v204
	ds_read_b64 v[118:119], v200 offset:16
	ds_read_b64 v[188:189], v202 offset:232
	ds_read_b64 v[176:177], v200 offset:32
	ds_read_b64 v[110:111], v202 offset:216
	ds_read_b64 v[166:167], v200 offset:48
	ds_read_b64 v[102:103], v202 offset:200
	s_waitcnt lgkmcnt(6)
	v_pk_add_f32 v[182:183], v[182:183], v[174:175] op_sel:[1,1] op_sel_hi:[0,0] neg_hi:[1,0]
	v_pk_mul_f32 v[186:187], v[100:101], v[182:183] op_sel:[1,1] op_sel_hi:[0,1]
	v_pk_fma_f32 v[100:101], v[100:101], v[182:183], v[186:187] op_sel_hi:[1,0,1] neg_lo:[0,0,1]
	s_waitcnt lgkmcnt(4)
	v_pk_add_f32 v[118:119], v[118:119], v[188:189] op_sel:[1,1] op_sel_hi:[0,0] neg_hi:[1,0]
	v_pk_mul_f32 v[168:169], v[126:127], v[118:119] op_sel:[1,1] op_sel_hi:[0,1]
	v_pk_fma_f32 v[126:127], v[126:127], v[118:119], v[168:169] op_sel_hi:[1,0,1] neg_lo:[0,0,1]
	ds_read_b64 v[186:187], v200 offset:64
	ds_read_b64 v[182:183], v202 offset:184
	ds_read_b64 v[168:169], v200 offset:80
	ds_read_b64 v[118:119], v202 offset:168
	s_waitcnt lgkmcnt(6)
	v_pk_add_f32 v[176:177], v[176:177], v[110:111] op_sel:[1,1] op_sel_hi:[0,0] neg_hi:[1,0]
	v_pk_mul_f32 v[174:175], v[104:105], v[176:177] op_sel:[1,1] op_sel_hi:[0,1]
	v_pk_fma_f32 v[104:105], v[104:105], v[176:177], v[174:175] op_sel_hi:[1,0,1] neg_lo:[0,0,1]
	s_waitcnt lgkmcnt(4)
	v_pk_add_f32 v[166:167], v[166:167], v[102:103] op_sel:[1,1] op_sel_hi:[0,0] neg_hi:[1,0]
	v_pk_mul_f32 v[188:189], v[106:107], v[166:167] op_sel:[1,1] op_sel_hi:[0,1]
	v_pk_fma_f32 v[106:107], v[106:107], v[166:167], v[188:189] op_sel_hi:[1,0,1] neg_lo:[0,0,1]
	ds_read_b64 v[174:175], v200 offset:96
	ds_read_b64 v[176:177], v202 offset:152
	ds_read_b64 v[188:189], v200 offset:112
	ds_read_b64 v[166:167], v202 offset:136
	s_waitcnt lgkmcnt(6)
	v_pk_add_f32 v[186:187], v[186:187], v[182:183] op_sel:[1,1] op_sel_hi:[0,0] neg_hi:[1,0]
	v_pk_mul_f32 v[110:111], v[108:109], v[186:187] op_sel:[1,1] op_sel_hi:[0,1]
	v_pk_fma_f32 v[108:109], v[108:109], v[186:187], v[110:111] op_sel_hi:[1,0,1] neg_lo:[0,0,1]
	s_waitcnt lgkmcnt(4)
	v_pk_add_f32 v[168:169], v[168:169], v[118:119] op_sel:[1,1] op_sel_hi:[0,0] neg_hi:[1,0]
	v_pk_mul_f32 v[102:103], v[180:181], v[168:169] op_sel:[1,1] op_sel_hi:[0,1]
	v_pk_fma_f32 v[180:181], v[180:181], v[168:169], v[102:103] op_sel_hi:[1,0,1] neg_lo:[0,0,1]
	ds_read_b64 v[110:111], v200 offset:128
	ds_read_b64 v[186:187], v202 offset:120
	ds_read_b64 v[102:103], v200 offset:144
	ds_read_b64 v[168:169], v202 offset:104
	s_waitcnt lgkmcnt(6)
	v_pk_add_f32 v[174:175], v[174:175], v[176:177] op_sel:[1,1] op_sel_hi:[0,0] neg_hi:[1,0]
	v_pk_mul_f32 v[182:183], v[112:113], v[174:175] op_sel:[1,1] op_sel_hi:[0,1]
	v_pk_fma_f32 v[112:113], v[112:113], v[174:175], v[182:183] op_sel_hi:[1,0,1] neg_lo:[0,0,1]
	s_waitcnt lgkmcnt(4)
	v_pk_add_f32 v[188:189], v[188:189], v[166:167] op_sel:[1,1] op_sel_hi:[0,0] neg_hi:[1,0]
	v_pk_mul_f32 v[118:119], v[114:115], v[188:189] op_sel:[1,1] op_sel_hi:[0,1]
	v_pk_fma_f32 v[114:115], v[114:115], v[188:189], v[118:119] op_sel_hi:[1,0,1] neg_lo:[0,0,1]
	ds_read_b64 v[182:183], v200 offset:160
	ds_read_b64 v[174:175], v202 offset:88
	ds_read_b64 v[118:119], v200 offset:176
	ds_read_b64 v[188:189], v202 offset:72
	s_waitcnt lgkmcnt(6)
; #define LAS __attribute__((address_space(3)))
; __device__ __forceinline__ f32x2 cmul(f32x2 a, f32x2 b) { return (f32x2){a.x * b.x - a.y * b.y, a.x * b.y + a.y * b.x}; }
; template <bool INV> __device__ __forceinline__ f32x2 cmul_tw(f32x2 a, f32x2 w) { return INV ? cmulc(a, w) : cmul(a, w); }
; template <bool INV> __device__ __forceinline__ void dft16(f32x2 (&x)[16]) {
;     constexpr float C1 = 0.92387953251128674f, S1 = 0.38268343236508977f, C2 = 0.70710678118654752f;
; #pragma unroll
;     for (int b = 0; b < 4; ++b) dft4<INV>(x[b], x[4 + b], x[8 + b], x[12 + b]);
;     const f32x2 w1 = {C1, -S1}, w2 = {C2, -C2}, w3 = {S1, -C1}, w4 = {0.f, -1.f}, w6 = {-C2, -C2}, w9 = {-C1, S1};
;     x[4 * 1 + 1] = cmul_tw<INV>(x[5], w1); x[4 * 1 + 2] = cmul_tw<INV>(x[6], w2); x[4 * 1 + 3] = cmul_tw<INV>(x[7], w3);
;     x[4 * 2 + 1] = cmul_tw<INV>(x[9], w2); x[4 * 2 + 2] = cmul_tw<INV>(x[10], w4); x[4 * 2 + 3] = cmul_tw<INV>(x[11], w6);
;     x[4 * 3 + 1] = cmul_tw<INV>(x[13], w3); x[4 * 3 + 2] = cmul_tw<INV>(x[14], w6); x[4 * 3 + 3] = cmul_tw<INV>(x[15], w9);
; #pragma unroll
;     for (int c = 0; c < 4; ++c) dft4<INV>(x[4 * c], x[4 * c + 1], x[4 * c + 2], x[4 * c + 3]);
;     f32x2 y[16];
; #pragma unroll
;     for (int k = 0; k < 16; ++k) y[k] = x[4 * (k & 3) + (k >> 2)];
; #pragma unroll
;     for (int k = 0; k < 16; ++k) x[k] = y[k];
; template <int MODE> __device__ __forceinline__ void fft_pair32(LAS f32x2* B, const LAS f32x2* F, int wave, int lane) {
;     ...
;     const int k1 = blk >> 4, k2 = blk & 15, kb1 = (16 - k1) & 15, b1 = k1 != 0 ? 1 : 0, kb2 = (16 - k2 - b1) & 15, b2 = (k2 != 0 || b1) ? 1 : 0;
;     const LAS f32x2* fa = F + 33 * blk; const LAS f32x2* fb = F + 33 * (16 * kb1 + kb2);
;     const LAS f32x2* fah = fa + hi; const LAS f32x2* fbh = fb + (1 - b2) - hi;
;     constexpr float SC = 1.0f / (2.0f * (float)FN);
; #pragma unroll
;     for (int k = 0; k < 16; ++k) { const f32x2 A = fah[2 * k]; f32x2 Bm = fbh[31 - 2 * k];
;         if (k == 0) { const f32x2 m0 = b2 ? fb[31] : fa[0]; Bm = hi ? Bm : m0; }
;         const f32x2 H = MODE == 0 ? (f32x2){(A.x + Bm.x) * SC, (A.y - Bm.y) * SC} : (f32x2){(A.y + Bm.y) * SC, (Bm.x - A.x) * SC};
;         v[k] = cmul(v[k], H); }
;     dft16<true>(v);
	v_pk_add_f32 v[110:111], v[110:111], v[186:187] op_sel:[1,1] op_sel_hi:[0,0] neg_hi:[1,0]
	v_pk_mul_f32 v[176:177], v[116:117], v[110:111] op_sel:[1,1] op_sel_hi:[0,1]
	v_pk_fma_f32 v[116:117], v[116:117], v[110:111], v[176:177] op_sel_hi:[1,0,1] neg_lo:[0,0,1]
	s_waitcnt lgkmcnt(4)
	v_pk_add_f32 v[102:103], v[102:103], v[168:169] op_sel:[1,1] op_sel_hi:[0,0] neg_hi:[1,0]
	v_pk_mul_f32 v[166:167], v[178:179], v[102:103] op_sel:[1,1] op_sel_hi:[0,1]
	v_pk_fma_f32 v[178:179], v[178:179], v[102:103], v[166:167] op_sel_hi:[1,0,1] neg_lo:[0,0,1]
	ds_read_b64 v[176:177], v200 offset:192
	ds_read_b64 v[110:111], v202 offset:56
	ds_read_b64 v[166:167], v200 offset:208
	ds_read_b64 v[102:103], v202 offset:40
	s_waitcnt lgkmcnt(6)
	v_pk_add_f32 v[182:183], v[182:183], v[174:175] op_sel:[1,1] op_sel_hi:[0,0] neg_hi:[1,0]
	v_pk_mul_f32 v[186:187], v[120:121], v[182:183] op_sel:[1,1] op_sel_hi:[0,1]
	v_pk_fma_f32 v[120:121], v[120:121], v[182:183], v[186:187] op_sel_hi:[1,0,1] neg_lo:[0,0,1]
	s_waitcnt lgkmcnt(4)
	v_pk_add_f32 v[118:119], v[118:119], v[188:189] op_sel:[1,1] op_sel_hi:[0,0] neg_hi:[1,0]
	v_pk_mul_f32 v[168:169], v[122:123], v[118:119] op_sel:[1,1] op_sel_hi:[0,1]
	v_pk_fma_f32 v[122:123], v[122:123], v[118:119], v[168:169] op_sel_hi:[1,0,1] neg_lo:[0,0,1]
	ds_read_b64 v[186:187], v200 offset:224
	ds_read_b64 v[182:183], v202 offset:24
	ds_read_b64 v[168:169], v200 offset:240
	ds_read_b64 v[118:119], v202 offset:8
	s_waitcnt lgkmcnt(6)
	v_pk_add_f32 v[176:177], v[176:177], v[110:111] op_sel:[1,1] op_sel_hi:[0,0] neg_hi:[1,0]
	v_pk_mul_f32 v[174:175], v[124:125], v[176:177] op_sel:[1,1] op_sel_hi:[0,1]
	v_pk_fma_f32 v[124:125], v[124:125], v[176:177], v[174:175] op_sel_hi:[1,0,1] neg_lo:[0,0,1]
	s_waitcnt lgkmcnt(4)
	v_pk_add_f32 v[166:167], v[166:167], v[102:103] op_sel:[1,1] op_sel_hi:[0,0] neg_hi:[1,0]
	v_pk_mul_f32 v[188:189], v[184:185], v[166:167] op_sel:[1,1] op_sel_hi:[0,1]
	v_pk_fma_f32 v[184:185], v[184:185], v[166:167], v[188:189] op_sel_hi:[1,0,1] neg_lo:[0,0,1]
	s_waitcnt lgkmcnt(2)
	v_pk_add_f32 v[186:187], v[186:187], v[182:183] op_sel:[1,1] op_sel_hi:[0,0] neg_hi:[1,0]
	v_pk_mul_f32 v[174:175], v[128:129], v[186:187] op_sel:[1,1] op_sel_hi:[0,1]
	v_pk_fma_f32 v[128:129], v[128:129], v[186:187], v[174:175] op_sel_hi:[1,0,1] neg_lo:[0,0,1]
	s_waitcnt lgkmcnt(0)
	v_pk_add_f32 v[168:169], v[168:169], v[118:119] op_sel:[1,1] op_sel_hi:[0,0] neg_hi:[1,0]
	v_pk_mul_f32 v[188:189], v[130:131], v[168:169] op_sel:[1,1] op_sel_hi:[0,1]
	v_pk_fma_f32 v[130:131], v[130:131], v[168:169], v[188:189] op_sel_hi:[1,0,1] neg_lo:[0,0,1]
	v_pk_add_f32 v[176:177], v[100:101], v[116:117]
	v_pk_add_f32 v[166:167], v[100:101], v[116:117] neg_lo:[0,1] neg_hi:[0,1]
	v_pk_add_f32 v[110:111], v[108:109], v[124:125]
	v_pk_add_f32 v[102:103], v[108:109], v[124:125] neg_lo:[0,1] neg_hi:[0,1]
	v_pk_add_f32 v[100:101], v[176:177], v[110:111]
	v_pk_add_f32 v[116:117], v[176:177], v[110:111] neg_lo:[0,1] neg_hi:[0,1]
	v_pk_add_f32 v[108:109], v[166:167], v[102:103] op_sel:[0,1] op_sel_hi:[1,0] neg_lo:[0,1]
	v_pk_add_f32 v[124:125], v[166:167], v[102:103] op_sel:[0,1] op_sel_hi:[1,0] neg_hi:[0,1]
	v_pk_add_f32 v[174:175], v[126:127], v[178:179]
	v_pk_add_f32 v[188:189], v[126:127], v[178:179] neg_lo:[0,1] neg_hi:[0,1]
	v_pk_add_f32 v[186:187], v[180:181], v[184:185]
	v_pk_add_f32 v[168:169], v[180:181], v[184:185] neg_lo:[0,1] neg_hi:[0,1]
	v_pk_add_f32 v[126:127], v[174:175], v[186:187]
	v_pk_add_f32 v[178:179], v[174:175], v[186:187] neg_lo:[0,1] neg_hi:[0,1]
	v_pk_add_f32 v[180:181], v[188:189], v[168:169] op_sel:[0,1] op_sel_hi:[1,0] neg_lo:[0,1]
	v_pk_add_f32 v[184:185], v[188:189], v[168:169] op_sel:[0,1] op_sel_hi:[1,0] neg_hi:[0,1]
	v_pk_add_f32 v[182:183], v[104:105], v[120:121]
	v_pk_add_f32 v[118:119], v[104:105], v[120:121] neg_lo:[0,1] neg_hi:[0,1]
	v_pk_add_f32 v[176:177], v[112:113], v[128:129]
	v_pk_add_f32 v[166:167], v[112:113], v[128:129] neg_lo:[0,1] neg_hi:[0,1]
	v_pk_add_f32 v[104:105], v[182:183], v[176:177]
	v_pk_add_f32 v[120:121], v[182:183], v[176:177] neg_lo:[0,1] neg_hi:[0,1]
	v_pk_add_f32 v[112:113], v[118:119], v[166:167] op_sel:[0,1] op_sel_hi:[1,0] neg_lo:[0,1]
	v_pk_add_f32 v[128:129], v[118:119], v[166:167] op_sel:[0,1] op_sel_hi:[1,0] neg_hi:[0,1]
	v_pk_add_f32 v[110:111], v[106:107], v[122:123]
	v_pk_add_f32 v[102:103], v[106:107], v[122:123] neg_lo:[0,1] neg_hi:[0,1]
	v_pk_add_f32 v[174:175], v[114:115], v[130:131]
	v_pk_add_f32 v[188:189], v[114:115], v[130:131] neg_lo:[0,1] neg_hi:[0,1]
	v_pk_add_f32 v[106:107], v[110:111], v[174:175]
	v_pk_add_f32 v[122:123], v[110:111], v[174:175] neg_lo:[0,1] neg_hi:[0,1]
	v_pk_add_f32 v[114:115], v[102:103], v[188:189] op_sel:[0,1] op_sel_hi:[1,0] neg_lo:[0,1]
	v_pk_add_f32 v[130:131], v[102:103], v[188:189] op_sel:[0,1] op_sel_hi:[1,0] neg_hi:[0,1]
	v_pk_mul_f32 v[186:187], v[180:181], s[68:69] op_sel:[1,1] op_sel_hi:[0,1]
	v_pk_fma_f32 v[180:181], v[180:181], s[68:69], v[186:187] op_sel_hi:[1,0,1] neg_hi:[0,0,1]
	v_pk_mul_f32 v[168:169], v[112:113], s[84:85] op_sel:[1,1] op_sel_hi:[0,1]
	v_pk_fma_f32 v[112:113], v[112:113], s[84:85], v[168:169] op_sel_hi:[1,0,1] neg_hi:[0,0,1]
	v_pk_mul_f32 v[182:183], v[114:115], s[88:89] op_sel:[1,1] op_sel_hi:[0,1]
	v_pk_fma_f32 v[114:115], v[114:115], s[88:89], v[182:183] op_sel_hi:[1,0,1] neg_hi:[0,0,1]
	v_pk_mul_f32 v[118:119], v[178:179], s[84:85] op_sel:[1,1] op_sel_hi:[0,1]
	v_pk_fma_f32 v[178:179], v[178:179], s[84:85], v[118:119] op_sel_hi:[1,0,1] neg_hi:[0,0,1]
	v_pk_mul_f32 v[176:177], v[122:123], s[90:91] op_sel:[1,1] op_sel_hi:[0,1]
	v_pk_fma_f32 v[122:123], v[122:123], s[90:91], v[176:177] op_sel_hi:[1,0,1] neg_hi:[0,0,1]
; __device__ __forceinline__ f32x2 cmulc(f32x2 a, f32x2 b) { return (f32x2){a.x * b.x + a.y * b.y, a.y * b.x - a.x * b.y}; }
; template <bool INV> __device__ __forceinline__ f32x2 cmul_tw(f32x2 a, f32x2 w) { return INV ? cmulc(a, w) : cmul(a, w); }
; template <bool INV> __device__ __forceinline__ void dft16(f32x2 (&x)[16]) {
;     constexpr float C1 = 0.92387953251128674f, S1 = 0.38268343236508977f, C2 = 0.70710678118654752f;
; #pragma unroll
;     for (int b = 0; b < 4; ++b) dft4<INV>(x[b], x[4 + b], x[8 + b], x[12 + b]);
;     const f32x2 w1 = {C1, -S1}, w2 = {C2, -C2}, w3 = {S1, -C1}, w4 = {0.f, -1.f}, w6 = {-C2, -C2}, w9 = {-C1, S1};
;     x[4 * 1 + 1] = cmul_tw<INV>(x[5], w1); x[4 * 1 + 2] = cmul_tw<INV>(x[6], w2); x[4 * 1 + 3] = cmul_tw<INV>(x[7], w3);
;     x[4 * 2 + 1] = cmul_tw<INV>(x[9], w2); x[4 * 2 + 2] = cmul_tw<INV>(x[10], w4); x[4 * 2 + 3] = cmul_tw<INV>(x[11], w6);
;     x[4 * 3 + 1] = cmul_tw<INV>(x[13], w3); x[4 * 3 + 2] = cmul_tw<INV>(x[14], w6); x[4 * 3 + 3] = cmul_tw<INV>(x[15], w9);
; #pragma unroll
;     for (int c = 0; c < 4; ++c) dft4<INV>(x[4 * c], x[4 * c + 1], x[4 * c + 2], x[4 * c + 3]);
;     f32x2 y[16];
; #pragma unroll
;     for (int k = 0; k < 16; ++k) y[k] = x[4 * (k & 3) + (k >> 2)];
; #pragma unroll
;     for (int k = 0; k < 16; ++k) x[k] = y[k];
; template <int MODE> __device__ __forceinline__ void fft_pair32(LAS f32x2* B, const LAS f32x2* F, int wave, int lane) {
;     ...
;     for (int j = 0; j < 16; ++j) { const f32x2 w = {hi ? CS[j] : 1.f, hi ? -SN[j] : 0.f}; const f32x2 u = j == 0 ? v[j] : cmulc(v[j], w);
;         const auto rx = __builtin_amdgcn_permlane32_swap(__float_as_uint(u.x), __float_as_uint(u.x), false, false);
;         const auto ry = __builtin_amdgcn_permlane32_swap(__float_as_uint(u.y), __float_as_uint(u.y), false, false);
;         const f32x2 a = {__uint_as_float(rx[0]), __uint_as_float(ry[0])}, b = {__uint_as_float(rx[1]), __uint_as_float(ry[1])};
;         p[16 * hi + j] = a + b * sg; }
	v_pk_mul_f32 v[166:167], v[184:185], s[88:89] op_sel:[1,1] op_sel_hi:[0,1]
	v_pk_fma_f32 v[184:185], v[184:185], s[88:89], v[166:167] op_sel_hi:[1,0,1] neg_hi:[0,0,1]
	v_pk_mul_f32 v[110:111], v[128:129], s[90:91] op_sel:[1,1] op_sel_hi:[0,1]
	v_pk_fma_f32 v[128:129], v[128:129], s[90:91], v[110:111] op_sel_hi:[1,0,1] neg_hi:[0,0,1]
	v_pk_mul_f32 v[102:103], v[130:131], s[98:99] op_sel:[1,1] op_sel_hi:[0,1]
	v_pk_fma_f32 v[130:131], v[130:131], s[98:99], v[102:103] op_sel_hi:[1,0,1] neg_hi:[0,0,1]
	v_pk_add_f32 v[174:175], v[100:101], v[104:105]
	v_pk_add_f32 v[188:189], v[100:101], v[104:105] neg_lo:[0,1] neg_hi:[0,1]
	v_pk_add_f32 v[186:187], v[126:127], v[106:107]
	v_pk_add_f32 v[168:169], v[126:127], v[106:107] neg_lo:[0,1] neg_hi:[0,1]
	v_pk_add_f32 v[100:101], v[174:175], v[186:187]
	v_pk_add_f32 v[104:105], v[174:175], v[186:187] neg_lo:[0,1] neg_hi:[0,1]
	v_pk_add_f32 v[126:127], v[188:189], v[168:169] op_sel:[0,1] op_sel_hi:[1,0] neg_lo:[0,1]
	v_pk_add_f32 v[106:107], v[188:189], v[168:169] op_sel:[0,1] op_sel_hi:[1,0] neg_hi:[0,1]
	v_pk_add_f32 v[182:183], v[108:109], v[112:113]
	v_pk_add_f32 v[118:119], v[108:109], v[112:113] neg_lo:[0,1] neg_hi:[0,1]
	v_pk_add_f32 v[176:177], v[180:181], v[114:115]
	v_pk_add_f32 v[166:167], v[180:181], v[114:115] neg_lo:[0,1] neg_hi:[0,1]
	v_pk_add_f32 v[108:109], v[182:183], v[176:177]
	v_pk_add_f32 v[112:113], v[182:183], v[176:177] neg_lo:[0,1] neg_hi:[0,1]
	v_pk_add_f32 v[180:181], v[118:119], v[166:167] op_sel:[0,1] op_sel_hi:[1,0] neg_lo:[0,1]
	v_pk_add_f32 v[114:115], v[118:119], v[166:167] op_sel:[0,1] op_sel_hi:[1,0] neg_hi:[0,1]
	v_pk_add_f32 v[110:111], v[116:117], v[120:121] op_sel:[0,1] op_sel_hi:[1,0] neg_lo:[0,1]
	v_pk_add_f32 v[102:103], v[116:117], v[120:121] op_sel:[0,1] op_sel_hi:[1,0] neg_hi:[0,1]
	v_pk_add_f32 v[174:175], v[178:179], v[122:123]
	v_pk_add_f32 v[188:189], v[178:179], v[122:123] neg_lo:[0,1] neg_hi:[0,1]
	v_pk_add_f32 v[116:117], v[110:111], v[174:175]
	v_pk_add_f32 v[120:121], v[110:111], v[174:175] neg_lo:[0,1] neg_hi:[0,1]
	v_pk_add_f32 v[178:179], v[102:103], v[188:189] op_sel:[0,1] op_sel_hi:[1,0] neg_lo:[0,1]
	v_pk_add_f32 v[122:123], v[102:103], v[188:189] op_sel:[0,1] op_sel_hi:[1,0] neg_hi:[0,1]
	v_pk_add_f32 v[186:187], v[124:125], v[128:129]
	v_pk_add_f32 v[168:169], v[124:125], v[128:129] neg_lo:[0,1] neg_hi:[0,1]
	v_pk_add_f32 v[182:183], v[184:185], v[130:131]
	v_pk_add_f32 v[118:119], v[184:185], v[130:131] neg_lo:[0,1] neg_hi:[0,1]
	v_pk_add_f32 v[124:125], v[186:187], v[182:183]
	v_pk_add_f32 v[128:129], v[186:187], v[182:183] neg_lo:[0,1] neg_hi:[0,1]
	v_pk_add_f32 v[184:185], v[168:169], v[118:119] op_sel:[0,1] op_sel_hi:[1,0] neg_lo:[0,1]
	v_pk_add_f32 v[130:131], v[168:169], v[118:119] op_sel:[0,1] op_sel_hi:[1,0] neg_hi:[0,1]
	v_mov_b32_e32 v176, v100
	v_mov_b32_e32 v177, v101
	v_pk_mul_f32 v[174:175], v[108:109], v[36:37] op_sel:[1,1] op_sel_hi:[0,1]
	v_pk_fma_f32 v[166:167], v[108:109], v[36:37], v[174:175] op_sel_hi:[1,0,1] neg_hi:[0,0,1]
	v_pk_fma_f32 v[108:109], v[108:109], v[36:37], v[174:175] op_sel_hi:[1,0,1] neg_hi:[0,0,1]
	v_pk_mul_f32 v[188:189], v[116:117], v[38:39] op_sel:[1,1] op_sel_hi:[0,1]
	v_pk_fma_f32 v[110:111], v[116:117], v[38:39], v[188:189] op_sel_hi:[1,0,1] neg_hi:[0,0,1]
	v_pk_fma_f32 v[116:117], v[116:117], v[38:39], v[188:189] op_sel_hi:[1,0,1] neg_hi:[0,0,1]
	v_pk_mul_f32 v[186:187], v[124:125], v[40:41] op_sel:[1,1] op_sel_hi:[0,1]
	v_pk_fma_f32 v[102:103], v[124:125], v[40:41], v[186:187] op_sel_hi:[1,0,1] neg_hi:[0,0,1]
	v_pk_fma_f32 v[124:125], v[124:125], v[40:41], v[186:187] op_sel_hi:[1,0,1] neg_hi:[0,0,1]
	s_nop 1
	v_permlane32_swap_b32_e32 v100, v176
	v_permlane32_swap_b32_e32 v101, v177
	v_permlane32_swap_b32_e32 v108, v166
	v_permlane32_swap_b32_e32 v109, v167
	v_permlane32_swap_b32_e32 v116, v110
	v_permlane32_swap_b32_e32 v117, v111
	v_permlane32_swap_b32_e32 v124, v102
	v_permlane32_swap_b32_e32 v125, v103
	v_pk_fma_f32 v[100:101], v[176:177], v[190:191], v[100:101] op_sel_hi:[1,0,1]
	ds_write_b64 v198, v[100:101]
	v_pk_fma_f32 v[108:109], v[166:167], v[190:191], v[108:109] op_sel_hi:[1,0,1]
	ds_write_b64 v198, v[108:109] offset:8
	v_pk_fma_f32 v[116:117], v[110:111], v[190:191], v[116:117] op_sel_hi:[1,0,1]
	ds_write_b64 v198, v[116:117] offset:16
	v_pk_fma_f32 v[124:125], v[102:103], v[190:191], v[124:125] op_sel_hi:[1,0,1]
	ds_write_b64 v198, v[124:125] offset:24
	v_pk_mul_f32 v[188:189], v[126:127], v[42:43] op_sel:[1,1] op_sel_hi:[0,1]
	v_pk_fma_f32 v[168:169], v[126:127], v[42:43], v[188:189] op_sel_hi:[1,0,1] neg_hi:[0,0,1]
	v_pk_fma_f32 v[126:127], v[126:127], v[42:43], v[188:189] op_sel_hi:[1,0,1] neg_hi:[0,0,1]
	v_pk_mul_f32 v[186:187], v[180:181], v[44:45] op_sel:[1,1] op_sel_hi:[0,1]
	v_pk_fma_f32 v[182:183], v[180:181], v[44:45], v[186:187] op_sel_hi:[1,0,1] neg_hi:[0,0,1]
	v_pk_fma_f32 v[180:181], v[180:181], v[44:45], v[186:187] op_sel_hi:[1,0,1] neg_hi:[0,0,1]
	v_pk_mul_f32 v[176:177], v[178:179], v[46:47] op_sel:[1,1] op_sel_hi:[0,1]
	v_pk_fma_f32 v[118:119], v[178:179], v[46:47], v[176:177] op_sel_hi:[1,0,1] neg_hi:[0,0,1]
	v_pk_fma_f32 v[178:179], v[178:179], v[46:47], v[176:177] op_sel_hi:[1,0,1] neg_hi:[0,0,1]
	v_pk_mul_f32 v[166:167], v[184:185], v[48:49] op_sel:[1,1] op_sel_hi:[0,1]
	v_pk_fma_f32 v[174:175], v[184:185], v[48:49], v[166:167] op_sel_hi:[1,0,1] neg_hi:[0,0,1]
	v_pk_fma_f32 v[184:185], v[184:185], v[48:49], v[166:167] op_sel_hi:[1,0,1] neg_hi:[0,0,1]
	s_nop 1
	v_permlane32_swap_b32_e32 v126, v168
	v_permlane32_swap_b32_e32 v127, v169
	v_permlane32_swap_b32_e32 v180, v182
	v_permlane32_swap_b32_e32 v181, v183
	v_permlane32_swap_b32_e32 v178, v118
; #define LAS __attribute__((address_space(3)))
; __device__ __forceinline__ f32x2 cmulc(f32x2 a, f32x2 b) { return (f32x2){a.x * b.x + a.y * b.y, a.y * b.x - a.x * b.y}; }
; __device__ __forceinline__ void fft_inv2(LAS f32x2* B, const LAS f32x2* TW2, int tid) {
;     asm volatile("" : "+v"(tid));
;     const int b = tid >> 5, n2 = tid & 31, base = 512 * b + n2; f32x2 x[16];
;     x[0] = B[fpad(base)];
; #pragma unroll
;     for (int k = 1; k < 16; ++k) x[k] = cmulc(B[fpad(base + 32 * k)], TW2[k * 32 + n2]);
; template <int MODE> __device__ __forceinline__ void fft_pair32(LAS f32x2* B, const LAS f32x2* F, int wave, int lane) {
;     ...
;     for (int j = 0; j < 16; ++j) { const f32x2 w = {hi ? CS[j] : 1.f, hi ? -SN[j] : 0.f}; const f32x2 u = j == 0 ? v[j] : cmulc(v[j], w);
;         const auto rx = __builtin_amdgcn_permlane32_swap(__float_as_uint(u.x), __float_as_uint(u.x), false, false);
;         const auto ry = __builtin_amdgcn_permlane32_swap(__float_as_uint(u.y), __float_as_uint(u.y), false, false);
;         const f32x2 a = {__uint_as_float(rx[0]), __uint_as_float(ry[0])}, b = {__uint_as_float(rx[1]), __uint_as_float(ry[1])};
;         p[16 * hi + j] = a + b * sg; }
	v_permlane32_swap_b32_e32 v179, v119
	v_permlane32_swap_b32_e32 v184, v174
	v_permlane32_swap_b32_e32 v185, v175
	v_pk_fma_f32 v[126:127], v[168:169], v[190:191], v[126:127] op_sel_hi:[1,0,1]
	ds_write_b64 v198, v[126:127] offset:32
	v_pk_fma_f32 v[180:181], v[182:183], v[190:191], v[180:181] op_sel_hi:[1,0,1]
	ds_write_b64 v198, v[180:181] offset:40
	v_pk_fma_f32 v[178:179], v[118:119], v[190:191], v[178:179] op_sel_hi:[1,0,1]
	ds_write_b64 v198, v[178:179] offset:48
	v_pk_fma_f32 v[184:185], v[174:175], v[190:191], v[184:185] op_sel_hi:[1,0,1]
	ds_write_b64 v198, v[184:185] offset:56
	v_pk_mul_f32 v[176:177], v[104:105], v[50:51] op_sel:[1,1] op_sel_hi:[0,1]
	v_pk_fma_f32 v[110:111], v[104:105], v[50:51], v[176:177] op_sel_hi:[1,0,1] neg_hi:[0,0,1]
	v_pk_fma_f32 v[104:105], v[104:105], v[50:51], v[176:177] op_sel_hi:[1,0,1] neg_hi:[0,0,1]
	v_pk_mul_f32 v[166:167], v[112:113], v[52:53] op_sel:[1,1] op_sel_hi:[0,1]
	v_pk_fma_f32 v[102:103], v[112:113], v[52:53], v[166:167] op_sel_hi:[1,0,1] neg_hi:[0,0,1]
	v_pk_fma_f32 v[112:113], v[112:113], v[52:53], v[166:167] op_sel_hi:[1,0,1] neg_hi:[0,0,1]
	v_pk_mul_f32 v[168:169], v[120:121], v[54:55] op_sel:[1,1] op_sel_hi:[0,1]
	v_pk_fma_f32 v[188:189], v[120:121], v[54:55], v[168:169] op_sel_hi:[1,0,1] neg_hi:[0,0,1]
	v_pk_fma_f32 v[120:121], v[120:121], v[54:55], v[168:169] op_sel_hi:[1,0,1] neg_hi:[0,0,1]
	v_pk_mul_f32 v[182:183], v[128:129], v[90:91] op_sel:[1,1] op_sel_hi:[0,1]
	v_pk_fma_f32 v[186:187], v[128:129], v[90:91], v[182:183] op_sel_hi:[1,0,1] neg_hi:[0,0,1]
	v_pk_fma_f32 v[128:129], v[128:129], v[90:91], v[182:183] op_sel_hi:[1,0,1] neg_hi:[0,0,1]
	s_nop 1
	v_permlane32_swap_b32_e32 v104, v110
	v_permlane32_swap_b32_e32 v105, v111
	v_permlane32_swap_b32_e32 v112, v102
	v_permlane32_swap_b32_e32 v113, v103
	v_permlane32_swap_b32_e32 v120, v188
	v_permlane32_swap_b32_e32 v121, v189
	v_permlane32_swap_b32_e32 v128, v186
	v_permlane32_swap_b32_e32 v129, v187
	v_pk_fma_f32 v[104:105], v[110:111], v[190:191], v[104:105] op_sel_hi:[1,0,1]
	ds_write_b64 v198, v[104:105] offset:64
	v_pk_fma_f32 v[112:113], v[102:103], v[190:191], v[112:113] op_sel_hi:[1,0,1]
	ds_write_b64 v198, v[112:113] offset:72
	v_pk_fma_f32 v[120:121], v[188:189], v[190:191], v[120:121] op_sel_hi:[1,0,1]
	ds_write_b64 v198, v[120:121] offset:80
	v_pk_fma_f32 v[128:129], v[186:187], v[190:191], v[128:129] op_sel_hi:[1,0,1]
	ds_write_b64 v198, v[128:129] offset:88
	v_pk_mul_f32 v[168:169], v[106:107], v[92:93] op_sel:[1,1] op_sel_hi:[0,1]
	v_pk_fma_f32 v[118:119], v[106:107], v[92:93], v[168:169] op_sel_hi:[1,0,1] neg_hi:[0,0,1]
	v_pk_fma_f32 v[106:107], v[106:107], v[92:93], v[168:169] op_sel_hi:[1,0,1] neg_hi:[0,0,1]
	v_pk_mul_f32 v[182:183], v[114:115], v[94:95] op_sel:[1,1] op_sel_hi:[0,1]
	v_pk_fma_f32 v[174:175], v[114:115], v[94:95], v[182:183] op_sel_hi:[1,0,1] neg_hi:[0,0,1]
	v_pk_fma_f32 v[114:115], v[114:115], v[94:95], v[182:183] op_sel_hi:[1,0,1] neg_hi:[0,0,1]
	v_pk_mul_f32 v[110:111], v[122:123], v[96:97] op_sel:[1,1] op_sel_hi:[0,1]
	v_pk_fma_f32 v[176:177], v[122:123], v[96:97], v[110:111] op_sel_hi:[1,0,1] neg_hi:[0,0,1]
	v_pk_fma_f32 v[122:123], v[122:123], v[96:97], v[110:111] op_sel_hi:[1,0,1] neg_hi:[0,0,1]
	v_pk_mul_f32 v[102:103], v[130:131], v[98:99] op_sel:[1,1] op_sel_hi:[0,1]
	v_pk_fma_f32 v[166:167], v[130:131], v[98:99], v[102:103] op_sel_hi:[1,0,1] neg_hi:[0,0,1]
	v_pk_fma_f32 v[130:131], v[130:131], v[98:99], v[102:103] op_sel_hi:[1,0,1] neg_hi:[0,0,1]
	s_nop 1
	v_permlane32_swap_b32_e32 v106, v118
	v_permlane32_swap_b32_e32 v107, v119
	v_permlane32_swap_b32_e32 v114, v174
	v_permlane32_swap_b32_e32 v115, v175
	v_permlane32_swap_b32_e32 v122, v176
	v_permlane32_swap_b32_e32 v123, v177
	v_permlane32_swap_b32_e32 v130, v166
	v_permlane32_swap_b32_e32 v131, v167
	v_pk_fma_f32 v[106:107], v[118:119], v[190:191], v[106:107] op_sel_hi:[1,0,1]
	ds_write_b64 v198, v[106:107] offset:96
	v_pk_fma_f32 v[114:115], v[174:175], v[190:191], v[114:115] op_sel_hi:[1,0,1]
	ds_write_b64 v198, v[114:115] offset:104
	v_pk_fma_f32 v[122:123], v[176:177], v[190:191], v[122:123] op_sel_hi:[1,0,1]
	ds_write_b64 v198, v[122:123] offset:112
	v_pk_fma_f32 v[130:131], v[166:167], v[190:191], v[130:131] op_sel_hi:[1,0,1]
	ds_write_b64 v198, v[130:131] offset:120
	s_waitcnt lgkmcnt(0)
	ds_read_b64 v[100:101], v5
	ds_read_b64 v[108:109], v5 offset:264
	ds_read_b64 v[188:189], v56 offset:256
	ds_read_b64 v[116:117], v5 offset:528
	ds_read_b64 v[186:187], v56 offset:512
	ds_read_b64 v[124:125], v5 offset:792
	ds_read_b64 v[168:169], v56 offset:768
	ds_read_b64 v[126:127], v5 offset:1056
	ds_read_b64 v[182:183], v56 offset:1024
	ds_read_b64 v[180:181], v5 offset:1320
	ds_read_b64 v[110:111], v56 offset:1280
	ds_read_b64 v[178:179], v5 offset:1584
	ds_read_b64 v[102:103], v56 offset:1536
	ds_read_b64 v[184:185], v5 offset:1848
	ds_read_b64 v[118:119], v56 offset:1792
	ds_read_b64 v[104:105], v5 offset:2112
	ds_read_b64 v[174:175], v56 offset:2048
	s_waitcnt lgkmcnt(14)
	v_pk_mul_f32 v[176:177], v[108:109], v[188:189] op_sel:[1,1] op_sel_hi:[0,1]
	v_pk_fma_f32 v[108:109], v[108:109], v[188:189], v[176:177] op_sel_hi:[1,0,1] neg_hi:[0,0,1]
	s_waitcnt lgkmcnt(12)
	v_pk_mul_f32 v[166:167], v[116:117], v[186:187] op_sel:[1,1] op_sel_hi:[0,1]
	v_pk_fma_f32 v[116:117], v[116:117], v[186:187], v[166:167] op_sel_hi:[1,0,1] neg_hi:[0,0,1]
	s_waitcnt lgkmcnt(10)
	v_pk_mul_f32 v[176:177], v[124:125], v[168:169] op_sel:[1,1] op_sel_hi:[0,1]
	v_pk_fma_f32 v[124:125], v[124:125], v[168:169], v[176:177] op_sel_hi:[1,0,1] neg_hi:[0,0,1]
	s_waitcnt lgkmcnt(8)
; #define LAS __attribute__((address_space(3)))
; __device__ __forceinline__ f32x2 cmulc(f32x2 a, f32x2 b) { return (f32x2){a.x * b.x + a.y * b.y, a.y * b.x - a.x * b.y}; }
; template <bool INV> __device__ __forceinline__ f32x2 cmul_tw(f32x2 a, f32x2 w) { return INV ? cmulc(a, w) : cmul(a, w); }
; template <bool INV> __device__ __forceinline__ void dft16(f32x2 (&x)[16]) {
;     constexpr float C1 = 0.92387953251128674f, S1 = 0.38268343236508977f, C2 = 0.70710678118654752f;
; #pragma unroll
;     for (int b = 0; b < 4; ++b) dft4<INV>(x[b], x[4 + b], x[8 + b], x[12 + b]);
;     const f32x2 w1 = {C1, -S1}, w2 = {C2, -C2}, w3 = {S1, -C1}, w4 = {0.f, -1.f}, w6 = {-C2, -C2}, w9 = {-C1, S1};
;     x[4 * 1 + 1] = cmul_tw<INV>(x[5], w1); x[4 * 1 + 2] = cmul_tw<INV>(x[6], w2); x[4 * 1 + 3] = cmul_tw<INV>(x[7], w3);
;     x[4 * 2 + 1] = cmul_tw<INV>(x[9], w2); x[4 * 2 + 2] = cmul_tw<INV>(x[10], w4); x[4 * 2 + 3] = cmul_tw<INV>(x[11], w6);
;     x[4 * 3 + 1] = cmul_tw<INV>(x[13], w3); x[4 * 3 + 2] = cmul_tw<INV>(x[14], w6); x[4 * 3 + 3] = cmul_tw<INV>(x[15], w9);
; #pragma unroll
;     for (int c = 0; c < 4; ++c) dft4<INV>(x[4 * c], x[4 * c + 1], x[4 * c + 2], x[4 * c + 3]);
;     f32x2 y[16];
; #pragma unroll
;     for (int k = 0; k < 16; ++k) y[k] = x[4 * (k & 3) + (k >> 2)];
; #pragma unroll
;     for (int k = 0; k < 16; ++k) x[k] = y[k];
; __device__ __forceinline__ void fft_inv2(LAS f32x2* B, const LAS f32x2* TW2, int tid) {
;     asm volatile("" : "+v"(tid));
;     const int b = tid >> 5, n2 = tid & 31, base = 512 * b + n2; f32x2 x[16];
;     x[0] = B[fpad(base)];
; #pragma unroll
;     for (int k = 1; k < 16; ++k) x[k] = cmulc(B[fpad(base + 32 * k)], TW2[k * 32 + n2]);
;     dft16<true>(x);
	v_pk_mul_f32 v[166:167], v[126:127], v[182:183] op_sel:[1,1] op_sel_hi:[0,1]
	v_pk_fma_f32 v[126:127], v[126:127], v[182:183], v[166:167] op_sel_hi:[1,0,1] neg_hi:[0,0,1]
	ds_read_b64 v[112:113], v5 offset:2376
	ds_read_b64 v[176:177], v56 offset:2304
	ds_read_b64 v[120:121], v5 offset:2640
	ds_read_b64 v[166:167], v56 offset:2560
	ds_read_b64 v[128:129], v5 offset:2904
	ds_read_b64 v[188:189], v56 offset:2816
	ds_read_b64 v[106:107], v5 offset:3168
	ds_read_b64 v[186:187], v56 offset:3072
	s_waitcnt lgkmcnt(14)
	v_pk_mul_f32 v[168:169], v[180:181], v[110:111] op_sel:[1,1] op_sel_hi:[0,1]
	v_pk_fma_f32 v[180:181], v[180:181], v[110:111], v[168:169] op_sel_hi:[1,0,1] neg_hi:[0,0,1]
	s_waitcnt lgkmcnt(12)
	v_pk_mul_f32 v[182:183], v[178:179], v[102:103] op_sel:[1,1] op_sel_hi:[0,1]
	v_pk_fma_f32 v[178:179], v[178:179], v[102:103], v[182:183] op_sel_hi:[1,0,1] neg_hi:[0,0,1]
	s_waitcnt lgkmcnt(10)
	v_pk_mul_f32 v[168:169], v[184:185], v[118:119] op_sel:[1,1] op_sel_hi:[0,1]
	v_pk_fma_f32 v[184:185], v[184:185], v[118:119], v[168:169] op_sel_hi:[1,0,1] neg_hi:[0,0,1]
	s_waitcnt lgkmcnt(8)
	v_pk_mul_f32 v[182:183], v[104:105], v[174:175] op_sel:[1,1] op_sel_hi:[0,1]
	v_pk_fma_f32 v[104:105], v[104:105], v[174:175], v[182:183] op_sel_hi:[1,0,1] neg_hi:[0,0,1]
	ds_read_b64 v[114:115], v5 offset:3432
	ds_read_b64 v[168:169], v56 offset:3328
	ds_read_b64 v[122:123], v5 offset:3696
	ds_read_b64 v[182:183], v56 offset:3584
	ds_read_b64 v[130:131], v5 offset:3960
	ds_read_b64 v[110:111], v56 offset:3840
	s_waitcnt lgkmcnt(12)
	v_pk_mul_f32 v[102:103], v[112:113], v[176:177] op_sel:[1,1] op_sel_hi:[0,1]
	v_pk_fma_f32 v[112:113], v[112:113], v[176:177], v[102:103] op_sel_hi:[1,0,1] neg_hi:[0,0,1]
	s_waitcnt lgkmcnt(10)
	v_pk_mul_f32 v[118:119], v[120:121], v[166:167] op_sel:[1,1] op_sel_hi:[0,1]
	v_pk_fma_f32 v[120:121], v[120:121], v[166:167], v[118:119] op_sel_hi:[1,0,1] neg_hi:[0,0,1]
	s_waitcnt lgkmcnt(8)
	v_pk_mul_f32 v[174:175], v[128:129], v[188:189] op_sel:[1,1] op_sel_hi:[0,1]
	v_pk_fma_f32 v[128:129], v[128:129], v[188:189], v[174:175] op_sel_hi:[1,0,1] neg_hi:[0,0,1]
	s_waitcnt lgkmcnt(6)
	v_pk_mul_f32 v[102:103], v[106:107], v[186:187] op_sel:[1,1] op_sel_hi:[0,1]
	v_pk_fma_f32 v[106:107], v[106:107], v[186:187], v[102:103] op_sel_hi:[1,0,1] neg_hi:[0,0,1]
	s_waitcnt lgkmcnt(4)
	v_pk_mul_f32 v[118:119], v[114:115], v[168:169] op_sel:[1,1] op_sel_hi:[0,1]
	v_pk_fma_f32 v[114:115], v[114:115], v[168:169], v[118:119] op_sel_hi:[1,0,1] neg_hi:[0,0,1]
	s_waitcnt lgkmcnt(2)
	v_pk_mul_f32 v[174:175], v[122:123], v[182:183] op_sel:[1,1] op_sel_hi:[0,1]
	v_pk_fma_f32 v[122:123], v[122:123], v[182:183], v[174:175] op_sel_hi:[1,0,1] neg_hi:[0,0,1]
	s_waitcnt lgkmcnt(0)
	v_pk_mul_f32 v[102:103], v[130:131], v[110:111] op_sel:[1,1] op_sel_hi:[0,1]
	v_pk_fma_f32 v[130:131], v[130:131], v[110:111], v[102:103] op_sel_hi:[1,0,1] neg_hi:[0,0,1]
	v_pk_add_f32 v[176:177], v[100:101], v[104:105]
	v_pk_add_f32 v[166:167], v[100:101], v[104:105] neg_lo:[0,1] neg_hi:[0,1]
	v_pk_add_f32 v[188:189], v[126:127], v[106:107]
	v_pk_add_f32 v[186:187], v[126:127], v[106:107] neg_lo:[0,1] neg_hi:[0,1]
	v_pk_add_f32 v[100:101], v[176:177], v[188:189]
	v_pk_add_f32 v[104:105], v[176:177], v[188:189] neg_lo:[0,1] neg_hi:[0,1]
	v_pk_add_f32 v[126:127], v[166:167], v[186:187] op_sel:[0,1] op_sel_hi:[1,0] neg_lo:[0,1]
	v_pk_add_f32 v[106:107], v[166:167], v[186:187] op_sel:[0,1] op_sel_hi:[1,0] neg_hi:[0,1]
	v_pk_add_f32 v[118:119], v[108:109], v[112:113]
	v_pk_add_f32 v[174:175], v[108:109], v[112:113] neg_lo:[0,1] neg_hi:[0,1]
	v_pk_add_f32 v[102:103], v[180:181], v[114:115]
	v_pk_add_f32 v[168:169], v[180:181], v[114:115] neg_lo:[0,1] neg_hi:[0,1]
	v_pk_add_f32 v[108:109], v[118:119], v[102:103]
	v_pk_add_f32 v[112:113], v[118:119], v[102:103] neg_lo:[0,1] neg_hi:[0,1]
	v_pk_add_f32 v[180:181], v[174:175], v[168:169] op_sel:[0,1] op_sel_hi:[1,0] neg_lo:[0,1]
	v_pk_add_f32 v[114:115], v[174:175], v[168:169] op_sel:[0,1] op_sel_hi:[1,0] neg_hi:[0,1]
	v_pk_add_f32 v[182:183], v[116:117], v[120:121]
	v_pk_add_f32 v[110:111], v[116:117], v[120:121] neg_lo:[0,1] neg_hi:[0,1]
	v_pk_add_f32 v[176:177], v[178:179], v[122:123]
	v_pk_add_f32 v[166:167], v[178:179], v[122:123] neg_lo:[0,1] neg_hi:[0,1]
	v_pk_add_f32 v[116:117], v[182:183], v[176:177]
	v_pk_add_f32 v[120:121], v[182:183], v[176:177] neg_lo:[0,1] neg_hi:[0,1]
	v_pk_add_f32 v[178:179], v[110:111], v[166:167] op_sel:[0,1] op_sel_hi:[1,0] neg_lo:[0,1]
	v_pk_add_f32 v[122:123], v[110:111], v[166:167] op_sel:[0,1] op_sel_hi:[1,0] neg_hi:[0,1]
	v_pk_add_f32 v[188:189], v[124:125], v[128:129]
	v_pk_add_f32 v[186:187], v[124:125], v[128:129] neg_lo:[0,1] neg_hi:[0,1]
	v_pk_add_f32 v[118:119], v[184:185], v[130:131]
	v_pk_add_f32 v[174:175], v[184:185], v[130:131] neg_lo:[0,1] neg_hi:[0,1]
	v_pk_add_f32 v[124:125], v[188:189], v[118:119]
	v_pk_add_f32 v[128:129], v[188:189], v[118:119] neg_lo:[0,1] neg_hi:[0,1]
	v_pk_add_f32 v[184:185], v[186:187], v[174:175] op_sel:[0,1] op_sel_hi:[1,0] neg_lo:[0,1]
	v_pk_add_f32 v[130:131], v[186:187], v[174:175] op_sel:[0,1] op_sel_hi:[1,0] neg_hi:[0,1]
	v_pk_mul_f32 v[102:103], v[180:181], s[68:69] op_sel:[1,1] op_sel_hi:[0,1]
	v_pk_fma_f32 v[180:181], v[180:181], s[68:69], v[102:103] op_sel_hi:[1,0,1] neg_hi:[0,0,1]
	v_pk_mul_f32 v[168:169], v[178:179], s[84:85] op_sel:[1,1] op_sel_hi:[0,1]
	v_pk_fma_f32 v[178:179], v[178:179], s[84:85], v[168:169] op_sel_hi:[1,0,1] neg_hi:[0,0,1]
	v_pk_mul_f32 v[182:183], v[184:185], s[88:89] op_sel:[1,1] op_sel_hi:[0,1]
	v_pk_fma_f32 v[184:185], v[184:185], s[88:89], v[182:183] op_sel_hi:[1,0,1] neg_hi:[0,0,1]
	v_pk_mul_f32 v[110:111], v[112:113], s[84:85] op_sel:[1,1] op_sel_hi:[0,1]
; #define LAS __attribute__((address_space(3)))
; __device__ __forceinline__ f32x2 cmulc(f32x2 a, f32x2 b) { return (f32x2){a.x * b.x + a.y * b.y, a.y * b.x - a.x * b.y}; }
; __device__ __forceinline__ void fft_inv2(LAS f32x2* B, const LAS f32x2* TW2, int tid) {
;     asm volatile("" : "+v"(tid));
;     const int b = tid >> 5, n2 = tid & 31, base = 512 * b + n2; f32x2 x[16];
;     x[0] = B[fpad(base)];
; #pragma unroll
;     for (int k = 1; k < 16; ++k) x[k] = cmulc(B[fpad(base + 32 * k)], TW2[k * 32 + n2]);
;     dft16<true>(x);
; #pragma unroll
;     for (int r = 0; r < 16; ++r) B[fpad(base + 32 * r)] = x[r];
; }
; __device__ __forceinline__ void fft_inv1(f32x2 (&x)[16], const LAS f32x2* B, int n2, const f32x2 (&w)[16]) {
;     asm volatile("" : "+v"(n2));
;     x[0] = B[fpad(n2)];
; #pragma unroll
;     for (int k = 1; k < 16; ++k) x[k] = cmulc(B[fpad(512 * k + n2)], w[k]);
;     dft16_inv_lo(x);
; }
	v_pk_fma_f32 v[112:113], v[112:113], s[84:85], v[110:111] op_sel_hi:[1,0,1] neg_hi:[0,0,1]
	v_pk_mul_f32 v[176:177], v[128:129], s[90:91] op_sel:[1,1] op_sel_hi:[0,1]
	v_pk_fma_f32 v[128:129], v[128:129], s[90:91], v[176:177] op_sel_hi:[1,0,1] neg_hi:[0,0,1]
	v_pk_mul_f32 v[166:167], v[114:115], s[88:89] op_sel:[1,1] op_sel_hi:[0,1]
	v_pk_fma_f32 v[114:115], v[114:115], s[88:89], v[166:167] op_sel_hi:[1,0,1] neg_hi:[0,0,1]
	v_pk_mul_f32 v[188:189], v[122:123], s[90:91] op_sel:[1,1] op_sel_hi:[0,1]
	v_pk_fma_f32 v[122:123], v[122:123], s[90:91], v[188:189] op_sel_hi:[1,0,1] neg_hi:[0,0,1]
	v_pk_mul_f32 v[186:187], v[130:131], s[98:99] op_sel:[1,1] op_sel_hi:[0,1]
	v_pk_fma_f32 v[130:131], v[130:131], s[98:99], v[186:187] op_sel_hi:[1,0,1] neg_hi:[0,0,1]
	v_pk_add_f32 v[118:119], v[100:101], v[116:117]
	v_pk_add_f32 v[174:175], v[100:101], v[116:117] neg_lo:[0,1] neg_hi:[0,1]
	v_pk_add_f32 v[102:103], v[108:109], v[124:125]
	v_pk_add_f32 v[168:169], v[108:109], v[124:125] neg_lo:[0,1] neg_hi:[0,1]
	v_pk_add_f32 v[100:101], v[118:119], v[102:103]
	v_pk_add_f32 v[116:117], v[118:119], v[102:103] neg_lo:[0,1] neg_hi:[0,1]
	v_pk_add_f32 v[108:109], v[174:175], v[168:169] op_sel:[0,1] op_sel_hi:[1,0] neg_lo:[0,1]
	v_pk_add_f32 v[124:125], v[174:175], v[168:169] op_sel:[0,1] op_sel_hi:[1,0] neg_hi:[0,1]
	v_pk_add_f32 v[182:183], v[126:127], v[178:179]
	v_pk_add_f32 v[110:111], v[126:127], v[178:179] neg_lo:[0,1] neg_hi:[0,1]
	v_pk_add_f32 v[176:177], v[180:181], v[184:185]
	v_pk_add_f32 v[166:167], v[180:181], v[184:185] neg_lo:[0,1] neg_hi:[0,1]
	v_pk_add_f32 v[126:127], v[182:183], v[176:177]
	v_pk_add_f32 v[178:179], v[182:183], v[176:177] neg_lo:[0,1] neg_hi:[0,1]
	v_pk_add_f32 v[180:181], v[110:111], v[166:167] op_sel:[0,1] op_sel_hi:[1,0] neg_lo:[0,1]
	v_pk_add_f32 v[184:185], v[110:111], v[166:167] op_sel:[0,1] op_sel_hi:[1,0] neg_hi:[0,1]
	v_pk_add_f32 v[188:189], v[104:105], v[120:121] op_sel:[0,1] op_sel_hi:[1,0] neg_lo:[0,1]
	v_pk_add_f32 v[186:187], v[104:105], v[120:121] op_sel:[0,1] op_sel_hi:[1,0] neg_hi:[0,1]
	v_pk_add_f32 v[118:119], v[112:113], v[128:129]
	v_pk_add_f32 v[174:175], v[112:113], v[128:129] neg_lo:[0,1] neg_hi:[0,1]
	v_pk_add_f32 v[104:105], v[188:189], v[118:119]
	v_pk_add_f32 v[120:121], v[188:189], v[118:119] neg_lo:[0,1] neg_hi:[0,1]
	v_pk_add_f32 v[112:113], v[186:187], v[174:175] op_sel:[0,1] op_sel_hi:[1,0] neg_lo:[0,1]
	v_pk_add_f32 v[128:129], v[186:187], v[174:175] op_sel:[0,1] op_sel_hi:[1,0] neg_hi:[0,1]
	v_pk_add_f32 v[102:103], v[106:107], v[122:123]
	v_pk_add_f32 v[168:169], v[106:107], v[122:123] neg_lo:[0,1] neg_hi:[0,1]
	v_pk_add_f32 v[182:183], v[114:115], v[130:131]
	v_pk_add_f32 v[110:111], v[114:115], v[130:131] neg_lo:[0,1] neg_hi:[0,1]
	v_pk_add_f32 v[106:107], v[102:103], v[182:183]
	v_pk_add_f32 v[122:123], v[102:103], v[182:183] neg_lo:[0,1] neg_hi:[0,1]
	v_pk_add_f32 v[114:115], v[168:169], v[110:111] op_sel:[0,1] op_sel_hi:[1,0] neg_lo:[0,1]
	v_pk_add_f32 v[130:131], v[168:169], v[110:111] op_sel:[0,1] op_sel_hi:[1,0] neg_hi:[0,1]
	ds_write_b64 v5, v[100:101]
	ds_write_b64 v5, v[126:127] offset:264
	ds_write_b64 v5, v[104:105] offset:528
	ds_write_b64 v5, v[106:107] offset:792
	ds_write_b64 v5, v[108:109] offset:1056
	ds_write_b64 v5, v[180:181] offset:1320
	ds_write_b64 v5, v[112:113] offset:1584
	ds_write_b64 v5, v[114:115] offset:1848
	ds_write_b64 v5, v[116:117] offset:2112
	ds_write_b64 v5, v[178:179] offset:2376
	ds_write_b64 v5, v[120:121] offset:2640
	ds_write_b64 v5, v[122:123] offset:2904
	ds_write_b64 v5, v[124:125] offset:3168
	ds_write_b64 v5, v[184:185] offset:3432
	ds_write_b64 v5, v[128:129] offset:3696
	ds_write_b64 v5, v[130:131] offset:3960
	s_waitcnt lgkmcnt(0)
	s_barrier
	ds_read_b64 v[100:101], v3
	ds_read_b64 v[108:109], v3 offset:16896
	ds_read_b64 v[116:117], v3 offset:33792
	ds_read_b64 v[124:125], v3 offset:50688
	ds_read_b64 v[126:127], v3 offset:4224
	ds_read_b64 v[180:181], v3 offset:21120
	ds_read_b64 v[178:179], v3 offset:38016
	ds_read_b64 v[184:185], v3 offset:54912
	ds_read_b64 v[104:105], v3 offset:8448
	ds_read_b64 v[112:113], v3 offset:25344
	ds_read_b64 v[120:121], v3 offset:42240
	ds_read_b64 v[128:129], v3 offset:59136
	ds_read_b64 v[106:107], v3 offset:12672
	ds_read_b64 v[114:115], v3 offset:29568
	ds_read_b64 v[122:123], v3 offset:46464
	ds_read_b64 v[130:131], v3 offset:63360
	s_waitcnt lgkmcnt(14)
	v_pk_mul_f32 v[176:177], v[108:109], v[12:13] op_sel:[1,1] op_sel_hi:[0,1]
	v_pk_fma_f32 v[108:109], v[108:109], v[12:13], v[176:177] op_sel_hi:[1,0,1] neg_hi:[0,0,1]
	s_waitcnt lgkmcnt(13)
	v_pk_mul_f32 v[166:167], v[116:117], v[20:21] op_sel:[1,1] op_sel_hi:[0,1]
	v_pk_fma_f32 v[116:117], v[116:117], v[20:21], v[166:167] op_sel_hi:[1,0,1] neg_hi:[0,0,1]
	s_waitcnt lgkmcnt(12)
	v_pk_mul_f32 v[188:189], v[124:125], v[28:29] op_sel:[1,1] op_sel_hi:[0,1]
	v_pk_fma_f32 v[124:125], v[124:125], v[28:29], v[188:189] op_sel_hi:[1,0,1] neg_hi:[0,0,1]
	s_waitcnt lgkmcnt(11)
	v_pk_mul_f32 v[186:187], v[126:127], v[6:7] op_sel:[1,1] op_sel_hi:[0,1]
	v_pk_fma_f32 v[126:127], v[126:127], v[6:7], v[186:187] op_sel_hi:[1,0,1] neg_hi:[0,0,1]
	s_waitcnt lgkmcnt(10)
	v_pk_mul_f32 v[118:119], v[180:181], v[14:15] op_sel:[1,1] op_sel_hi:[0,1]
	v_pk_fma_f32 v[180:181], v[180:181], v[14:15], v[118:119] op_sel_hi:[1,0,1] neg_hi:[0,0,1]
	s_waitcnt lgkmcnt(9)
	v_pk_mul_f32 v[174:175], v[178:179], v[22:23] op_sel:[1,1] op_sel_hi:[0,1]
	v_pk_fma_f32 v[178:179], v[178:179], v[22:23], v[174:175] op_sel_hi:[1,0,1] neg_hi:[0,0,1]
	s_waitcnt lgkmcnt(8)
	v_pk_mul_f32 v[102:103], v[184:185], v[30:31] op_sel:[1,1] op_sel_hi:[0,1]
	v_pk_fma_f32 v[184:185], v[184:185], v[30:31], v[102:103] op_sel_hi:[1,0,1] neg_hi:[0,0,1]
	s_waitcnt lgkmcnt(7)
; #define LAS __attribute__((address_space(3)))
; __device__ __forceinline__ f32x2 cmulc(f32x2 a, f32x2 b) { return (f32x2){a.x * b.x + a.y * b.y, a.y * b.x - a.x * b.y}; }
; __device__ __forceinline__ void dft16_inv_lo(f32x2 (&x)[16]) {
;     constexpr float C1 = 0.92387953251128674f, S1 = 0.38268343236508977f, C2 = 0.70710678118654752f;
; #pragma unroll
;     for (int b = 0; b < 4; ++b) dft4<true>(x[b], x[4 + b], x[8 + b], x[12 + b]);
;     const f32x2 w1 = {C1, -S1}, w2 = {C2, -C2}, w3 = {S1, -C1}, w4 = {0.f, -1.f}, w6 = {-C2, -C2}, w9 = {-C1, S1};
;     x[5] = cmulc(x[5], w1); x[6] = cmulc(x[6], w2); x[7] = cmulc(x[7], w3);
;     x[9] = cmulc(x[9], w2); x[10] = cmulc(x[10], w4); x[11] = cmulc(x[11], w6);
;     x[13] = cmulc(x[13], w3); x[14] = cmulc(x[14], w6); x[15] = cmulc(x[15], w9);
;     f32x2 y[8];
; #pragma unroll
;     for (int c = 0; c < 4; ++c) { const f32x2 t0 = x[4 * c] + x[4 * c + 2], t1 = x[4 * c] - x[4 * c + 2], t2 = x[4 * c + 1] + x[4 * c + 3], t3 = x[4 * c + 1] - x[4 * c + 3];
;         y[c] = t0 + t2; y[4 + c] = t1 + (f32x2){-t3.y, t3.x}; }
; #pragma unroll
;     for (int k = 0; k < 8; ++k) x[k] = y[k];
; }
; __device__ __forceinline__ void fft_inv1(f32x2 (&x)[16], const LAS f32x2* B, int n2, const f32x2 (&w)[16]) {
;     asm volatile("" : "+v"(n2));
;     x[0] = B[fpad(n2)];
; #pragma unroll
;     for (int k = 1; k < 16; ++k) x[k] = cmulc(B[fpad(512 * k + n2)], w[k]);
;     dft16_inv_lo(x);
; }
	v_pk_mul_f32 v[168:169], v[104:105], v[8:9] op_sel:[1,1] op_sel_hi:[0,1]
	v_pk_fma_f32 v[104:105], v[104:105], v[8:9], v[168:169] op_sel_hi:[1,0,1] neg_hi:[0,0,1]
	s_waitcnt lgkmcnt(6)
	v_pk_mul_f32 v[182:183], v[112:113], v[16:17] op_sel:[1,1] op_sel_hi:[0,1]
	v_pk_fma_f32 v[112:113], v[112:113], v[16:17], v[182:183] op_sel_hi:[1,0,1] neg_hi:[0,0,1]
	s_waitcnt lgkmcnt(5)
	v_pk_mul_f32 v[110:111], v[120:121], v[24:25] op_sel:[1,1] op_sel_hi:[0,1]
	v_pk_fma_f32 v[120:121], v[120:121], v[24:25], v[110:111] op_sel_hi:[1,0,1] neg_hi:[0,0,1]
	s_waitcnt lgkmcnt(4)
	v_pk_mul_f32 v[176:177], v[128:129], v[32:33] op_sel:[1,1] op_sel_hi:[0,1]
	v_pk_fma_f32 v[128:129], v[128:129], v[32:33], v[176:177] op_sel_hi:[1,0,1] neg_hi:[0,0,1]
	s_waitcnt lgkmcnt(3)
	v_pk_mul_f32 v[166:167], v[106:107], v[10:11] op_sel:[1,1] op_sel_hi:[0,1]
	v_pk_fma_f32 v[106:107], v[106:107], v[10:11], v[166:167] op_sel_hi:[1,0,1] neg_hi:[0,0,1]
	s_waitcnt lgkmcnt(2)
	v_pk_mul_f32 v[188:189], v[114:115], v[18:19] op_sel:[1,1] op_sel_hi:[0,1]
	v_pk_fma_f32 v[114:115], v[114:115], v[18:19], v[188:189] op_sel_hi:[1,0,1] neg_hi:[0,0,1]
	s_waitcnt lgkmcnt(1)
	v_pk_mul_f32 v[186:187], v[122:123], v[26:27] op_sel:[1,1] op_sel_hi:[0,1]
	v_pk_fma_f32 v[122:123], v[122:123], v[26:27], v[186:187] op_sel_hi:[1,0,1] neg_hi:[0,0,1]
	s_waitcnt lgkmcnt(0)
	v_pk_mul_f32 v[118:119], v[130:131], v[34:35] op_sel:[1,1] op_sel_hi:[0,1]
	v_pk_fma_f32 v[130:131], v[130:131], v[34:35], v[118:119] op_sel_hi:[1,0,1] neg_hi:[0,0,1]
	v_pk_add_f32 v[174:175], v[100:101], v[116:117]
	v_pk_add_f32 v[102:103], v[100:101], v[116:117] neg_lo:[0,1] neg_hi:[0,1]
	v_pk_add_f32 v[168:169], v[108:109], v[124:125]
	v_pk_add_f32 v[182:183], v[108:109], v[124:125] neg_lo:[0,1] neg_hi:[0,1]
	v_pk_add_f32 v[100:101], v[174:175], v[168:169]
	v_pk_add_f32 v[116:117], v[174:175], v[168:169] neg_lo:[0,1] neg_hi:[0,1]
	v_pk_add_f32 v[108:109], v[102:103], v[182:183] op_sel:[0,1] op_sel_hi:[1,0] neg_lo:[0,1]
	v_pk_add_f32 v[124:125], v[102:103], v[182:183] op_sel:[0,1] op_sel_hi:[1,0] neg_hi:[0,1]
	v_pk_add_f32 v[110:111], v[126:127], v[178:179]
	v_pk_add_f32 v[176:177], v[126:127], v[178:179] neg_lo:[0,1] neg_hi:[0,1]
	v_pk_add_f32 v[166:167], v[180:181], v[184:185]
	v_pk_add_f32 v[188:189], v[180:181], v[184:185] neg_lo:[0,1] neg_hi:[0,1]
	v_pk_add_f32 v[126:127], v[110:111], v[166:167]
	v_pk_add_f32 v[178:179], v[110:111], v[166:167] neg_lo:[0,1] neg_hi:[0,1]
	v_pk_add_f32 v[180:181], v[176:177], v[188:189] op_sel:[0,1] op_sel_hi:[1,0] neg_lo:[0,1]
	v_pk_add_f32 v[184:185], v[176:177], v[188:189] op_sel:[0,1] op_sel_hi:[1,0] neg_hi:[0,1]
	v_pk_add_f32 v[186:187], v[104:105], v[120:121]
	v_pk_add_f32 v[118:119], v[104:105], v[120:121] neg_lo:[0,1] neg_hi:[0,1]
	v_pk_add_f32 v[174:175], v[112:113], v[128:129]
	v_pk_add_f32 v[102:103], v[112:113], v[128:129] neg_lo:[0,1] neg_hi:[0,1]
	v_pk_add_f32 v[104:105], v[186:187], v[174:175]
	v_pk_add_f32 v[120:121], v[186:187], v[174:175] neg_lo:[0,1] neg_hi:[0,1]
	v_pk_add_f32 v[112:113], v[118:119], v[102:103] op_sel:[0,1] op_sel_hi:[1,0] neg_lo:[0,1]
	v_pk_add_f32 v[128:129], v[118:119], v[102:103] op_sel:[0,1] op_sel_hi:[1,0] neg_hi:[0,1]
	v_pk_add_f32 v[168:169], v[106:107], v[122:123]
	v_pk_add_f32 v[182:183], v[106:107], v[122:123] neg_lo:[0,1] neg_hi:[0,1]
	v_pk_add_f32 v[110:111], v[114:115], v[130:131]
	v_pk_add_f32 v[176:177], v[114:115], v[130:131] neg_lo:[0,1] neg_hi:[0,1]
	v_pk_add_f32 v[106:107], v[168:169], v[110:111]
	v_pk_add_f32 v[122:123], v[168:169], v[110:111] neg_lo:[0,1] neg_hi:[0,1]
	v_pk_add_f32 v[114:115], v[182:183], v[176:177] op_sel:[0,1] op_sel_hi:[1,0] neg_lo:[0,1]
	v_pk_add_f32 v[130:131], v[182:183], v[176:177] op_sel:[0,1] op_sel_hi:[1,0] neg_hi:[0,1]
	v_pk_mul_f32 v[166:167], v[180:181], s[68:69] op_sel:[1,1] op_sel_hi:[0,1]
	v_pk_fma_f32 v[180:181], v[180:181], s[68:69], v[166:167] op_sel_hi:[1,0,1] neg_hi:[0,0,1]
	v_pk_mul_f32 v[188:189], v[112:113], s[84:85] op_sel:[1,1] op_sel_hi:[0,1]
	v_pk_fma_f32 v[112:113], v[112:113], s[84:85], v[188:189] op_sel_hi:[1,0,1] neg_hi:[0,0,1]
	v_pk_mul_f32 v[186:187], v[114:115], s[88:89] op_sel:[1,1] op_sel_hi:[0,1]
	v_pk_fma_f32 v[114:115], v[114:115], s[88:89], v[186:187] op_sel_hi:[1,0,1] neg_hi:[0,0,1]
	v_pk_mul_f32 v[118:119], v[178:179], s[84:85] op_sel:[1,1] op_sel_hi:[0,1]
	v_pk_fma_f32 v[178:179], v[178:179], s[84:85], v[118:119] op_sel_hi:[1,0,1] neg_hi:[0,0,1]
	v_pk_mul_f32 v[174:175], v[122:123], s[90:91] op_sel:[1,1] op_sel_hi:[0,1]
	v_pk_fma_f32 v[122:123], v[122:123], s[90:91], v[174:175] op_sel_hi:[1,0,1] neg_hi:[0,0,1]
	v_pk_mul_f32 v[102:103], v[184:185], s[88:89] op_sel:[1,1] op_sel_hi:[0,1]
	v_pk_fma_f32 v[184:185], v[184:185], s[88:89], v[102:103] op_sel_hi:[1,0,1] neg_hi:[0,0,1]
	v_pk_mul_f32 v[168:169], v[128:129], s[90:91] op_sel:[1,1] op_sel_hi:[0,1]
	v_pk_fma_f32 v[128:129], v[128:129], s[90:91], v[168:169] op_sel_hi:[1,0,1] neg_hi:[0,0,1]
	v_pk_mul_f32 v[182:183], v[130:131], s[98:99] op_sel:[1,1] op_sel_hi:[0,1]
	v_pk_fma_f32 v[130:131], v[130:131], s[98:99], v[182:183] op_sel_hi:[1,0,1] neg_hi:[0,0,1]
	v_pk_add_f32 v[110:111], v[100:101], v[104:105]
	v_pk_add_f32 v[176:177], v[100:101], v[104:105] neg_lo:[0,1] neg_hi:[0,1]
	v_pk_add_f32 v[166:167], v[126:127], v[106:107]
	v_pk_add_f32 v[188:189], v[126:127], v[106:107] neg_lo:[0,1] neg_hi:[0,1]
	v_pk_add_f32 v[100:101], v[110:111], v[166:167]
	v_pk_add_f32 v[126:127], v[176:177], v[188:189] op_sel:[0,1] op_sel_hi:[1,0] neg_lo:[0,1]
	v_pk_add_f32 v[186:187], v[108:109], v[112:113]
	v_pk_add_f32 v[118:119], v[108:109], v[112:113] neg_lo:[0,1] neg_hi:[0,1]
	v_pk_add_f32 v[174:175], v[180:181], v[114:115]
	v_pk_add_f32 v[102:103], v[180:181], v[114:115] neg_lo:[0,1] neg_hi:[0,1]
	v_pk_add_f32 v[108:109], v[186:187], v[174:175]
	v_pk_add_f32 v[180:181], v[118:119], v[102:103] op_sel:[0,1] op_sel_hi:[1,0] neg_lo:[0,1]
	v_pk_add_f32 v[168:169], v[116:117], v[120:121] op_sel:[0,1] op_sel_hi:[1,0] neg_lo:[0,1]
	v_pk_add_f32 v[182:183], v[116:117], v[120:121] op_sel:[0,1] op_sel_hi:[1,0] neg_hi:[0,1]
	v_pk_add_f32 v[110:111], v[178:179], v[122:123]
	v_pk_add_f32 v[176:177], v[178:179], v[122:123] neg_lo:[0,1] neg_hi:[0,1]
	v_pk_add_f32 v[116:117], v[168:169], v[110:111]
	v_pk_add_f32 v[178:179], v[182:183], v[176:177] op_sel:[0,1] op_sel_hi:[1,0] neg_lo:[0,1]
	v_pk_add_f32 v[166:167], v[124:125], v[128:129]
	v_pk_add_f32 v[188:189], v[124:125], v[128:129] neg_lo:[0,1] neg_hi:[0,1]
	v_pk_add_f32 v[186:187], v[184:185], v[130:131]
	v_pk_add_f32 v[118:119], v[184:185], v[130:131] neg_lo:[0,1] neg_hi:[0,1]
	v_pk_add_f32 v[124:125], v[166:167], v[186:187]
	v_pk_add_f32 v[184:185], v[188:189], v[118:119] op_sel:[0,1] op_sel_hi:[1,0] neg_lo:[0,1]
	s_load_dword s35, s[50:51], 0x1000
	s_mul_i32 s43, s80, 0x8800
	s_add_u32 s46, s40, s43
	s_addc_u32 s47, s41, 0
	s_waitcnt lgkmcnt(0)
; __device__ __forceinline__ void hyena_fft(LAS unsigned char* lds, int layer, int G, const int wave_s) {
;     ...
;             { const float fb1 = fbias[HY + c]; float* zo = ZT + (size_t)c * MT;
; #pragma unroll
;               for (int r = 0; r < 8; ++r) { const int t = n2 + 512 * r;
;                   zo[t] = ux[r][0] * (x[r].x + fb1 * uz[r][0]); zo[SEQ + t] = ux[r][1] * (x[r].y + fb1 * uz[r][1]); } }
;         }
	v_mov_b32_e32 v194, s35
	v_pk_fma_f32 v[174:175], v[132:133], v[194:195], v[100:101] op_sel_hi:[1,0,1]
	v_pk_mul_f32 v[174:175], v[148:149], v[174:175]
	s_add_u32 s60, s46, 0
	s_addc_u32 s61, s47, 0
	s_add_u32 s62, s60, 0x4000
	s_addc_u32 s63, s61, 0
	global_store_dword v212, v174, s[60:61]
	global_store_dword v212, v175, s[62:63]
	v_pk_fma_f32 v[102:103], v[134:135], v[194:195], v[108:109] op_sel_hi:[1,0,1]
	v_pk_mul_f32 v[102:103], v[150:151], v[102:103]
	global_store_dword v212, v102, s[60:61] offset:2048
	global_store_dword v212, v103, s[62:63] offset:2048
	v_pk_fma_f32 v[168:169], v[136:137], v[194:195], v[116:117] op_sel_hi:[1,0,1]
	v_pk_mul_f32 v[168:169], v[152:153], v[168:169]
	s_add_u32 s60, s46, 0x1000
	s_addc_u32 s61, s47, 0
	s_add_u32 s62, s60, 0x4000
	s_addc_u32 s63, s61, 0
	global_store_dword v212, v168, s[60:61]
	global_store_dword v212, v169, s[62:63]
	v_pk_fma_f32 v[182:183], v[138:139], v[194:195], v[124:125] op_sel_hi:[1,0,1]
	v_pk_mul_f32 v[182:183], v[154:155], v[182:183]
	global_store_dword v212, v182, s[60:61] offset:2048
	global_store_dword v212, v183, s[62:63] offset:2048
	v_pk_fma_f32 v[110:111], v[140:141], v[194:195], v[126:127] op_sel_hi:[1,0,1]
	v_pk_mul_f32 v[110:111], v[158:159], v[110:111]
	s_add_u32 s60, s46, 0x2000
	s_addc_u32 s61, s47, 0
	s_add_u32 s62, s60, 0x4000
	s_addc_u32 s63, s61, 0
	global_store_dword v212, v110, s[60:61]
	global_store_dword v212, v111, s[62:63]
	v_pk_fma_f32 v[176:177], v[142:143], v[194:195], v[180:181] op_sel_hi:[1,0,1]
	v_pk_mul_f32 v[176:177], v[160:161], v[176:177]
	global_store_dword v212, v176, s[60:61] offset:2048
	global_store_dword v212, v177, s[62:63] offset:2048
	v_pk_fma_f32 v[166:167], v[144:145], v[194:195], v[178:179] op_sel_hi:[1,0,1]
	v_pk_mul_f32 v[166:167], v[162:163], v[166:167]
	s_add_u32 s60, s46, 0x3000
	s_addc_u32 s61, s47, 0
	s_add_u32 s62, s60, 0x4000
	s_addc_u32 s63, s61, 0
	global_store_dword v212, v166, s[60:61]
	global_store_dword v212, v167, s[62:63]
	v_pk_fma_f32 v[188:189], v[146:147], v[194:195], v[184:185] op_sel_hi:[1,0,1]
	v_pk_mul_f32 v[188:189], v[164:165], v[188:189]
	global_store_dword v212, v188, s[60:61] offset:2048
	global_store_dword v212, v189, s[62:63] offset:2048
	s_add_u32 s80, s80, 1
	s_cmp_lt_i32 s80, s93
	s_cbranch_scc1 .Lhfft_loop
	s_waitcnt vmcnt(0) lgkmcnt(0)
